# scan: packed (sa,y) dots with bank-conflict-free swizzled a/r LDS layout + merged v reads
# baseline (speedup 1.0000x reference)
; #define LAS __attribute__((address_space(3)))
; __device__ __forceinline__ void rwkv_scan(Frame& F, int wg, unsigned* shw, unsigned wait_target, int wait_blk) {
;     ...
;     auto lstore = [&](const LdRegs& L, int b) {
;         LAS float* rec = buf + (b * RW_TB + lstep) * RW_REC;
;         const u32x4 av = L.a, bv = L.b, kv = L.k, rv = L.r;
;         f32x4 a_0 = {bflo(av.x), bfhi(av.x), bflo(av.y), bfhi(av.y)}, a_1 = {bflo(av.z), bfhi(av.z), bflo(av.w), bfhi(av.w)};
;         f32x4 b_0 = {bflo(bv.x), bfhi(bv.x), bflo(bv.y), bfhi(bv.y)}, b_1 = {bflo(bv.z), bfhi(bv.z), bflo(bv.w), bfhi(bv.w)};
;         f32x4 k_0 = {bflo(kv.x), bfhi(kv.x), bflo(kv.y), bfhi(kv.y)}, k_1 = {bflo(kv.z), bfhi(kv.z), bflo(kv.w), bfhi(kv.w)};
;         f32x4 r_0 = {bflo(rv.x), bfhi(rv.x), bflo(rv.y), bfhi(rv.y)}, r_1 = {bflo(rv.z), bfhi(rv.z), bflo(rv.w), bfhi(rv.w)};
;         *(LAS f32x4*)(rec + 8 * part) = L.w0; *(LAS f32x4*)(rec + 8 * part + 4) = L.w1;
;         *(LAS f32x4*)(rec + 64 + 8 * part) = a_0; *(LAS f32x4*)(rec + 64 + 8 * part + 4) = a_1;
;         *(LAS f32x4*)(rec + 128 + 8 * part) = b_0; *(LAS f32x4*)(rec + 128 + 8 * part + 4) = b_1;
;         *(LAS f32x4*)(rec + 192 + 8 * part) = k_0; *(LAS f32x4*)(rec + 192 + 8 * part + 4) = k_1;
;         *(LAS f32x4*)(rec + 256 + 8 * part) = L.w0 * r_0; *(LAS f32x4*)(rec + 256 + 8 * part + 4) = L.w1 * r_1;
;         if (part < 2) { const u32x4 vv = L.v;
;             const float v8[8] = {bflo(vv.x), bfhi(vv.x), bflo(vv.y), bfhi(vv.y), bflo(vv.z), bfhi(vv.z), bflo(vv.w), bfhi(vv.w)};
; #pragma unroll
;             for (int e = 0; e < 8; ++e) *(LAS f32x4*)(rec + 320 + (8 * part + e) * 4) = (f32x4){v8[e], v8[e] * L.kr, L.br, 0.f}; }
;     ...
;     if (loader) { gload(L0, 0); lstore(L0, 0); gload(L0, 1); gload(L1, 2); }
.LBB0_838:
	s_or_b64 exec, exec, s[6:7]
	s_movk_i32 s6, 0x600
	v_mad_i32_i24 v7, v60, s6, 0
	s_waitcnt vmcnt(0)
	v_add_u32_e32 v100, v7, v195
	v_lshl_add_u32 v101, v195, 1, v7
	v_lshrrev_b32_e32 v102, 3, v195
	v_and_b32_e32 v102, 16, v102
	v_add_u32_e32 v101, v101, v102
	v_xor_b32_e32 v103, 16, v101
	v_lshlrev_b32_e32 v104, 16, v24
	v_and_b32_e32 v105, 0xffff0000, v24
	v_lshlrev_b32_e32 v106, 16, v25
	v_and_b32_e32 v107, 0xffff0000, v25
	v_lshlrev_b32_e32 v108, 16, v26
	v_and_b32_e32 v109, 0xffff0000, v26
	v_lshlrev_b32_e32 v110, 16, v27
	v_and_b32_e32 v111, 0xffff0000, v27
	ds_write_b128 v100, v[104:107] offset:768
	ds_write_b128 v100, v[108:111] offset:784
	v_lshlrev_b32_e32 v112, 16, v20
	v_and_b32_e32 v113, 0xffff0000, v20
	v_lshlrev_b32_e32 v114, 16, v21
	v_and_b32_e32 v115, 0xffff0000, v21
	v_lshlrev_b32_e32 v116, 16, v22
	v_and_b32_e32 v117, 0xffff0000, v22
	v_lshlrev_b32_e32 v118, 16, v23
	v_and_b32_e32 v119, 0xffff0000, v23
	ds_write_b128 v100, v[112:115] offset:1024
	ds_write_b128 v100, v[116:119] offset:1040
	v_lshlrev_b32_e32 v120, 16, v28
	v_lshlrev_b32_e32 v121, 16, v16
	v_and_b32_e32 v122, 0xffff0000, v28
	v_and_b32_e32 v123, 0xffff0000, v16
	ds_write_b128 v101, v[120:123] offset:256
	v_lshlrev_b32_e32 v124, 16, v29
	v_lshlrev_b32_e32 v125, 16, v17
	v_and_b32_e32 v126, 0xffff0000, v29
	v_and_b32_e32 v127, 0xffff0000, v17
	ds_write_b128 v103, v[124:127] offset:256
	v_lshlrev_b32_e32 v128, 16, v30
	v_lshlrev_b32_e32 v129, 16, v18
	v_and_b32_e32 v130, 0xffff0000, v30
	v_and_b32_e32 v131, 0xffff0000, v18
	ds_write_b128 v101, v[128:131] offset:288
	v_lshlrev_b32_e32 v132, 16, v31
	v_lshlrev_b32_e32 v133, 16, v19
	v_and_b32_e32 v134, 0xffff0000, v31
	v_and_b32_e32 v135, 0xffff0000, v19
	ds_write_b128 v103, v[132:135] offset:288
	ds_write_b128 v100, v[12:15] offset:0
	ds_write_b128 v100, v[8:11] offset:16
	s_and_saveexec_b64 s[6:7], s[4:5]
	s_cbranch_execz .LBB0_840
	v_and_b32_e32 v100, 3, v60
	v_mul_u32_u24_e32 v100, 0x5fc, v100
	v_lshl_add_u32 v101, v63, 7, v7
	v_sub_u32_e32 v101, v101, v100
	v_lshlrev_b32_e32 v104, 16, v0
	v_and_b32_e32 v105, 0xffff0000, v0
	v_lshlrev_b32_e32 v106, 16, v1
	v_and_b32_e32 v107, 0xffff0000, v1
	v_lshlrev_b32_e32 v108, 16, v2
	v_and_b32_e32 v109, 0xffff0000, v2
	v_lshlrev_b32_e32 v110, 16, v3
	v_and_b32_e32 v111, 0xffff0000, v3
	ds_write_b32 v101, v104 offset:1280
	ds_write_b32 v101, v105 offset:1296
	ds_write_b32 v101, v106 offset:1312
	ds_write_b32 v101, v107 offset:1328
	ds_write_b32 v101, v108 offset:1344
	ds_write_b32 v101, v109 offset:1360
	ds_write_b32 v101, v110 offset:1376
	ds_write_b32 v101, v111 offset:1392

; #define LAS __attribute__((address_space(3)))
; __device__ __forceinline__ void rwkv_scan(Frame& F, int wg, unsigned* shw, unsigned wait_target, int wait_blk) {
;     ...
;     auto lstore = [&](const LdRegs& L, int b) {
;         LAS float* rec = buf + (b * RW_TB + lstep) * RW_REC;
;         const u32x4 av = L.a, bv = L.b, kv = L.k, rv = L.r;
;         f32x4 a_0 = {bflo(av.x), bfhi(av.x), bflo(av.y), bfhi(av.y)}, a_1 = {bflo(av.z), bfhi(av.z), bflo(av.w), bfhi(av.w)};
;         f32x4 b_0 = {bflo(bv.x), bfhi(bv.x), bflo(bv.y), bfhi(bv.y)}, b_1 = {bflo(bv.z), bfhi(bv.z), bflo(bv.w), bfhi(bv.w)};
;         f32x4 k_0 = {bflo(kv.x), bfhi(kv.x), bflo(kv.y), bfhi(kv.y)}, k_1 = {bflo(kv.z), bfhi(kv.z), bflo(kv.w), bfhi(kv.w)};
;         f32x4 r_0 = {bflo(rv.x), bfhi(rv.x), bflo(rv.y), bfhi(rv.y)}, r_1 = {bflo(rv.z), bfhi(rv.z), bflo(rv.w), bfhi(rv.w)};
;         *(LAS f32x4*)(rec + 8 * part) = L.w0; *(LAS f32x4*)(rec + 8 * part + 4) = L.w1;
;         *(LAS f32x4*)(rec + 64 + 8 * part) = a_0; *(LAS f32x4*)(rec + 64 + 8 * part + 4) = a_1;
;         *(LAS f32x4*)(rec + 128 + 8 * part) = b_0; *(LAS f32x4*)(rec + 128 + 8 * part + 4) = b_1;
;         *(LAS f32x4*)(rec + 192 + 8 * part) = k_0; *(LAS f32x4*)(rec + 192 + 8 * part + 4) = k_1;
;         *(LAS f32x4*)(rec + 256 + 8 * part) = L.w0 * r_0; *(LAS f32x4*)(rec + 256 + 8 * part + 4) = L.w1 * r_1;
;         if (part < 2) { const u32x4 vv = L.v;
;             const float v8[8] = {bflo(vv.x), bfhi(vv.x), bflo(vv.y), bfhi(vv.y), bflo(vv.z), bfhi(vv.z), bflo(vv.w), bfhi(vv.w)};
; #pragma unroll
;             for (int e = 0; e < 8; ++e) *(LAS f32x4*)(rec + 320 + (8 * part + e) * 4) = (f32x4){v8[e], v8[e] * L.kr, L.br, 0.f}; }
;     ...
;         if (loader) { lstore(L0, 1); if (blk + 3 < NBLK) gload(L0, blk + 3); }
;         else scan_block(blk);
;         __syncthreads();
;         if (loader) { if (blk + 2 < NBLK) { lstore(L1, 0); if (blk + 4 < NBLK) gload(L1, blk + 4); } }
.LBB0_850:
	s_and_b64 vcc, exec, s[50:51]
	s_cbranch_vccz .LBB0_890
	s_waitcnt vmcnt(0)
	v_add_u32_e32 v100, v199, v195
	v_lshl_add_u32 v101, v195, 1, v199
	v_lshrrev_b32_e32 v102, 3, v195
	v_and_b32_e32 v102, 16, v102
	v_add_u32_e32 v101, v101, v102
	v_xor_b32_e32 v103, 16, v101
	v_lshlrev_b32_e32 v104, 16, v20
	v_and_b32_e32 v105, 0xffff0000, v20
	v_lshlrev_b32_e32 v106, 16, v21
	v_and_b32_e32 v107, 0xffff0000, v21
	v_lshlrev_b32_e32 v108, 16, v22
	v_and_b32_e32 v109, 0xffff0000, v22
	v_lshlrev_b32_e32 v110, 16, v23
	v_and_b32_e32 v111, 0xffff0000, v23
	ds_write_b128 v100, v[104:107] offset:49920
	ds_write_b128 v100, v[108:111] offset:49936
	v_lshlrev_b32_e32 v112, 16, v24
	v_and_b32_e32 v113, 0xffff0000, v24
	v_lshlrev_b32_e32 v114, 16, v25
	v_and_b32_e32 v115, 0xffff0000, v25
	v_lshlrev_b32_e32 v116, 16, v26
	v_and_b32_e32 v117, 0xffff0000, v26
	v_lshlrev_b32_e32 v118, 16, v27
	v_and_b32_e32 v119, 0xffff0000, v27
	ds_write_b128 v100, v[112:115] offset:50176
	ds_write_b128 v100, v[116:119] offset:50192
	v_lshlrev_b32_e32 v120, 16, v16
	v_lshlrev_b32_e32 v121, 16, v28
	v_and_b32_e32 v122, 0xffff0000, v16
	v_and_b32_e32 v123, 0xffff0000, v28
	ds_write_b128 v101, v[120:123] offset:49408
	v_lshlrev_b32_e32 v124, 16, v17
	v_lshlrev_b32_e32 v125, 16, v29
	v_and_b32_e32 v126, 0xffff0000, v17
	v_and_b32_e32 v127, 0xffff0000, v29
	ds_write_b128 v103, v[124:127] offset:49408
	v_lshlrev_b32_e32 v128, 16, v18
	v_lshlrev_b32_e32 v129, 16, v30
	v_and_b32_e32 v130, 0xffff0000, v18
	v_and_b32_e32 v131, 0xffff0000, v30
	ds_write_b128 v101, v[128:131] offset:49440
	v_lshlrev_b32_e32 v132, 16, v19
	v_lshlrev_b32_e32 v133, 16, v31
	v_and_b32_e32 v134, 0xffff0000, v19
	v_and_b32_e32 v135, 0xffff0000, v31
	ds_write_b128 v103, v[132:135] offset:49440
	ds_write_b128 v100, v[12:15] offset:49152
	ds_write_b128 v100, v[8:11] offset:49168
	s_and_saveexec_b64 s[50:51], s[10:11]
	s_cbranch_execz .LBB0_853
	v_and_b32_e32 v100, 3, v201
	v_mul_u32_u24_e32 v100, 0x5fc, v100
	v_add_u32_e32 v101, v199, v200
	v_sub_u32_e32 v101, v101, v100
	v_lshlrev_b32_e32 v104, 16, v0
	v_and_b32_e32 v105, 0xffff0000, v0
	v_lshlrev_b32_e32 v106, 16, v1
	v_and_b32_e32 v107, 0xffff0000, v1
	v_lshlrev_b32_e32 v108, 16, v2
	v_and_b32_e32 v109, 0xffff0000, v2
	v_lshlrev_b32_e32 v110, 16, v3
	v_and_b32_e32 v111, 0xffff0000, v3
	ds_write_b32 v101, v104 offset:50432
	ds_write_b32 v101, v105 offset:50448
	ds_write_b32 v101, v106 offset:50464
	ds_write_b32 v101, v107 offset:50480
	ds_write_b32 v101, v108 offset:50496
	ds_write_b32 v101, v109 offset:50512
	ds_write_b32 v101, v110 offset:50528
	ds_write_b32 v101, v111 offset:50544

; __device__ __forceinline__ void rwkv_scan(Frame& F, int wg, unsigned* shw, unsigned wait_target, int wait_blk) {
;     ...
;     auto scan_block = [&](int blk) {
;             const LAS float* rb = buf + ((blk & 1) * RW_TB) * RW_REC + 4 * j;
;             const LAS float* rv_ = buf + ((blk & 1) * RW_TB) * RW_REC + 320 + (4 * F.wave + rg) * 4;
;     ...
;             RwOps R[4];
;             RW_LD(R[0], 0); RW_LD(R[1], 1); RW_LD(R[2], 2);
;             for (int s4 = 0; s4 < RW_TB; s4 += 4) {
;                 float pz[4], u[4];
; #pragma unroll
;                 for (int q = 0; q < 4; ++q) {
;                     RW_LD(R[(q + 3) & 3], s4 + q + 3);
;                     const RwOps& cur = R[q];
;                     const f32x2 slo = {st.x, st.y}, shi = {st.z, st.w};
;                     f32x2 ma = slo * (f32x2){cur.a.x, cur.a.y}; ma = __builtin_elementwise_fma(shi, (f32x2){cur.a.z, cur.a.w}, ma);
;                     f32x2 mz = slo * (f32x2){cur.wr.x, cur.wr.y}; mz = __builtin_elementwise_fma(shi, (f32x2){cur.wr.z, cur.wr.w}, mz);
;                     float psa = ma.x + ma.y; pz[q] = mz.x + mz.y;
;                     const f32x2 vb = {cur.vs.x, cur.vs.x};
;                     f32x2 tlo = (f32x2){cur.k.x, cur.k.y} * vb, thi = (f32x2){cur.k.z, cur.k.w} * vb;
;                     tlo = __builtin_elementwise_fma(slo, (f32x2){cur.w.x, cur.w.y}, tlo); thi = __builtin_elementwise_fma(shi, (f32x2){cur.w.z, cur.w.w}, thi);
;                     psa = red16(psa);
;                     const f32x2 pb = {psa, psa};
;                     tlo = __builtin_elementwise_fma((f32x2){cur.b.x, cur.b.y}, pb, tlo); thi = __builtin_elementwise_fma((f32x2){cur.b.z, cur.b.w}, pb, thi);
;                     st = (f32x4){tlo.x, tlo.y, thi.x, thi.y};
;                     u[q] = psa * cur.vs.z + cur.vs.y;
;                 }
;                 const float qa = (odd1 ? pz[1] : pz[0]) + dppf<0xB1>(odd1 ? pz[0] : pz[1]);
;                 const float qb = (odd1 ? pz[3] : pz[2]) + dppf<0xB1>(odd1 ? pz[2] : pz[3]);
;                 float r = (odd2 ? qb : qa) + dppf<0x4E>(odd2 ? qa : qb);
;                 r += dppf<0x124>(r); r += dppf<0x128>(r);
;                 const float us = odd2 ? (odd1 ? u[3] : u[2]) : (odd1 ? u[1] : u[0]);
;                 if (j < 4) { const int t = blk * RW_TB + s4 + j; ((float*)(Ub + (size_t)t * (PWP * 2) + URR * 2))[h * 64 + row] = r + us; }
.LBB0_873:
	s_mul_i32 s50, s59, 0x58000
	s_add_i32 s50, s50, 0xffff5000
	v_and_b32_e32 v163, 8, v194
	v_lshlrev_b32_e32 v163, 1, v163
	v_add_u32_e32 v162, v198, v198
	v_add_u32_e32 v162, v162, v163
	v_xor_b32_e32 v163, 16, v162
	ds_read_b128 v[80:83], v162 offset:256
	ds_read_b128 v[84:87], v163 offset:256
	ds_read_b128 v[92:95], v198 offset:1024
	ds_read_b128 v[136:139], v204 offset:1280
	ds_read_b128 v[76:79], v198 offset:0
	ds_read_b128 v[88:91], v198 offset:768
	ds_read_b128 v[100:103], v162 offset:1792
	ds_read_b128 v[104:107], v163 offset:1792
	ds_read_b128 v[112:115], v198 offset:2560
	ds_read_b128 v[96:99], v198 offset:1536
	ds_read_b128 v[108:111], v198 offset:2304
	v_lshrrev_b32_e32 v161, 2, v194
	v_mul_u32_u24_e32 v161, 0x2c00, v161
	v_lshl_add_u32 v161, v186, 2, v161
	v_add_u32_e32 v161, s50, v161
	s_waitcnt lgkmcnt(5)
	v_pk_mul_f32 v[144:145], v[68:69], v[80:81] op_sel_hi:[0,1]
	v_pk_fma_f32 v[144:145], v[68:69], v[82:83], v[144:145] op_sel:[1,0,0] op_sel_hi:[1,1,1]
	v_pk_fma_f32 v[144:145], v[70:71], v[84:85], v[144:145] op_sel_hi:[0,1,1]
	v_pk_fma_f32 v[144:145], v[70:71], v[86:87], v[144:145] op_sel:[1,0,0] op_sel_hi:[1,1,1]
	v_pk_mul_f32 v[154:155], v[92:93], v[136:137] op_sel_hi:[1,0]
	v_pk_mul_f32 v[156:157], v[94:95], v[136:137] op_sel_hi:[1,0]
	v_add_f32_dpp v152, v144, v144 quad_perm:[1,0,3,2] row_mask:0xf bank_mask:0xf bound_ctrl:1
	v_pk_fma_f32 v[154:155], v[68:69], v[76:77], v[154:155]
	v_pk_fma_f32 v[156:157], v[70:71], v[78:79], v[156:157]
	v_add_f32_dpp v152, v152, v152 quad_perm:[2,3,0,1] row_mask:0xf bank_mask:0xf bound_ctrl:1
	v_add_f32_dpp v158, v147, v147 row_ror:8 row_mask:0xf bank_mask:0xf
	v_add_f32_dpp v159, v149, v149 row_ror:8 row_mask:0xf bank_mask:0xf
	v_add_f32_dpp v152, v152, v152 row_half_mirror row_mask:0xf bank_mask:0xf bound_ctrl:1
	v_add_f32_dpp v158, v151, v151 row_ror:8 row_mask:0xf bank_mask:0xc
	v_add_f32_dpp v159, v145, v145 row_ror:8 row_mask:0xf bank_mask:0xc
	v_add_f32_dpp v152, v152, v152 row_mirror row_mask:0xf bank_mask:0xf bound_ctrl:1
	v_pk_fma_f32 v[72:73], v[88:89], v[152:153], v[154:155] op_sel_hi:[1,0,1]
	v_pk_fma_f32 v[74:75], v[90:91], v[152:153], v[156:157] op_sel_hi:[1,0,1]
	ds_read_b128 v[120:123], v162 offset:3328
	ds_read_b128 v[124:127], v163 offset:3328
	v_add_f32_dpp v160, v158, v158 row_half_mirror row_mask:0xf bank_mask:0xf
	v_add_f32_dpp v160, v159, v159 row_half_mirror row_mask:0xf bank_mask:0xa
	ds_read_b128 v[132:135], v198 offset:4096
	ds_read_b128 v[116:119], v198 offset:3072
	v_add_f32_dpp v160, v160, v160 quad_perm:[1,0,3,2] row_mask:0xf bank_mask:0xf bound_ctrl:1
	ds_read_b128 v[128:131], v198 offset:3840
	s_nop 0
	v_add_f32_dpp v160, v160, v160 quad_perm:[2,3,0,1] row_mask:0xf bank_mask:0xf bound_ctrl:1
	s_cmp_lg_u32 s59, 0
	s_cselect_b64 exec, -1, 0
	global_store_dword v161, v160, s[34:35]
	s_mov_b64 exec, -1
	v_add_u32_e32 v161, 0xb000, v161
	s_waitcnt lgkmcnt(5)
	v_pk_mul_f32 v[146:147], v[72:73], v[100:101] op_sel_hi:[0,1]
	v_pk_fma_f32 v[146:147], v[72:73], v[102:103], v[146:147] op_sel:[1,0,0] op_sel_hi:[1,1,1]
	v_pk_fma_f32 v[146:147], v[74:75], v[104:105], v[146:147] op_sel_hi:[0,1,1]
	v_pk_fma_f32 v[146:147], v[74:75], v[106:107], v[146:147] op_sel:[1,0,0] op_sel_hi:[1,1,1]
	v_pk_mul_f32 v[154:155], v[112:113], v[136:137] op_sel:[0,1] op_sel_hi:[1,1]
	v_pk_mul_f32 v[156:157], v[114:115], v[136:137] op_sel:[0,1] op_sel_hi:[1,1]
	v_add_f32_dpp v152, v146, v146 quad_perm:[1,0,3,2] row_mask:0xf bank_mask:0xf bound_ctrl:1
	v_pk_fma_f32 v[154:155], v[72:73], v[96:97], v[154:155]
	v_pk_fma_f32 v[156:157], v[74:75], v[98:99], v[156:157]
	v_add_f32_dpp v152, v152, v152 quad_perm:[2,3,0,1] row_mask:0xf bank_mask:0xf bound_ctrl:1
	ds_read_b128 v[80:83], v162 offset:4864
	ds_read_b128 v[84:87], v163 offset:4864
	v_add_f32_dpp v152, v152, v152 row_half_mirror row_mask:0xf bank_mask:0xf bound_ctrl:1
	ds_read_b128 v[92:95], v198 offset:5632
	ds_read_b128 v[76:79], v198 offset:4608
	v_add_f32_dpp v152, v152, v152 row_mirror row_mask:0xf bank_mask:0xf bound_ctrl:1
	v_pk_fma_f32 v[68:69], v[108:109], v[152:153], v[154:155] op_sel_hi:[1,0,1]
	v_pk_fma_f32 v[70:71], v[110:111], v[152:153], v[156:157] op_sel_hi:[1,0,1]
	ds_read_b128 v[88:91], v198 offset:5376
	s_waitcnt lgkmcnt(5)
	v_pk_mul_f32 v[148:149], v[68:69], v[120:121] op_sel_hi:[0,1]
	v_pk_fma_f32 v[148:149], v[68:69], v[122:123], v[148:149] op_sel:[1,0,0] op_sel_hi:[1,1,1]
	v_pk_fma_f32 v[148:149], v[70:71], v[124:125], v[148:149] op_sel_hi:[0,1,1]
	v_pk_fma_f32 v[148:149], v[70:71], v[126:127], v[148:149] op_sel:[1,0,0] op_sel_hi:[1,1,1]
	v_pk_mul_f32 v[154:155], v[132:133], v[138:139] op_sel_hi:[1,0]
	v_pk_mul_f32 v[156:157], v[134:135], v[138:139] op_sel_hi:[1,0]
	v_add_f32_dpp v152, v148, v148 quad_perm:[1,0,3,2] row_mask:0xf bank_mask:0xf bound_ctrl:1
	v_pk_fma_f32 v[154:155], v[68:69], v[116:117], v[154:155]
	v_pk_fma_f32 v[156:157], v[70:71], v[118:119], v[156:157]
	v_add_f32_dpp v152, v152, v152 quad_perm:[2,3,0,1] row_mask:0xf bank_mask:0xf bound_ctrl:1
	ds_read_b128 v[100:103], v162 offset:6400
	ds_read_b128 v[104:107], v163 offset:6400
	v_add_f32_dpp v152, v152, v152 row_half_mirror row_mask:0xf bank_mask:0xf bound_ctrl:1
	ds_read_b128 v[112:115], v198 offset:7168
	ds_read_b128 v[140:143], v204 offset:7424
	v_add_f32_dpp v152, v152, v152 row_mirror row_mask:0xf bank_mask:0xf bound_ctrl:1
	v_pk_fma_f32 v[72:73], v[128:129], v[152:153], v[154:155] op_sel_hi:[1,0,1]
	v_pk_fma_f32 v[74:75], v[130:131], v[152:153], v[156:157] op_sel_hi:[1,0,1]
	ds_read_b128 v[96:99], v198 offset:6144
	ds_read_b128 v[108:111], v198 offset:6912
	s_waitcnt lgkmcnt(6)
; __device__ __forceinline__ void rwkv_scan(Frame& F, int wg, unsigned* shw, unsigned wait_target, int wait_blk) {
;     ...
;             for (int s4 = 0; s4 < RW_TB; s4 += 4) {
;                 float pz[4], u[4];
; #pragma unroll
;                 for (int q = 0; q < 4; ++q) {
;                     RW_LD(R[(q + 3) & 3], s4 + q + 3);
;                     const RwOps& cur = R[q];
;                     const f32x2 slo = {st.x, st.y}, shi = {st.z, st.w};
;                     f32x2 ma = slo * (f32x2){cur.a.x, cur.a.y}; ma = __builtin_elementwise_fma(shi, (f32x2){cur.a.z, cur.a.w}, ma);
;                     f32x2 mz = slo * (f32x2){cur.wr.x, cur.wr.y}; mz = __builtin_elementwise_fma(shi, (f32x2){cur.wr.z, cur.wr.w}, mz);
;                     float psa = ma.x + ma.y; pz[q] = mz.x + mz.y;
;                     const f32x2 vb = {cur.vs.x, cur.vs.x};
;                     f32x2 tlo = (f32x2){cur.k.x, cur.k.y} * vb, thi = (f32x2){cur.k.z, cur.k.w} * vb;
;                     tlo = __builtin_elementwise_fma(slo, (f32x2){cur.w.x, cur.w.y}, tlo); thi = __builtin_elementwise_fma(shi, (f32x2){cur.w.z, cur.w.w}, thi);
;                     psa = red16(psa);
;                     const f32x2 pb = {psa, psa};
;                     tlo = __builtin_elementwise_fma((f32x2){cur.b.x, cur.b.y}, pb, tlo); thi = __builtin_elementwise_fma((f32x2){cur.b.z, cur.b.w}, pb, thi);
;                     st = (f32x4){tlo.x, tlo.y, thi.x, thi.y};
;                     u[q] = psa * cur.vs.z + cur.vs.y;
;                 }
;                 const float qa = (odd1 ? pz[1] : pz[0]) + dppf<0xB1>(odd1 ? pz[0] : pz[1]);
;                 const float qb = (odd1 ? pz[3] : pz[2]) + dppf<0xB1>(odd1 ? pz[2] : pz[3]);
;                 float r = (odd2 ? qb : qa) + dppf<0x4E>(odd2 ? qa : qb);
;                 r += dppf<0x124>(r); r += dppf<0x128>(r);
;                 const float us = odd2 ? (odd1 ? u[3] : u[2]) : (odd1 ? u[1] : u[0]);
;                 if (j < 4) { const int t = blk * RW_TB + s4 + j; ((float*)(Ub + (size_t)t * (PWP * 2) + URR * 2))[h * 64 + row] = r + us; }
	v_pk_mul_f32 v[150:151], v[72:73], v[80:81] op_sel_hi:[0,1]
	v_pk_fma_f32 v[150:151], v[72:73], v[82:83], v[150:151] op_sel:[1,0,0] op_sel_hi:[1,1,1]
	v_pk_fma_f32 v[150:151], v[74:75], v[84:85], v[150:151] op_sel_hi:[0,1,1]
	v_pk_fma_f32 v[150:151], v[74:75], v[86:87], v[150:151] op_sel:[1,0,0] op_sel_hi:[1,1,1]
	v_pk_mul_f32 v[154:155], v[92:93], v[138:139] op_sel:[0,1] op_sel_hi:[1,1]
	v_pk_mul_f32 v[156:157], v[94:95], v[138:139] op_sel:[0,1] op_sel_hi:[1,1]
	v_add_f32_dpp v152, v150, v150 quad_perm:[1,0,3,2] row_mask:0xf bank_mask:0xf bound_ctrl:1
	v_pk_fma_f32 v[154:155], v[72:73], v[76:77], v[154:155]
	v_pk_fma_f32 v[156:157], v[74:75], v[78:79], v[156:157]
	v_add_f32_dpp v152, v152, v152 quad_perm:[2,3,0,1] row_mask:0xf bank_mask:0xf bound_ctrl:1
	ds_read_b128 v[120:123], v162 offset:7936
	ds_read_b128 v[124:127], v163 offset:7936
	v_add_f32_dpp v152, v152, v152 row_half_mirror row_mask:0xf bank_mask:0xf bound_ctrl:1
	ds_read_b128 v[132:135], v198 offset:8704
	ds_read_b128 v[116:119], v198 offset:7680
	v_add_f32_dpp v152, v152, v152 row_mirror row_mask:0xf bank_mask:0xf bound_ctrl:1
	v_pk_fma_f32 v[68:69], v[88:89], v[152:153], v[154:155] op_sel_hi:[1,0,1]
	v_pk_fma_f32 v[70:71], v[90:91], v[152:153], v[156:157] op_sel_hi:[1,0,1]
	ds_read_b128 v[128:131], v198 offset:8448
	s_waitcnt lgkmcnt(5)
	v_pk_mul_f32 v[144:145], v[68:69], v[100:101] op_sel_hi:[0,1]
	v_pk_fma_f32 v[144:145], v[68:69], v[102:103], v[144:145] op_sel:[1,0,0] op_sel_hi:[1,1,1]
	v_pk_fma_f32 v[144:145], v[70:71], v[104:105], v[144:145] op_sel_hi:[0,1,1]
	v_pk_fma_f32 v[144:145], v[70:71], v[106:107], v[144:145] op_sel:[1,0,0] op_sel_hi:[1,1,1]
	v_pk_mul_f32 v[154:155], v[112:113], v[140:141] op_sel_hi:[1,0]
	v_pk_mul_f32 v[156:157], v[114:115], v[140:141] op_sel_hi:[1,0]
	v_add_f32_dpp v152, v144, v144 quad_perm:[1,0,3,2] row_mask:0xf bank_mask:0xf bound_ctrl:1
	v_pk_fma_f32 v[154:155], v[68:69], v[96:97], v[154:155]
	v_pk_fma_f32 v[156:157], v[70:71], v[98:99], v[156:157]
	v_add_f32_dpp v152, v152, v152 quad_perm:[2,3,0,1] row_mask:0xf bank_mask:0xf bound_ctrl:1
	v_add_f32_dpp v158, v147, v147 row_ror:8 row_mask:0xf bank_mask:0xf
	v_add_f32_dpp v159, v149, v149 row_ror:8 row_mask:0xf bank_mask:0xf
	v_add_f32_dpp v152, v152, v152 row_half_mirror row_mask:0xf bank_mask:0xf bound_ctrl:1
	v_add_f32_dpp v158, v151, v151 row_ror:8 row_mask:0xf bank_mask:0xc
	v_add_f32_dpp v159, v145, v145 row_ror:8 row_mask:0xf bank_mask:0xc
	v_add_f32_dpp v152, v152, v152 row_mirror row_mask:0xf bank_mask:0xf bound_ctrl:1
	v_pk_fma_f32 v[72:73], v[108:109], v[152:153], v[154:155] op_sel_hi:[1,0,1]
	v_pk_fma_f32 v[74:75], v[110:111], v[152:153], v[156:157] op_sel_hi:[1,0,1]
	ds_read_b128 v[80:83], v162 offset:9472
	ds_read_b128 v[84:87], v163 offset:9472
	v_add_f32_dpp v160, v158, v158 row_half_mirror row_mask:0xf bank_mask:0xf
	v_add_f32_dpp v160, v159, v159 row_half_mirror row_mask:0xf bank_mask:0xa
	ds_read_b128 v[92:95], v198 offset:10240
	ds_read_b128 v[76:79], v198 offset:9216
	v_add_f32_dpp v160, v160, v160 quad_perm:[1,0,3,2] row_mask:0xf bank_mask:0xf bound_ctrl:1
	ds_read_b128 v[88:91], v198 offset:9984
	s_nop 0
	v_add_f32_dpp v160, v160, v160 quad_perm:[2,3,0,1] row_mask:0xf bank_mask:0xf bound_ctrl:1
	global_store_dword v161, v160, s[34:35]
	v_add_u32_e32 v161, 0xb000, v161
	s_waitcnt lgkmcnt(5)
	v_pk_mul_f32 v[146:147], v[72:73], v[120:121] op_sel_hi:[0,1]
	v_pk_fma_f32 v[146:147], v[72:73], v[122:123], v[146:147] op_sel:[1,0,0] op_sel_hi:[1,1,1]
	v_pk_fma_f32 v[146:147], v[74:75], v[124:125], v[146:147] op_sel_hi:[0,1,1]
	v_pk_fma_f32 v[146:147], v[74:75], v[126:127], v[146:147] op_sel:[1,0,0] op_sel_hi:[1,1,1]
	v_pk_mul_f32 v[154:155], v[132:133], v[140:141] op_sel:[0,1] op_sel_hi:[1,1]
	v_pk_mul_f32 v[156:157], v[134:135], v[140:141] op_sel:[0,1] op_sel_hi:[1,1]
	v_add_f32_dpp v152, v146, v146 quad_perm:[1,0,3,2] row_mask:0xf bank_mask:0xf bound_ctrl:1
	v_pk_fma_f32 v[154:155], v[72:73], v[116:117], v[154:155]
	v_pk_fma_f32 v[156:157], v[74:75], v[118:119], v[156:157]
	v_add_f32_dpp v152, v152, v152 quad_perm:[2,3,0,1] row_mask:0xf bank_mask:0xf bound_ctrl:1
	ds_read_b128 v[100:103], v162 offset:11008
	ds_read_b128 v[104:107], v163 offset:11008
	v_add_f32_dpp v152, v152, v152 row_half_mirror row_mask:0xf bank_mask:0xf bound_ctrl:1
	ds_read_b128 v[112:115], v198 offset:11776
	ds_read_b128 v[96:99], v198 offset:10752
	v_add_f32_dpp v152, v152, v152 row_mirror row_mask:0xf bank_mask:0xf bound_ctrl:1
	v_pk_fma_f32 v[68:69], v[128:129], v[152:153], v[154:155] op_sel_hi:[1,0,1]
	v_pk_fma_f32 v[70:71], v[130:131], v[152:153], v[156:157] op_sel_hi:[1,0,1]
	ds_read_b128 v[108:111], v198 offset:11520
	s_waitcnt lgkmcnt(5)
	v_pk_mul_f32 v[148:149], v[68:69], v[80:81] op_sel_hi:[0,1]
	v_pk_fma_f32 v[148:149], v[68:69], v[82:83], v[148:149] op_sel:[1,0,0] op_sel_hi:[1,1,1]
	v_pk_fma_f32 v[148:149], v[70:71], v[84:85], v[148:149] op_sel_hi:[0,1,1]
	v_pk_fma_f32 v[148:149], v[70:71], v[86:87], v[148:149] op_sel:[1,0,0] op_sel_hi:[1,1,1]
	v_pk_mul_f32 v[154:155], v[92:93], v[142:143] op_sel_hi:[1,0]
	v_pk_mul_f32 v[156:157], v[94:95], v[142:143] op_sel_hi:[1,0]
	v_add_f32_dpp v152, v148, v148 quad_perm:[1,0,3,2] row_mask:0xf bank_mask:0xf bound_ctrl:1
	v_pk_fma_f32 v[154:155], v[68:69], v[76:77], v[154:155]
	v_pk_fma_f32 v[156:157], v[70:71], v[78:79], v[156:157]
	v_add_f32_dpp v152, v152, v152 quad_perm:[2,3,0,1] row_mask:0xf bank_mask:0xf bound_ctrl:1
	ds_read_b128 v[120:123], v162 offset:12544
	ds_read_b128 v[124:127], v163 offset:12544
	v_add_f32_dpp v152, v152, v152 row_half_mirror row_mask:0xf bank_mask:0xf bound_ctrl:1
	ds_read_b128 v[132:135], v198 offset:13312
	ds_read_b128 v[136:139], v204 offset:13568
	v_add_f32_dpp v152, v152, v152 row_mirror row_mask:0xf bank_mask:0xf bound_ctrl:1
	v_pk_fma_f32 v[72:73], v[88:89], v[152:153], v[154:155] op_sel_hi:[1,0,1]
	v_pk_fma_f32 v[74:75], v[90:91], v[152:153], v[156:157] op_sel_hi:[1,0,1]
	ds_read_b128 v[116:119], v198 offset:12288
	ds_read_b128 v[128:131], v198 offset:13056
	s_waitcnt lgkmcnt(6)
; __device__ __forceinline__ void rwkv_scan(Frame& F, int wg, unsigned* shw, unsigned wait_target, int wait_blk) {
;     ...
;             for (int s4 = 0; s4 < RW_TB; s4 += 4) {
;                 float pz[4], u[4];
; #pragma unroll
;                 for (int q = 0; q < 4; ++q) {
;                     RW_LD(R[(q + 3) & 3], s4 + q + 3);
;                     const RwOps& cur = R[q];
;                     const f32x2 slo = {st.x, st.y}, shi = {st.z, st.w};
;                     f32x2 ma = slo * (f32x2){cur.a.x, cur.a.y}; ma = __builtin_elementwise_fma(shi, (f32x2){cur.a.z, cur.a.w}, ma);
;                     f32x2 mz = slo * (f32x2){cur.wr.x, cur.wr.y}; mz = __builtin_elementwise_fma(shi, (f32x2){cur.wr.z, cur.wr.w}, mz);
;                     float psa = ma.x + ma.y; pz[q] = mz.x + mz.y;
;                     const f32x2 vb = {cur.vs.x, cur.vs.x};
;                     f32x2 tlo = (f32x2){cur.k.x, cur.k.y} * vb, thi = (f32x2){cur.k.z, cur.k.w} * vb;
;                     tlo = __builtin_elementwise_fma(slo, (f32x2){cur.w.x, cur.w.y}, tlo); thi = __builtin_elementwise_fma(shi, (f32x2){cur.w.z, cur.w.w}, thi);
;                     psa = red16(psa);
;                     const f32x2 pb = {psa, psa};
;                     tlo = __builtin_elementwise_fma((f32x2){cur.b.x, cur.b.y}, pb, tlo); thi = __builtin_elementwise_fma((f32x2){cur.b.z, cur.b.w}, pb, thi);
;                     st = (f32x4){tlo.x, tlo.y, thi.x, thi.y};
;                     u[q] = psa * cur.vs.z + cur.vs.y;
;                 }
;                 const float qa = (odd1 ? pz[1] : pz[0]) + dppf<0xB1>(odd1 ? pz[0] : pz[1]);
;                 const float qb = (odd1 ? pz[3] : pz[2]) + dppf<0xB1>(odd1 ? pz[2] : pz[3]);
;                 float r = (odd2 ? qb : qa) + dppf<0x4E>(odd2 ? qa : qb);
;                 r += dppf<0x124>(r); r += dppf<0x128>(r);
;                 const float us = odd2 ? (odd1 ? u[3] : u[2]) : (odd1 ? u[1] : u[0]);
;                 if (j < 4) { const int t = blk * RW_TB + s4 + j; ((float*)(Ub + (size_t)t * (PWP * 2) + URR * 2))[h * 64 + row] = r + us; }
	v_pk_mul_f32 v[150:151], v[72:73], v[100:101] op_sel_hi:[0,1]
	v_pk_fma_f32 v[150:151], v[72:73], v[102:103], v[150:151] op_sel:[1,0,0] op_sel_hi:[1,1,1]
	v_pk_fma_f32 v[150:151], v[74:75], v[104:105], v[150:151] op_sel_hi:[0,1,1]
	v_pk_fma_f32 v[150:151], v[74:75], v[106:107], v[150:151] op_sel:[1,0,0] op_sel_hi:[1,1,1]
	v_pk_mul_f32 v[154:155], v[112:113], v[142:143] op_sel:[0,1] op_sel_hi:[1,1]
	v_pk_mul_f32 v[156:157], v[114:115], v[142:143] op_sel:[0,1] op_sel_hi:[1,1]
	v_add_f32_dpp v152, v150, v150 quad_perm:[1,0,3,2] row_mask:0xf bank_mask:0xf bound_ctrl:1
	v_pk_fma_f32 v[154:155], v[72:73], v[96:97], v[154:155]
	v_pk_fma_f32 v[156:157], v[74:75], v[98:99], v[156:157]
	v_add_f32_dpp v152, v152, v152 quad_perm:[2,3,0,1] row_mask:0xf bank_mask:0xf bound_ctrl:1
	ds_read_b128 v[80:83], v162 offset:14080
	ds_read_b128 v[84:87], v163 offset:14080
	v_add_f32_dpp v152, v152, v152 row_half_mirror row_mask:0xf bank_mask:0xf bound_ctrl:1
	ds_read_b128 v[92:95], v198 offset:14848
	ds_read_b128 v[76:79], v198 offset:13824
	v_add_f32_dpp v152, v152, v152 row_mirror row_mask:0xf bank_mask:0xf bound_ctrl:1
	v_pk_fma_f32 v[68:69], v[108:109], v[152:153], v[154:155] op_sel_hi:[1,0,1]
	v_pk_fma_f32 v[70:71], v[110:111], v[152:153], v[156:157] op_sel_hi:[1,0,1]
	ds_read_b128 v[88:91], v198 offset:14592
	s_waitcnt lgkmcnt(5)
	v_pk_mul_f32 v[144:145], v[68:69], v[120:121] op_sel_hi:[0,1]
	v_pk_fma_f32 v[144:145], v[68:69], v[122:123], v[144:145] op_sel:[1,0,0] op_sel_hi:[1,1,1]
	v_pk_fma_f32 v[144:145], v[70:71], v[124:125], v[144:145] op_sel_hi:[0,1,1]
	v_pk_fma_f32 v[144:145], v[70:71], v[126:127], v[144:145] op_sel:[1,0,0] op_sel_hi:[1,1,1]
	v_pk_mul_f32 v[154:155], v[132:133], v[136:137] op_sel_hi:[1,0]
	v_pk_mul_f32 v[156:157], v[134:135], v[136:137] op_sel_hi:[1,0]
	v_add_f32_dpp v152, v144, v144 quad_perm:[1,0,3,2] row_mask:0xf bank_mask:0xf bound_ctrl:1
	v_pk_fma_f32 v[154:155], v[68:69], v[116:117], v[154:155]
	v_pk_fma_f32 v[156:157], v[70:71], v[118:119], v[156:157]
	v_add_f32_dpp v152, v152, v152 quad_perm:[2,3,0,1] row_mask:0xf bank_mask:0xf bound_ctrl:1
	v_add_f32_dpp v158, v147, v147 row_ror:8 row_mask:0xf bank_mask:0xf
	v_add_f32_dpp v159, v149, v149 row_ror:8 row_mask:0xf bank_mask:0xf
	v_add_f32_dpp v152, v152, v152 row_half_mirror row_mask:0xf bank_mask:0xf bound_ctrl:1
	v_add_f32_dpp v158, v151, v151 row_ror:8 row_mask:0xf bank_mask:0xc
	v_add_f32_dpp v159, v145, v145 row_ror:8 row_mask:0xf bank_mask:0xc
	v_add_f32_dpp v152, v152, v152 row_mirror row_mask:0xf bank_mask:0xf bound_ctrl:1
	v_pk_fma_f32 v[72:73], v[128:129], v[152:153], v[154:155] op_sel_hi:[1,0,1]
	v_pk_fma_f32 v[74:75], v[130:131], v[152:153], v[156:157] op_sel_hi:[1,0,1]
	ds_read_b128 v[100:103], v162 offset:15616
	ds_read_b128 v[104:107], v163 offset:15616
	v_add_f32_dpp v160, v158, v158 row_half_mirror row_mask:0xf bank_mask:0xf
	v_add_f32_dpp v160, v159, v159 row_half_mirror row_mask:0xf bank_mask:0xa
	ds_read_b128 v[112:115], v198 offset:16384
	ds_read_b128 v[96:99], v198 offset:15360
	v_add_f32_dpp v160, v160, v160 quad_perm:[1,0,3,2] row_mask:0xf bank_mask:0xf bound_ctrl:1
	ds_read_b128 v[108:111], v198 offset:16128
	s_nop 0
	v_add_f32_dpp v160, v160, v160 quad_perm:[2,3,0,1] row_mask:0xf bank_mask:0xf bound_ctrl:1
	global_store_dword v161, v160, s[34:35]
	v_add_u32_e32 v161, 0xb000, v161
	s_waitcnt lgkmcnt(5)
	v_pk_mul_f32 v[146:147], v[72:73], v[80:81] op_sel_hi:[0,1]
	v_pk_fma_f32 v[146:147], v[72:73], v[82:83], v[146:147] op_sel:[1,0,0] op_sel_hi:[1,1,1]
	v_pk_fma_f32 v[146:147], v[74:75], v[84:85], v[146:147] op_sel_hi:[0,1,1]
	v_pk_fma_f32 v[146:147], v[74:75], v[86:87], v[146:147] op_sel:[1,0,0] op_sel_hi:[1,1,1]
	v_pk_mul_f32 v[154:155], v[92:93], v[136:137] op_sel:[0,1] op_sel_hi:[1,1]
	v_pk_mul_f32 v[156:157], v[94:95], v[136:137] op_sel:[0,1] op_sel_hi:[1,1]
	v_add_f32_dpp v152, v146, v146 quad_perm:[1,0,3,2] row_mask:0xf bank_mask:0xf bound_ctrl:1
	v_pk_fma_f32 v[154:155], v[72:73], v[76:77], v[154:155]
	v_pk_fma_f32 v[156:157], v[74:75], v[78:79], v[156:157]
	v_add_f32_dpp v152, v152, v152 quad_perm:[2,3,0,1] row_mask:0xf bank_mask:0xf bound_ctrl:1
	ds_read_b128 v[120:123], v162 offset:17152
	ds_read_b128 v[124:127], v163 offset:17152
	v_add_f32_dpp v152, v152, v152 row_half_mirror row_mask:0xf bank_mask:0xf bound_ctrl:1
	ds_read_b128 v[132:135], v198 offset:17920
	ds_read_b128 v[116:119], v198 offset:16896
	v_add_f32_dpp v152, v152, v152 row_mirror row_mask:0xf bank_mask:0xf bound_ctrl:1
	v_pk_fma_f32 v[68:69], v[88:89], v[152:153], v[154:155] op_sel_hi:[1,0,1]
	v_pk_fma_f32 v[70:71], v[90:91], v[152:153], v[156:157] op_sel_hi:[1,0,1]
	ds_read_b128 v[128:131], v198 offset:17664
	s_waitcnt lgkmcnt(5)
	v_pk_mul_f32 v[148:149], v[68:69], v[100:101] op_sel_hi:[0,1]
	v_pk_fma_f32 v[148:149], v[68:69], v[102:103], v[148:149] op_sel:[1,0,0] op_sel_hi:[1,1,1]
	v_pk_fma_f32 v[148:149], v[70:71], v[104:105], v[148:149] op_sel_hi:[0,1,1]
	v_pk_fma_f32 v[148:149], v[70:71], v[106:107], v[148:149] op_sel:[1,0,0] op_sel_hi:[1,1,1]
	v_pk_mul_f32 v[154:155], v[112:113], v[138:139] op_sel_hi:[1,0]
	v_pk_mul_f32 v[156:157], v[114:115], v[138:139] op_sel_hi:[1,0]
	v_add_f32_dpp v152, v148, v148 quad_perm:[1,0,3,2] row_mask:0xf bank_mask:0xf bound_ctrl:1
	v_pk_fma_f32 v[154:155], v[68:69], v[96:97], v[154:155]
	v_pk_fma_f32 v[156:157], v[70:71], v[98:99], v[156:157]
	v_add_f32_dpp v152, v152, v152 quad_perm:[2,3,0,1] row_mask:0xf bank_mask:0xf bound_ctrl:1
	ds_read_b128 v[80:83], v162 offset:18688
	ds_read_b128 v[84:87], v163 offset:18688
	v_add_f32_dpp v152, v152, v152 row_half_mirror row_mask:0xf bank_mask:0xf bound_ctrl:1
	ds_read_b128 v[92:95], v198 offset:19456
	ds_read_b128 v[140:143], v204 offset:19712
	v_add_f32_dpp v152, v152, v152 row_mirror row_mask:0xf bank_mask:0xf bound_ctrl:1
	v_pk_fma_f32 v[72:73], v[108:109], v[152:153], v[154:155] op_sel_hi:[1,0,1]
	v_pk_fma_f32 v[74:75], v[110:111], v[152:153], v[156:157] op_sel_hi:[1,0,1]
	ds_read_b128 v[76:79], v198 offset:18432
	ds_read_b128 v[88:91], v198 offset:19200
	s_waitcnt lgkmcnt(6)
; __device__ __forceinline__ void rwkv_scan(Frame& F, int wg, unsigned* shw, unsigned wait_target, int wait_blk) {
;     ...
;             for (int s4 = 0; s4 < RW_TB; s4 += 4) {
;                 float pz[4], u[4];
; #pragma unroll
;                 for (int q = 0; q < 4; ++q) {
;                     RW_LD(R[(q + 3) & 3], s4 + q + 3);
;                     const RwOps& cur = R[q];
;                     const f32x2 slo = {st.x, st.y}, shi = {st.z, st.w};
;                     f32x2 ma = slo * (f32x2){cur.a.x, cur.a.y}; ma = __builtin_elementwise_fma(shi, (f32x2){cur.a.z, cur.a.w}, ma);
;                     f32x2 mz = slo * (f32x2){cur.wr.x, cur.wr.y}; mz = __builtin_elementwise_fma(shi, (f32x2){cur.wr.z, cur.wr.w}, mz);
;                     float psa = ma.x + ma.y; pz[q] = mz.x + mz.y;
;                     const f32x2 vb = {cur.vs.x, cur.vs.x};
;                     f32x2 tlo = (f32x2){cur.k.x, cur.k.y} * vb, thi = (f32x2){cur.k.z, cur.k.w} * vb;
;                     tlo = __builtin_elementwise_fma(slo, (f32x2){cur.w.x, cur.w.y}, tlo); thi = __builtin_elementwise_fma(shi, (f32x2){cur.w.z, cur.w.w}, thi);
;                     psa = red16(psa);
;                     const f32x2 pb = {psa, psa};
;                     tlo = __builtin_elementwise_fma((f32x2){cur.b.x, cur.b.y}, pb, tlo); thi = __builtin_elementwise_fma((f32x2){cur.b.z, cur.b.w}, pb, thi);
;                     st = (f32x4){tlo.x, tlo.y, thi.x, thi.y};
;                     u[q] = psa * cur.vs.z + cur.vs.y;
;                 }
;                 const float qa = (odd1 ? pz[1] : pz[0]) + dppf<0xB1>(odd1 ? pz[0] : pz[1]);
;                 const float qb = (odd1 ? pz[3] : pz[2]) + dppf<0xB1>(odd1 ? pz[2] : pz[3]);
;                 float r = (odd2 ? qb : qa) + dppf<0x4E>(odd2 ? qa : qb);
;                 r += dppf<0x124>(r); r += dppf<0x128>(r);
;                 const float us = odd2 ? (odd1 ? u[3] : u[2]) : (odd1 ? u[1] : u[0]);
;                 if (j < 4) { const int t = blk * RW_TB + s4 + j; ((float*)(Ub + (size_t)t * (PWP * 2) + URR * 2))[h * 64 + row] = r + us; }
	v_pk_mul_f32 v[150:151], v[72:73], v[120:121] op_sel_hi:[0,1]
	v_pk_fma_f32 v[150:151], v[72:73], v[122:123], v[150:151] op_sel:[1,0,0] op_sel_hi:[1,1,1]
	v_pk_fma_f32 v[150:151], v[74:75], v[124:125], v[150:151] op_sel_hi:[0,1,1]
	v_pk_fma_f32 v[150:151], v[74:75], v[126:127], v[150:151] op_sel:[1,0,0] op_sel_hi:[1,1,1]
	v_pk_mul_f32 v[154:155], v[132:133], v[138:139] op_sel:[0,1] op_sel_hi:[1,1]
	v_pk_mul_f32 v[156:157], v[134:135], v[138:139] op_sel:[0,1] op_sel_hi:[1,1]
	v_add_f32_dpp v152, v150, v150 quad_perm:[1,0,3,2] row_mask:0xf bank_mask:0xf bound_ctrl:1
	v_pk_fma_f32 v[154:155], v[72:73], v[116:117], v[154:155]
	v_pk_fma_f32 v[156:157], v[74:75], v[118:119], v[156:157]
	v_add_f32_dpp v152, v152, v152 quad_perm:[2,3,0,1] row_mask:0xf bank_mask:0xf bound_ctrl:1
	ds_read_b128 v[100:103], v162 offset:20224
	ds_read_b128 v[104:107], v163 offset:20224
	v_add_f32_dpp v152, v152, v152 row_half_mirror row_mask:0xf bank_mask:0xf bound_ctrl:1
	ds_read_b128 v[112:115], v198 offset:20992
	ds_read_b128 v[96:99], v198 offset:19968
	v_add_f32_dpp v152, v152, v152 row_mirror row_mask:0xf bank_mask:0xf bound_ctrl:1
	v_pk_fma_f32 v[68:69], v[128:129], v[152:153], v[154:155] op_sel_hi:[1,0,1]
	v_pk_fma_f32 v[70:71], v[130:131], v[152:153], v[156:157] op_sel_hi:[1,0,1]
	ds_read_b128 v[108:111], v198 offset:20736
	s_waitcnt lgkmcnt(5)
	v_pk_mul_f32 v[144:145], v[68:69], v[80:81] op_sel_hi:[0,1]
	v_pk_fma_f32 v[144:145], v[68:69], v[82:83], v[144:145] op_sel:[1,0,0] op_sel_hi:[1,1,1]
	v_pk_fma_f32 v[144:145], v[70:71], v[84:85], v[144:145] op_sel_hi:[0,1,1]
	v_pk_fma_f32 v[144:145], v[70:71], v[86:87], v[144:145] op_sel:[1,0,0] op_sel_hi:[1,1,1]
	v_pk_mul_f32 v[154:155], v[92:93], v[140:141] op_sel_hi:[1,0]
	v_pk_mul_f32 v[156:157], v[94:95], v[140:141] op_sel_hi:[1,0]
	v_add_f32_dpp v152, v144, v144 quad_perm:[1,0,3,2] row_mask:0xf bank_mask:0xf bound_ctrl:1
	v_pk_fma_f32 v[154:155], v[68:69], v[76:77], v[154:155]
	v_pk_fma_f32 v[156:157], v[70:71], v[78:79], v[156:157]
	v_add_f32_dpp v152, v152, v152 quad_perm:[2,3,0,1] row_mask:0xf bank_mask:0xf bound_ctrl:1
	v_add_f32_dpp v158, v147, v147 row_ror:8 row_mask:0xf bank_mask:0xf
	v_add_f32_dpp v159, v149, v149 row_ror:8 row_mask:0xf bank_mask:0xf
	v_add_f32_dpp v152, v152, v152 row_half_mirror row_mask:0xf bank_mask:0xf bound_ctrl:1
	v_add_f32_dpp v158, v151, v151 row_ror:8 row_mask:0xf bank_mask:0xc
	v_add_f32_dpp v159, v145, v145 row_ror:8 row_mask:0xf bank_mask:0xc
	v_add_f32_dpp v152, v152, v152 row_mirror row_mask:0xf bank_mask:0xf bound_ctrl:1
	v_pk_fma_f32 v[72:73], v[88:89], v[152:153], v[154:155] op_sel_hi:[1,0,1]
	v_pk_fma_f32 v[74:75], v[90:91], v[152:153], v[156:157] op_sel_hi:[1,0,1]
	ds_read_b128 v[120:123], v162 offset:21760
	ds_read_b128 v[124:127], v163 offset:21760
	v_add_f32_dpp v160, v158, v158 row_half_mirror row_mask:0xf bank_mask:0xf
	v_add_f32_dpp v160, v159, v159 row_half_mirror row_mask:0xf bank_mask:0xa
	ds_read_b128 v[132:135], v198 offset:22528
	ds_read_b128 v[116:119], v198 offset:21504
	v_add_f32_dpp v160, v160, v160 quad_perm:[1,0,3,2] row_mask:0xf bank_mask:0xf bound_ctrl:1
	ds_read_b128 v[128:131], v198 offset:22272
	s_nop 0
	v_add_f32_dpp v160, v160, v160 quad_perm:[2,3,0,1] row_mask:0xf bank_mask:0xf bound_ctrl:1
	global_store_dword v161, v160, s[34:35]
	v_add_u32_e32 v161, 0xb000, v161
	s_waitcnt lgkmcnt(5)
	v_pk_mul_f32 v[146:147], v[72:73], v[100:101] op_sel_hi:[0,1]
	v_pk_fma_f32 v[146:147], v[72:73], v[102:103], v[146:147] op_sel:[1,0,0] op_sel_hi:[1,1,1]
	v_pk_fma_f32 v[146:147], v[74:75], v[104:105], v[146:147] op_sel_hi:[0,1,1]
	v_pk_fma_f32 v[146:147], v[74:75], v[106:107], v[146:147] op_sel:[1,0,0] op_sel_hi:[1,1,1]
	v_pk_mul_f32 v[154:155], v[112:113], v[140:141] op_sel:[0,1] op_sel_hi:[1,1]
	v_pk_mul_f32 v[156:157], v[114:115], v[140:141] op_sel:[0,1] op_sel_hi:[1,1]
	v_add_f32_dpp v152, v146, v146 quad_perm:[1,0,3,2] row_mask:0xf bank_mask:0xf bound_ctrl:1
	v_pk_fma_f32 v[154:155], v[72:73], v[96:97], v[154:155]
	v_pk_fma_f32 v[156:157], v[74:75], v[98:99], v[156:157]
	v_add_f32_dpp v152, v152, v152 quad_perm:[2,3,0,1] row_mask:0xf bank_mask:0xf bound_ctrl:1
	ds_read_b128 v[80:83], v162 offset:23296
	ds_read_b128 v[84:87], v163 offset:23296
	v_add_f32_dpp v152, v152, v152 row_half_mirror row_mask:0xf bank_mask:0xf bound_ctrl:1
	ds_read_b128 v[92:95], v198 offset:24064
	ds_read_b128 v[76:79], v198 offset:23040
	v_add_f32_dpp v152, v152, v152 row_mirror row_mask:0xf bank_mask:0xf bound_ctrl:1
	v_pk_fma_f32 v[68:69], v[108:109], v[152:153], v[154:155] op_sel_hi:[1,0,1]
	v_pk_fma_f32 v[70:71], v[110:111], v[152:153], v[156:157] op_sel_hi:[1,0,1]
	ds_read_b128 v[88:91], v198 offset:23808
	s_waitcnt lgkmcnt(5)
	v_pk_mul_f32 v[148:149], v[68:69], v[120:121] op_sel_hi:[0,1]
	v_pk_fma_f32 v[148:149], v[68:69], v[122:123], v[148:149] op_sel:[1,0,0] op_sel_hi:[1,1,1]
	v_pk_fma_f32 v[148:149], v[70:71], v[124:125], v[148:149] op_sel_hi:[0,1,1]
	v_pk_fma_f32 v[148:149], v[70:71], v[126:127], v[148:149] op_sel:[1,0,0] op_sel_hi:[1,1,1]
	v_pk_mul_f32 v[154:155], v[132:133], v[142:143] op_sel_hi:[1,0]
	v_pk_mul_f32 v[156:157], v[134:135], v[142:143] op_sel_hi:[1,0]
	v_add_f32_dpp v152, v148, v148 quad_perm:[1,0,3,2] row_mask:0xf bank_mask:0xf bound_ctrl:1
	v_pk_fma_f32 v[154:155], v[68:69], v[116:117], v[154:155]
	v_pk_fma_f32 v[156:157], v[70:71], v[118:119], v[156:157]
	v_add_f32_dpp v152, v152, v152 quad_perm:[2,3,0,1] row_mask:0xf bank_mask:0xf bound_ctrl:1
	ds_read_b128 v[100:103], v162 offset:24832
	ds_read_b128 v[104:107], v163 offset:24832
	v_add_f32_dpp v152, v152, v152 row_half_mirror row_mask:0xf bank_mask:0xf bound_ctrl:1
	ds_read_b128 v[112:115], v198 offset:25600
	ds_read_b128 v[136:139], v204 offset:25856
	v_add_f32_dpp v152, v152, v152 row_mirror row_mask:0xf bank_mask:0xf bound_ctrl:1
	v_pk_fma_f32 v[72:73], v[128:129], v[152:153], v[154:155] op_sel_hi:[1,0,1]
	v_pk_fma_f32 v[74:75], v[130:131], v[152:153], v[156:157] op_sel_hi:[1,0,1]
	ds_read_b128 v[96:99], v198 offset:24576
	ds_read_b128 v[108:111], v198 offset:25344
	s_waitcnt lgkmcnt(6)
; __device__ __forceinline__ void rwkv_scan(Frame& F, int wg, unsigned* shw, unsigned wait_target, int wait_blk) {
;     ...
;             for (int s4 = 0; s4 < RW_TB; s4 += 4) {
;                 float pz[4], u[4];
; #pragma unroll
;                 for (int q = 0; q < 4; ++q) {
;                     RW_LD(R[(q + 3) & 3], s4 + q + 3);
;                     const RwOps& cur = R[q];
;                     const f32x2 slo = {st.x, st.y}, shi = {st.z, st.w};
;                     f32x2 ma = slo * (f32x2){cur.a.x, cur.a.y}; ma = __builtin_elementwise_fma(shi, (f32x2){cur.a.z, cur.a.w}, ma);
;                     f32x2 mz = slo * (f32x2){cur.wr.x, cur.wr.y}; mz = __builtin_elementwise_fma(shi, (f32x2){cur.wr.z, cur.wr.w}, mz);
;                     float psa = ma.x + ma.y; pz[q] = mz.x + mz.y;
;                     const f32x2 vb = {cur.vs.x, cur.vs.x};
;                     f32x2 tlo = (f32x2){cur.k.x, cur.k.y} * vb, thi = (f32x2){cur.k.z, cur.k.w} * vb;
;                     tlo = __builtin_elementwise_fma(slo, (f32x2){cur.w.x, cur.w.y}, tlo); thi = __builtin_elementwise_fma(shi, (f32x2){cur.w.z, cur.w.w}, thi);
;                     psa = red16(psa);
;                     const f32x2 pb = {psa, psa};
;                     tlo = __builtin_elementwise_fma((f32x2){cur.b.x, cur.b.y}, pb, tlo); thi = __builtin_elementwise_fma((f32x2){cur.b.z, cur.b.w}, pb, thi);
;                     st = (f32x4){tlo.x, tlo.y, thi.x, thi.y};
;                     u[q] = psa * cur.vs.z + cur.vs.y;
;                 }
;                 const float qa = (odd1 ? pz[1] : pz[0]) + dppf<0xB1>(odd1 ? pz[0] : pz[1]);
;                 const float qb = (odd1 ? pz[3] : pz[2]) + dppf<0xB1>(odd1 ? pz[2] : pz[3]);
;                 float r = (odd2 ? qb : qa) + dppf<0x4E>(odd2 ? qa : qb);
;                 r += dppf<0x124>(r); r += dppf<0x128>(r);
;                 const float us = odd2 ? (odd1 ? u[3] : u[2]) : (odd1 ? u[1] : u[0]);
;                 if (j < 4) { const int t = blk * RW_TB + s4 + j; ((float*)(Ub + (size_t)t * (PWP * 2) + URR * 2))[h * 64 + row] = r + us; }
	v_pk_mul_f32 v[150:151], v[72:73], v[80:81] op_sel_hi:[0,1]
	v_pk_fma_f32 v[150:151], v[72:73], v[82:83], v[150:151] op_sel:[1,0,0] op_sel_hi:[1,1,1]
	v_pk_fma_f32 v[150:151], v[74:75], v[84:85], v[150:151] op_sel_hi:[0,1,1]
	v_pk_fma_f32 v[150:151], v[74:75], v[86:87], v[150:151] op_sel:[1,0,0] op_sel_hi:[1,1,1]
	v_pk_mul_f32 v[154:155], v[92:93], v[142:143] op_sel:[0,1] op_sel_hi:[1,1]
	v_pk_mul_f32 v[156:157], v[94:95], v[142:143] op_sel:[0,1] op_sel_hi:[1,1]
	v_add_f32_dpp v152, v150, v150 quad_perm:[1,0,3,2] row_mask:0xf bank_mask:0xf bound_ctrl:1
	v_pk_fma_f32 v[154:155], v[72:73], v[76:77], v[154:155]
	v_pk_fma_f32 v[156:157], v[74:75], v[78:79], v[156:157]
	v_add_f32_dpp v152, v152, v152 quad_perm:[2,3,0,1] row_mask:0xf bank_mask:0xf bound_ctrl:1
	ds_read_b128 v[120:123], v162 offset:26368
	ds_read_b128 v[124:127], v163 offset:26368
	v_add_f32_dpp v152, v152, v152 row_half_mirror row_mask:0xf bank_mask:0xf bound_ctrl:1
	ds_read_b128 v[132:135], v198 offset:27136
	ds_read_b128 v[116:119], v198 offset:26112
	v_add_f32_dpp v152, v152, v152 row_mirror row_mask:0xf bank_mask:0xf bound_ctrl:1
	v_pk_fma_f32 v[68:69], v[88:89], v[152:153], v[154:155] op_sel_hi:[1,0,1]
	v_pk_fma_f32 v[70:71], v[90:91], v[152:153], v[156:157] op_sel_hi:[1,0,1]
	ds_read_b128 v[128:131], v198 offset:26880
	s_waitcnt lgkmcnt(5)
	v_pk_mul_f32 v[144:145], v[68:69], v[100:101] op_sel_hi:[0,1]
	v_pk_fma_f32 v[144:145], v[68:69], v[102:103], v[144:145] op_sel:[1,0,0] op_sel_hi:[1,1,1]
	v_pk_fma_f32 v[144:145], v[70:71], v[104:105], v[144:145] op_sel_hi:[0,1,1]
	v_pk_fma_f32 v[144:145], v[70:71], v[106:107], v[144:145] op_sel:[1,0,0] op_sel_hi:[1,1,1]
	v_pk_mul_f32 v[154:155], v[112:113], v[136:137] op_sel_hi:[1,0]
	v_pk_mul_f32 v[156:157], v[114:115], v[136:137] op_sel_hi:[1,0]
	v_add_f32_dpp v152, v144, v144 quad_perm:[1,0,3,2] row_mask:0xf bank_mask:0xf bound_ctrl:1
	v_pk_fma_f32 v[154:155], v[68:69], v[96:97], v[154:155]
	v_pk_fma_f32 v[156:157], v[70:71], v[98:99], v[156:157]
	v_add_f32_dpp v152, v152, v152 quad_perm:[2,3,0,1] row_mask:0xf bank_mask:0xf bound_ctrl:1
	v_add_f32_dpp v158, v147, v147 row_ror:8 row_mask:0xf bank_mask:0xf
	v_add_f32_dpp v159, v149, v149 row_ror:8 row_mask:0xf bank_mask:0xf
	v_add_f32_dpp v152, v152, v152 row_half_mirror row_mask:0xf bank_mask:0xf bound_ctrl:1
	v_add_f32_dpp v158, v151, v151 row_ror:8 row_mask:0xf bank_mask:0xc
	v_add_f32_dpp v159, v145, v145 row_ror:8 row_mask:0xf bank_mask:0xc
	v_add_f32_dpp v152, v152, v152 row_mirror row_mask:0xf bank_mask:0xf bound_ctrl:1
	v_pk_fma_f32 v[72:73], v[108:109], v[152:153], v[154:155] op_sel_hi:[1,0,1]
	v_pk_fma_f32 v[74:75], v[110:111], v[152:153], v[156:157] op_sel_hi:[1,0,1]
	ds_read_b128 v[80:83], v162 offset:27904
	ds_read_b128 v[84:87], v163 offset:27904
	v_add_f32_dpp v160, v158, v158 row_half_mirror row_mask:0xf bank_mask:0xf
	v_add_f32_dpp v160, v159, v159 row_half_mirror row_mask:0xf bank_mask:0xa
	ds_read_b128 v[92:95], v198 offset:28672
	ds_read_b128 v[76:79], v198 offset:27648
	v_add_f32_dpp v160, v160, v160 quad_perm:[1,0,3,2] row_mask:0xf bank_mask:0xf bound_ctrl:1
	ds_read_b128 v[88:91], v198 offset:28416
	s_nop 0
	v_add_f32_dpp v160, v160, v160 quad_perm:[2,3,0,1] row_mask:0xf bank_mask:0xf bound_ctrl:1
	global_store_dword v161, v160, s[34:35]
	v_add_u32_e32 v161, 0xb000, v161
	s_waitcnt lgkmcnt(5)
	v_pk_mul_f32 v[146:147], v[72:73], v[120:121] op_sel_hi:[0,1]
	v_pk_fma_f32 v[146:147], v[72:73], v[122:123], v[146:147] op_sel:[1,0,0] op_sel_hi:[1,1,1]
	v_pk_fma_f32 v[146:147], v[74:75], v[124:125], v[146:147] op_sel_hi:[0,1,1]
	v_pk_fma_f32 v[146:147], v[74:75], v[126:127], v[146:147] op_sel:[1,0,0] op_sel_hi:[1,1,1]
	v_pk_mul_f32 v[154:155], v[132:133], v[136:137] op_sel:[0,1] op_sel_hi:[1,1]
	v_pk_mul_f32 v[156:157], v[134:135], v[136:137] op_sel:[0,1] op_sel_hi:[1,1]
	v_add_f32_dpp v152, v146, v146 quad_perm:[1,0,3,2] row_mask:0xf bank_mask:0xf bound_ctrl:1
	v_pk_fma_f32 v[154:155], v[72:73], v[116:117], v[154:155]
	v_pk_fma_f32 v[156:157], v[74:75], v[118:119], v[156:157]
	v_add_f32_dpp v152, v152, v152 quad_perm:[2,3,0,1] row_mask:0xf bank_mask:0xf bound_ctrl:1
	ds_read_b128 v[100:103], v162 offset:29440
	ds_read_b128 v[104:107], v163 offset:29440
	v_add_f32_dpp v152, v152, v152 row_half_mirror row_mask:0xf bank_mask:0xf bound_ctrl:1
	ds_read_b128 v[112:115], v198 offset:30208
	ds_read_b128 v[96:99], v198 offset:29184
	v_add_f32_dpp v152, v152, v152 row_mirror row_mask:0xf bank_mask:0xf bound_ctrl:1
	v_pk_fma_f32 v[68:69], v[128:129], v[152:153], v[154:155] op_sel_hi:[1,0,1]
	v_pk_fma_f32 v[70:71], v[130:131], v[152:153], v[156:157] op_sel_hi:[1,0,1]
	ds_read_b128 v[108:111], v198 offset:29952
	s_waitcnt lgkmcnt(5)
	v_pk_mul_f32 v[148:149], v[68:69], v[80:81] op_sel_hi:[0,1]
	v_pk_fma_f32 v[148:149], v[68:69], v[82:83], v[148:149] op_sel:[1,0,0] op_sel_hi:[1,1,1]
	v_pk_fma_f32 v[148:149], v[70:71], v[84:85], v[148:149] op_sel_hi:[0,1,1]
	v_pk_fma_f32 v[148:149], v[70:71], v[86:87], v[148:149] op_sel:[1,0,0] op_sel_hi:[1,1,1]
	v_pk_mul_f32 v[154:155], v[92:93], v[138:139] op_sel_hi:[1,0]
	v_pk_mul_f32 v[156:157], v[94:95], v[138:139] op_sel_hi:[1,0]
	v_add_f32_dpp v152, v148, v148 quad_perm:[1,0,3,2] row_mask:0xf bank_mask:0xf bound_ctrl:1
	v_pk_fma_f32 v[154:155], v[68:69], v[76:77], v[154:155]
	v_pk_fma_f32 v[156:157], v[70:71], v[78:79], v[156:157]
	v_add_f32_dpp v152, v152, v152 quad_perm:[2,3,0,1] row_mask:0xf bank_mask:0xf bound_ctrl:1
	ds_read_b128 v[120:123], v162 offset:30976
	ds_read_b128 v[124:127], v163 offset:30976
	v_add_f32_dpp v152, v152, v152 row_half_mirror row_mask:0xf bank_mask:0xf bound_ctrl:1
	ds_read_b128 v[132:135], v198 offset:31744
	ds_read_b128 v[140:143], v204 offset:32000
	v_add_f32_dpp v152, v152, v152 row_mirror row_mask:0xf bank_mask:0xf bound_ctrl:1
	v_pk_fma_f32 v[72:73], v[88:89], v[152:153], v[154:155] op_sel_hi:[1,0,1]
	v_pk_fma_f32 v[74:75], v[90:91], v[152:153], v[156:157] op_sel_hi:[1,0,1]
	ds_read_b128 v[116:119], v198 offset:30720
	ds_read_b128 v[128:131], v198 offset:31488
	s_waitcnt lgkmcnt(6)
; __device__ __forceinline__ void rwkv_scan(Frame& F, int wg, unsigned* shw, unsigned wait_target, int wait_blk) {
;     ...
;             for (int s4 = 0; s4 < RW_TB; s4 += 4) {
;                 float pz[4], u[4];
; #pragma unroll
;                 for (int q = 0; q < 4; ++q) {
;                     RW_LD(R[(q + 3) & 3], s4 + q + 3);
;                     const RwOps& cur = R[q];
;                     const f32x2 slo = {st.x, st.y}, shi = {st.z, st.w};
;                     f32x2 ma = slo * (f32x2){cur.a.x, cur.a.y}; ma = __builtin_elementwise_fma(shi, (f32x2){cur.a.z, cur.a.w}, ma);
;                     f32x2 mz = slo * (f32x2){cur.wr.x, cur.wr.y}; mz = __builtin_elementwise_fma(shi, (f32x2){cur.wr.z, cur.wr.w}, mz);
;                     float psa = ma.x + ma.y; pz[q] = mz.x + mz.y;
;                     const f32x2 vb = {cur.vs.x, cur.vs.x};
;                     f32x2 tlo = (f32x2){cur.k.x, cur.k.y} * vb, thi = (f32x2){cur.k.z, cur.k.w} * vb;
;                     tlo = __builtin_elementwise_fma(slo, (f32x2){cur.w.x, cur.w.y}, tlo); thi = __builtin_elementwise_fma(shi, (f32x2){cur.w.z, cur.w.w}, thi);
;                     psa = red16(psa);
;                     const f32x2 pb = {psa, psa};
;                     tlo = __builtin_elementwise_fma((f32x2){cur.b.x, cur.b.y}, pb, tlo); thi = __builtin_elementwise_fma((f32x2){cur.b.z, cur.b.w}, pb, thi);
;                     st = (f32x4){tlo.x, tlo.y, thi.x, thi.y};
;                     u[q] = psa * cur.vs.z + cur.vs.y;
;                 }
;                 const float qa = (odd1 ? pz[1] : pz[0]) + dppf<0xB1>(odd1 ? pz[0] : pz[1]);
;                 const float qb = (odd1 ? pz[3] : pz[2]) + dppf<0xB1>(odd1 ? pz[2] : pz[3]);
;                 float r = (odd2 ? qb : qa) + dppf<0x4E>(odd2 ? qa : qb);
;                 r += dppf<0x124>(r); r += dppf<0x128>(r);
;                 const float us = odd2 ? (odd1 ? u[3] : u[2]) : (odd1 ? u[1] : u[0]);
;                 if (j < 4) { const int t = blk * RW_TB + s4 + j; ((float*)(Ub + (size_t)t * (PWP * 2) + URR * 2))[h * 64 + row] = r + us; }
	v_pk_mul_f32 v[150:151], v[72:73], v[100:101] op_sel_hi:[0,1]
	v_pk_fma_f32 v[150:151], v[72:73], v[102:103], v[150:151] op_sel:[1,0,0] op_sel_hi:[1,1,1]
	v_pk_fma_f32 v[150:151], v[74:75], v[104:105], v[150:151] op_sel_hi:[0,1,1]
	v_pk_fma_f32 v[150:151], v[74:75], v[106:107], v[150:151] op_sel:[1,0,0] op_sel_hi:[1,1,1]
	v_pk_mul_f32 v[154:155], v[112:113], v[138:139] op_sel:[0,1] op_sel_hi:[1,1]
	v_pk_mul_f32 v[156:157], v[114:115], v[138:139] op_sel:[0,1] op_sel_hi:[1,1]
	v_add_f32_dpp v152, v150, v150 quad_perm:[1,0,3,2] row_mask:0xf bank_mask:0xf bound_ctrl:1
	v_pk_fma_f32 v[154:155], v[72:73], v[96:97], v[154:155]
	v_pk_fma_f32 v[156:157], v[74:75], v[98:99], v[156:157]
	v_add_f32_dpp v152, v152, v152 quad_perm:[2,3,0,1] row_mask:0xf bank_mask:0xf bound_ctrl:1
	ds_read_b128 v[80:83], v162 offset:32512
	ds_read_b128 v[84:87], v163 offset:32512
	v_add_f32_dpp v152, v152, v152 row_half_mirror row_mask:0xf bank_mask:0xf bound_ctrl:1
	ds_read_b128 v[92:95], v198 offset:33280
	ds_read_b128 v[76:79], v198 offset:32256
	v_add_f32_dpp v152, v152, v152 row_mirror row_mask:0xf bank_mask:0xf bound_ctrl:1
	v_pk_fma_f32 v[68:69], v[108:109], v[152:153], v[154:155] op_sel_hi:[1,0,1]
	v_pk_fma_f32 v[70:71], v[110:111], v[152:153], v[156:157] op_sel_hi:[1,0,1]
	ds_read_b128 v[88:91], v198 offset:33024
	s_waitcnt lgkmcnt(5)
	v_pk_mul_f32 v[144:145], v[68:69], v[120:121] op_sel_hi:[0,1]
	v_pk_fma_f32 v[144:145], v[68:69], v[122:123], v[144:145] op_sel:[1,0,0] op_sel_hi:[1,1,1]
	v_pk_fma_f32 v[144:145], v[70:71], v[124:125], v[144:145] op_sel_hi:[0,1,1]
	v_pk_fma_f32 v[144:145], v[70:71], v[126:127], v[144:145] op_sel:[1,0,0] op_sel_hi:[1,1,1]
	v_pk_mul_f32 v[154:155], v[132:133], v[140:141] op_sel_hi:[1,0]
	v_pk_mul_f32 v[156:157], v[134:135], v[140:141] op_sel_hi:[1,0]
	v_add_f32_dpp v152, v144, v144 quad_perm:[1,0,3,2] row_mask:0xf bank_mask:0xf bound_ctrl:1
	v_pk_fma_f32 v[154:155], v[68:69], v[116:117], v[154:155]
	v_pk_fma_f32 v[156:157], v[70:71], v[118:119], v[156:157]
	v_add_f32_dpp v152, v152, v152 quad_perm:[2,3,0,1] row_mask:0xf bank_mask:0xf bound_ctrl:1
	v_add_f32_dpp v158, v147, v147 row_ror:8 row_mask:0xf bank_mask:0xf
	v_add_f32_dpp v159, v149, v149 row_ror:8 row_mask:0xf bank_mask:0xf
	v_add_f32_dpp v152, v152, v152 row_half_mirror row_mask:0xf bank_mask:0xf bound_ctrl:1
	v_add_f32_dpp v158, v151, v151 row_ror:8 row_mask:0xf bank_mask:0xc
	v_add_f32_dpp v159, v145, v145 row_ror:8 row_mask:0xf bank_mask:0xc
	v_add_f32_dpp v152, v152, v152 row_mirror row_mask:0xf bank_mask:0xf bound_ctrl:1
	v_pk_fma_f32 v[72:73], v[128:129], v[152:153], v[154:155] op_sel_hi:[1,0,1]
	v_pk_fma_f32 v[74:75], v[130:131], v[152:153], v[156:157] op_sel_hi:[1,0,1]
	ds_read_b128 v[100:103], v162 offset:34048
	ds_read_b128 v[104:107], v163 offset:34048
	v_add_f32_dpp v160, v158, v158 row_half_mirror row_mask:0xf bank_mask:0xf
	v_add_f32_dpp v160, v159, v159 row_half_mirror row_mask:0xf bank_mask:0xa
	ds_read_b128 v[112:115], v198 offset:34816
	ds_read_b128 v[96:99], v198 offset:33792
	v_add_f32_dpp v160, v160, v160 quad_perm:[1,0,3,2] row_mask:0xf bank_mask:0xf bound_ctrl:1
	ds_read_b128 v[108:111], v198 offset:34560
	s_nop 0
	v_add_f32_dpp v160, v160, v160 quad_perm:[2,3,0,1] row_mask:0xf bank_mask:0xf bound_ctrl:1
	global_store_dword v161, v160, s[34:35]
	v_add_u32_e32 v161, 0xb000, v161
	s_waitcnt lgkmcnt(5)
	v_pk_mul_f32 v[146:147], v[72:73], v[80:81] op_sel_hi:[0,1]
	v_pk_fma_f32 v[146:147], v[72:73], v[82:83], v[146:147] op_sel:[1,0,0] op_sel_hi:[1,1,1]
	v_pk_fma_f32 v[146:147], v[74:75], v[84:85], v[146:147] op_sel_hi:[0,1,1]
	v_pk_fma_f32 v[146:147], v[74:75], v[86:87], v[146:147] op_sel:[1,0,0] op_sel_hi:[1,1,1]
	v_pk_mul_f32 v[154:155], v[92:93], v[140:141] op_sel:[0,1] op_sel_hi:[1,1]
	v_pk_mul_f32 v[156:157], v[94:95], v[140:141] op_sel:[0,1] op_sel_hi:[1,1]
	v_add_f32_dpp v152, v146, v146 quad_perm:[1,0,3,2] row_mask:0xf bank_mask:0xf bound_ctrl:1
	v_pk_fma_f32 v[154:155], v[72:73], v[76:77], v[154:155]
	v_pk_fma_f32 v[156:157], v[74:75], v[78:79], v[156:157]
	v_add_f32_dpp v152, v152, v152 quad_perm:[2,3,0,1] row_mask:0xf bank_mask:0xf bound_ctrl:1
	ds_read_b128 v[120:123], v162 offset:35584
	ds_read_b128 v[124:127], v163 offset:35584
	v_add_f32_dpp v152, v152, v152 row_half_mirror row_mask:0xf bank_mask:0xf bound_ctrl:1
	ds_read_b128 v[132:135], v198 offset:36352
	ds_read_b128 v[116:119], v198 offset:35328
	v_add_f32_dpp v152, v152, v152 row_mirror row_mask:0xf bank_mask:0xf bound_ctrl:1
	v_pk_fma_f32 v[68:69], v[88:89], v[152:153], v[154:155] op_sel_hi:[1,0,1]
	v_pk_fma_f32 v[70:71], v[90:91], v[152:153], v[156:157] op_sel_hi:[1,0,1]
	ds_read_b128 v[128:131], v198 offset:36096
	s_waitcnt lgkmcnt(5)
	v_pk_mul_f32 v[148:149], v[68:69], v[100:101] op_sel_hi:[0,1]
	v_pk_fma_f32 v[148:149], v[68:69], v[102:103], v[148:149] op_sel:[1,0,0] op_sel_hi:[1,1,1]
	v_pk_fma_f32 v[148:149], v[70:71], v[104:105], v[148:149] op_sel_hi:[0,1,1]
	v_pk_fma_f32 v[148:149], v[70:71], v[106:107], v[148:149] op_sel:[1,0,0] op_sel_hi:[1,1,1]
	v_pk_mul_f32 v[154:155], v[112:113], v[142:143] op_sel_hi:[1,0]
	v_pk_mul_f32 v[156:157], v[114:115], v[142:143] op_sel_hi:[1,0]
	v_add_f32_dpp v152, v148, v148 quad_perm:[1,0,3,2] row_mask:0xf bank_mask:0xf bound_ctrl:1
	v_pk_fma_f32 v[154:155], v[68:69], v[96:97], v[154:155]
	v_pk_fma_f32 v[156:157], v[70:71], v[98:99], v[156:157]
	v_add_f32_dpp v152, v152, v152 quad_perm:[2,3,0,1] row_mask:0xf bank_mask:0xf bound_ctrl:1
	ds_read_b128 v[80:83], v162 offset:37120
	ds_read_b128 v[84:87], v163 offset:37120
	v_add_f32_dpp v152, v152, v152 row_half_mirror row_mask:0xf bank_mask:0xf bound_ctrl:1
	ds_read_b128 v[92:95], v198 offset:37888
	ds_read_b128 v[136:139], v204 offset:38144
	v_add_f32_dpp v152, v152, v152 row_mirror row_mask:0xf bank_mask:0xf bound_ctrl:1
	v_pk_fma_f32 v[72:73], v[108:109], v[152:153], v[154:155] op_sel_hi:[1,0,1]
	v_pk_fma_f32 v[74:75], v[110:111], v[152:153], v[156:157] op_sel_hi:[1,0,1]
	ds_read_b128 v[76:79], v198 offset:36864
	ds_read_b128 v[88:91], v198 offset:37632
	s_waitcnt lgkmcnt(6)
; __device__ __forceinline__ void rwkv_scan(Frame& F, int wg, unsigned* shw, unsigned wait_target, int wait_blk) {
;     ...
;             for (int s4 = 0; s4 < RW_TB; s4 += 4) {
;                 float pz[4], u[4];
; #pragma unroll
;                 for (int q = 0; q < 4; ++q) {
;                     RW_LD(R[(q + 3) & 3], s4 + q + 3);
;                     const RwOps& cur = R[q];
;                     const f32x2 slo = {st.x, st.y}, shi = {st.z, st.w};
;                     f32x2 ma = slo * (f32x2){cur.a.x, cur.a.y}; ma = __builtin_elementwise_fma(shi, (f32x2){cur.a.z, cur.a.w}, ma);
;                     f32x2 mz = slo * (f32x2){cur.wr.x, cur.wr.y}; mz = __builtin_elementwise_fma(shi, (f32x2){cur.wr.z, cur.wr.w}, mz);
;                     float psa = ma.x + ma.y; pz[q] = mz.x + mz.y;
;                     const f32x2 vb = {cur.vs.x, cur.vs.x};
;                     f32x2 tlo = (f32x2){cur.k.x, cur.k.y} * vb, thi = (f32x2){cur.k.z, cur.k.w} * vb;
;                     tlo = __builtin_elementwise_fma(slo, (f32x2){cur.w.x, cur.w.y}, tlo); thi = __builtin_elementwise_fma(shi, (f32x2){cur.w.z, cur.w.w}, thi);
;                     psa = red16(psa);
;                     const f32x2 pb = {psa, psa};
;                     tlo = __builtin_elementwise_fma((f32x2){cur.b.x, cur.b.y}, pb, tlo); thi = __builtin_elementwise_fma((f32x2){cur.b.z, cur.b.w}, pb, thi);
;                     st = (f32x4){tlo.x, tlo.y, thi.x, thi.y};
;                     u[q] = psa * cur.vs.z + cur.vs.y;
;                 }
;                 const float qa = (odd1 ? pz[1] : pz[0]) + dppf<0xB1>(odd1 ? pz[0] : pz[1]);
;                 const float qb = (odd1 ? pz[3] : pz[2]) + dppf<0xB1>(odd1 ? pz[2] : pz[3]);
;                 float r = (odd2 ? qb : qa) + dppf<0x4E>(odd2 ? qa : qb);
;                 r += dppf<0x124>(r); r += dppf<0x128>(r);
;                 const float us = odd2 ? (odd1 ? u[3] : u[2]) : (odd1 ? u[1] : u[0]);
;                 if (j < 4) { const int t = blk * RW_TB + s4 + j; ((float*)(Ub + (size_t)t * (PWP * 2) + URR * 2))[h * 64 + row] = r + us; }
	v_pk_mul_f32 v[150:151], v[72:73], v[120:121] op_sel_hi:[0,1]
	v_pk_fma_f32 v[150:151], v[72:73], v[122:123], v[150:151] op_sel:[1,0,0] op_sel_hi:[1,1,1]
	v_pk_fma_f32 v[150:151], v[74:75], v[124:125], v[150:151] op_sel_hi:[0,1,1]
	v_pk_fma_f32 v[150:151], v[74:75], v[126:127], v[150:151] op_sel:[1,0,0] op_sel_hi:[1,1,1]
	v_pk_mul_f32 v[154:155], v[132:133], v[142:143] op_sel:[0,1] op_sel_hi:[1,1]
	v_pk_mul_f32 v[156:157], v[134:135], v[142:143] op_sel:[0,1] op_sel_hi:[1,1]
	v_add_f32_dpp v152, v150, v150 quad_perm:[1,0,3,2] row_mask:0xf bank_mask:0xf bound_ctrl:1
	v_pk_fma_f32 v[154:155], v[72:73], v[116:117], v[154:155]
	v_pk_fma_f32 v[156:157], v[74:75], v[118:119], v[156:157]
	v_add_f32_dpp v152, v152, v152 quad_perm:[2,3,0,1] row_mask:0xf bank_mask:0xf bound_ctrl:1
	ds_read_b128 v[100:103], v162 offset:38656
	ds_read_b128 v[104:107], v163 offset:38656
	v_add_f32_dpp v152, v152, v152 row_half_mirror row_mask:0xf bank_mask:0xf bound_ctrl:1
	ds_read_b128 v[112:115], v198 offset:39424
	ds_read_b128 v[96:99], v198 offset:38400
	v_add_f32_dpp v152, v152, v152 row_mirror row_mask:0xf bank_mask:0xf bound_ctrl:1
	v_pk_fma_f32 v[68:69], v[128:129], v[152:153], v[154:155] op_sel_hi:[1,0,1]
	v_pk_fma_f32 v[70:71], v[130:131], v[152:153], v[156:157] op_sel_hi:[1,0,1]
	ds_read_b128 v[108:111], v198 offset:39168
	s_waitcnt lgkmcnt(5)
	v_pk_mul_f32 v[144:145], v[68:69], v[80:81] op_sel_hi:[0,1]
	v_pk_fma_f32 v[144:145], v[68:69], v[82:83], v[144:145] op_sel:[1,0,0] op_sel_hi:[1,1,1]
	v_pk_fma_f32 v[144:145], v[70:71], v[84:85], v[144:145] op_sel_hi:[0,1,1]
	v_pk_fma_f32 v[144:145], v[70:71], v[86:87], v[144:145] op_sel:[1,0,0] op_sel_hi:[1,1,1]
	v_pk_mul_f32 v[154:155], v[92:93], v[136:137] op_sel_hi:[1,0]
	v_pk_mul_f32 v[156:157], v[94:95], v[136:137] op_sel_hi:[1,0]
	v_add_f32_dpp v152, v144, v144 quad_perm:[1,0,3,2] row_mask:0xf bank_mask:0xf bound_ctrl:1
	v_pk_fma_f32 v[154:155], v[68:69], v[76:77], v[154:155]
	v_pk_fma_f32 v[156:157], v[70:71], v[78:79], v[156:157]
	v_add_f32_dpp v152, v152, v152 quad_perm:[2,3,0,1] row_mask:0xf bank_mask:0xf bound_ctrl:1
	v_add_f32_dpp v158, v147, v147 row_ror:8 row_mask:0xf bank_mask:0xf
	v_add_f32_dpp v159, v149, v149 row_ror:8 row_mask:0xf bank_mask:0xf
	v_add_f32_dpp v152, v152, v152 row_half_mirror row_mask:0xf bank_mask:0xf bound_ctrl:1
	v_add_f32_dpp v158, v151, v151 row_ror:8 row_mask:0xf bank_mask:0xc
	v_add_f32_dpp v159, v145, v145 row_ror:8 row_mask:0xf bank_mask:0xc
	v_add_f32_dpp v152, v152, v152 row_mirror row_mask:0xf bank_mask:0xf bound_ctrl:1
	v_pk_fma_f32 v[72:73], v[88:89], v[152:153], v[154:155] op_sel_hi:[1,0,1]
	v_pk_fma_f32 v[74:75], v[90:91], v[152:153], v[156:157] op_sel_hi:[1,0,1]
	ds_read_b128 v[120:123], v162 offset:40192
	ds_read_b128 v[124:127], v163 offset:40192
	v_add_f32_dpp v160, v158, v158 row_half_mirror row_mask:0xf bank_mask:0xf
	v_add_f32_dpp v160, v159, v159 row_half_mirror row_mask:0xf bank_mask:0xa
	ds_read_b128 v[132:135], v198 offset:40960
	ds_read_b128 v[116:119], v198 offset:39936
	v_add_f32_dpp v160, v160, v160 quad_perm:[1,0,3,2] row_mask:0xf bank_mask:0xf bound_ctrl:1
	ds_read_b128 v[128:131], v198 offset:40704
	s_nop 0
	v_add_f32_dpp v160, v160, v160 quad_perm:[2,3,0,1] row_mask:0xf bank_mask:0xf bound_ctrl:1
	global_store_dword v161, v160, s[34:35]
	v_add_u32_e32 v161, 0xb000, v161
	s_waitcnt lgkmcnt(5)
	v_pk_mul_f32 v[146:147], v[72:73], v[100:101] op_sel_hi:[0,1]
	v_pk_fma_f32 v[146:147], v[72:73], v[102:103], v[146:147] op_sel:[1,0,0] op_sel_hi:[1,1,1]
	v_pk_fma_f32 v[146:147], v[74:75], v[104:105], v[146:147] op_sel_hi:[0,1,1]
	v_pk_fma_f32 v[146:147], v[74:75], v[106:107], v[146:147] op_sel:[1,0,0] op_sel_hi:[1,1,1]
	v_pk_mul_f32 v[154:155], v[112:113], v[136:137] op_sel:[0,1] op_sel_hi:[1,1]
	v_pk_mul_f32 v[156:157], v[114:115], v[136:137] op_sel:[0,1] op_sel_hi:[1,1]
	v_add_f32_dpp v152, v146, v146 quad_perm:[1,0,3,2] row_mask:0xf bank_mask:0xf bound_ctrl:1
	v_pk_fma_f32 v[154:155], v[72:73], v[96:97], v[154:155]
	v_pk_fma_f32 v[156:157], v[74:75], v[98:99], v[156:157]
	v_add_f32_dpp v152, v152, v152 quad_perm:[2,3,0,1] row_mask:0xf bank_mask:0xf bound_ctrl:1
	ds_read_b128 v[80:83], v162 offset:41728
	ds_read_b128 v[84:87], v163 offset:41728
	v_add_f32_dpp v152, v152, v152 row_half_mirror row_mask:0xf bank_mask:0xf bound_ctrl:1
	ds_read_b128 v[92:95], v198 offset:42496
	ds_read_b128 v[76:79], v198 offset:41472
	v_add_f32_dpp v152, v152, v152 row_mirror row_mask:0xf bank_mask:0xf bound_ctrl:1
	v_pk_fma_f32 v[68:69], v[108:109], v[152:153], v[154:155] op_sel_hi:[1,0,1]
	v_pk_fma_f32 v[70:71], v[110:111], v[152:153], v[156:157] op_sel_hi:[1,0,1]
	ds_read_b128 v[88:91], v198 offset:42240
	s_waitcnt lgkmcnt(5)
	v_pk_mul_f32 v[148:149], v[68:69], v[120:121] op_sel_hi:[0,1]
	v_pk_fma_f32 v[148:149], v[68:69], v[122:123], v[148:149] op_sel:[1,0,0] op_sel_hi:[1,1,1]
	v_pk_fma_f32 v[148:149], v[70:71], v[124:125], v[148:149] op_sel_hi:[0,1,1]
	v_pk_fma_f32 v[148:149], v[70:71], v[126:127], v[148:149] op_sel:[1,0,0] op_sel_hi:[1,1,1]
	v_pk_mul_f32 v[154:155], v[132:133], v[138:139] op_sel_hi:[1,0]
	v_pk_mul_f32 v[156:157], v[134:135], v[138:139] op_sel_hi:[1,0]
	v_add_f32_dpp v152, v148, v148 quad_perm:[1,0,3,2] row_mask:0xf bank_mask:0xf bound_ctrl:1
	v_pk_fma_f32 v[154:155], v[68:69], v[116:117], v[154:155]
	v_pk_fma_f32 v[156:157], v[70:71], v[118:119], v[156:157]
	v_add_f32_dpp v152, v152, v152 quad_perm:[2,3,0,1] row_mask:0xf bank_mask:0xf bound_ctrl:1
	ds_read_b128 v[100:103], v162 offset:43264
	ds_read_b128 v[104:107], v163 offset:43264
	v_add_f32_dpp v152, v152, v152 row_half_mirror row_mask:0xf bank_mask:0xf bound_ctrl:1
	ds_read_b128 v[112:115], v198 offset:44032
	ds_read_b128 v[140:143], v204 offset:44288
	v_add_f32_dpp v152, v152, v152 row_mirror row_mask:0xf bank_mask:0xf bound_ctrl:1
	v_pk_fma_f32 v[72:73], v[128:129], v[152:153], v[154:155] op_sel_hi:[1,0,1]
	v_pk_fma_f32 v[74:75], v[130:131], v[152:153], v[156:157] op_sel_hi:[1,0,1]
	ds_read_b128 v[96:99], v198 offset:43008
	ds_read_b128 v[108:111], v198 offset:43776
	s_waitcnt lgkmcnt(6)
; __device__ __forceinline__ void rwkv_scan(Frame& F, int wg, unsigned* shw, unsigned wait_target, int wait_blk) {
;     ...
;             for (int s4 = 0; s4 < RW_TB; s4 += 4) {
;                 float pz[4], u[4];
; #pragma unroll
;                 for (int q = 0; q < 4; ++q) {
;                     RW_LD(R[(q + 3) & 3], s4 + q + 3);
;                     const RwOps& cur = R[q];
;                     const f32x2 slo = {st.x, st.y}, shi = {st.z, st.w};
;                     f32x2 ma = slo * (f32x2){cur.a.x, cur.a.y}; ma = __builtin_elementwise_fma(shi, (f32x2){cur.a.z, cur.a.w}, ma);
;                     f32x2 mz = slo * (f32x2){cur.wr.x, cur.wr.y}; mz = __builtin_elementwise_fma(shi, (f32x2){cur.wr.z, cur.wr.w}, mz);
;                     float psa = ma.x + ma.y; pz[q] = mz.x + mz.y;
;                     const f32x2 vb = {cur.vs.x, cur.vs.x};
;                     f32x2 tlo = (f32x2){cur.k.x, cur.k.y} * vb, thi = (f32x2){cur.k.z, cur.k.w} * vb;
;                     tlo = __builtin_elementwise_fma(slo, (f32x2){cur.w.x, cur.w.y}, tlo); thi = __builtin_elementwise_fma(shi, (f32x2){cur.w.z, cur.w.w}, thi);
;                     psa = red16(psa);
;                     const f32x2 pb = {psa, psa};
;                     tlo = __builtin_elementwise_fma((f32x2){cur.b.x, cur.b.y}, pb, tlo); thi = __builtin_elementwise_fma((f32x2){cur.b.z, cur.b.w}, pb, thi);
;                     st = (f32x4){tlo.x, tlo.y, thi.x, thi.y};
;                     u[q] = psa * cur.vs.z + cur.vs.y;
;                 }
;                 const float qa = (odd1 ? pz[1] : pz[0]) + dppf<0xB1>(odd1 ? pz[0] : pz[1]);
;                 const float qb = (odd1 ? pz[3] : pz[2]) + dppf<0xB1>(odd1 ? pz[2] : pz[3]);
;                 float r = (odd2 ? qb : qa) + dppf<0x4E>(odd2 ? qa : qb);
;                 r += dppf<0x124>(r); r += dppf<0x128>(r);
;                 const float us = odd2 ? (odd1 ? u[3] : u[2]) : (odd1 ? u[1] : u[0]);
;                 if (j < 4) { const int t = blk * RW_TB + s4 + j; ((float*)(Ub + (size_t)t * (PWP * 2) + URR * 2))[h * 64 + row] = r + us; }
	v_pk_mul_f32 v[150:151], v[72:73], v[80:81] op_sel_hi:[0,1]
	v_pk_fma_f32 v[150:151], v[72:73], v[82:83], v[150:151] op_sel:[1,0,0] op_sel_hi:[1,1,1]
	v_pk_fma_f32 v[150:151], v[74:75], v[84:85], v[150:151] op_sel_hi:[0,1,1]
	v_pk_fma_f32 v[150:151], v[74:75], v[86:87], v[150:151] op_sel:[1,0,0] op_sel_hi:[1,1,1]
	v_pk_mul_f32 v[154:155], v[92:93], v[138:139] op_sel:[0,1] op_sel_hi:[1,1]
	v_pk_mul_f32 v[156:157], v[94:95], v[138:139] op_sel:[0,1] op_sel_hi:[1,1]
	v_add_f32_dpp v152, v150, v150 quad_perm:[1,0,3,2] row_mask:0xf bank_mask:0xf bound_ctrl:1
	v_pk_fma_f32 v[154:155], v[72:73], v[76:77], v[154:155]
	v_pk_fma_f32 v[156:157], v[74:75], v[78:79], v[156:157]
	v_add_f32_dpp v152, v152, v152 quad_perm:[2,3,0,1] row_mask:0xf bank_mask:0xf bound_ctrl:1
	ds_read_b128 v[120:123], v162 offset:44800
	ds_read_b128 v[124:127], v163 offset:44800
	v_add_f32_dpp v152, v152, v152 row_half_mirror row_mask:0xf bank_mask:0xf bound_ctrl:1
	ds_read_b128 v[132:135], v198 offset:45568
	ds_read_b128 v[116:119], v198 offset:44544
	v_add_f32_dpp v152, v152, v152 row_mirror row_mask:0xf bank_mask:0xf bound_ctrl:1
	v_pk_fma_f32 v[68:69], v[88:89], v[152:153], v[154:155] op_sel_hi:[1,0,1]
	v_pk_fma_f32 v[70:71], v[90:91], v[152:153], v[156:157] op_sel_hi:[1,0,1]
	ds_read_b128 v[128:131], v198 offset:45312
	s_waitcnt lgkmcnt(5)
	v_pk_mul_f32 v[144:145], v[68:69], v[100:101] op_sel_hi:[0,1]
	v_pk_fma_f32 v[144:145], v[68:69], v[102:103], v[144:145] op_sel:[1,0,0] op_sel_hi:[1,1,1]
	v_pk_fma_f32 v[144:145], v[70:71], v[104:105], v[144:145] op_sel_hi:[0,1,1]
	v_pk_fma_f32 v[144:145], v[70:71], v[106:107], v[144:145] op_sel:[1,0,0] op_sel_hi:[1,1,1]
	v_pk_mul_f32 v[154:155], v[112:113], v[140:141] op_sel_hi:[1,0]
	v_pk_mul_f32 v[156:157], v[114:115], v[140:141] op_sel_hi:[1,0]
	v_add_f32_dpp v152, v144, v144 quad_perm:[1,0,3,2] row_mask:0xf bank_mask:0xf bound_ctrl:1
	v_pk_fma_f32 v[154:155], v[68:69], v[96:97], v[154:155]
	v_pk_fma_f32 v[156:157], v[70:71], v[98:99], v[156:157]
	v_add_f32_dpp v152, v152, v152 quad_perm:[2,3,0,1] row_mask:0xf bank_mask:0xf bound_ctrl:1
	v_add_f32_dpp v158, v147, v147 row_ror:8 row_mask:0xf bank_mask:0xf
	v_add_f32_dpp v159, v149, v149 row_ror:8 row_mask:0xf bank_mask:0xf
	v_add_f32_dpp v152, v152, v152 row_half_mirror row_mask:0xf bank_mask:0xf bound_ctrl:1
	v_add_f32_dpp v158, v151, v151 row_ror:8 row_mask:0xf bank_mask:0xc
	v_add_f32_dpp v159, v145, v145 row_ror:8 row_mask:0xf bank_mask:0xc
	v_add_f32_dpp v152, v152, v152 row_mirror row_mask:0xf bank_mask:0xf bound_ctrl:1
	v_pk_fma_f32 v[72:73], v[108:109], v[152:153], v[154:155] op_sel_hi:[1,0,1]
	v_pk_fma_f32 v[74:75], v[110:111], v[152:153], v[156:157] op_sel_hi:[1,0,1]
	ds_read_b128 v[80:83], v162 offset:46336
	ds_read_b128 v[84:87], v163 offset:46336
	v_add_f32_dpp v160, v158, v158 row_half_mirror row_mask:0xf bank_mask:0xf
	v_add_f32_dpp v160, v159, v159 row_half_mirror row_mask:0xf bank_mask:0xa
	ds_read_b128 v[92:95], v198 offset:47104
	ds_read_b128 v[76:79], v198 offset:46080
	v_add_f32_dpp v160, v160, v160 quad_perm:[1,0,3,2] row_mask:0xf bank_mask:0xf bound_ctrl:1
	ds_read_b128 v[88:91], v198 offset:46848
	s_nop 0
	v_add_f32_dpp v160, v160, v160 quad_perm:[2,3,0,1] row_mask:0xf bank_mask:0xf bound_ctrl:1
	global_store_dword v161, v160, s[34:35]
	v_add_u32_e32 v161, 0xb000, v161
	s_waitcnt lgkmcnt(5)
	v_pk_mul_f32 v[146:147], v[72:73], v[120:121] op_sel_hi:[0,1]
	v_pk_fma_f32 v[146:147], v[72:73], v[122:123], v[146:147] op_sel:[1,0,0] op_sel_hi:[1,1,1]
	v_pk_fma_f32 v[146:147], v[74:75], v[124:125], v[146:147] op_sel_hi:[0,1,1]
	v_pk_fma_f32 v[146:147], v[74:75], v[126:127], v[146:147] op_sel:[1,0,0] op_sel_hi:[1,1,1]
	v_pk_mul_f32 v[154:155], v[132:133], v[140:141] op_sel:[0,1] op_sel_hi:[1,1]
	v_pk_mul_f32 v[156:157], v[134:135], v[140:141] op_sel:[0,1] op_sel_hi:[1,1]
	v_add_f32_dpp v152, v146, v146 quad_perm:[1,0,3,2] row_mask:0xf bank_mask:0xf bound_ctrl:1
	v_pk_fma_f32 v[154:155], v[72:73], v[116:117], v[154:155]
	v_pk_fma_f32 v[156:157], v[74:75], v[118:119], v[156:157]
	v_add_f32_dpp v152, v152, v152 quad_perm:[2,3,0,1] row_mask:0xf bank_mask:0xf bound_ctrl:1
	ds_read_b128 v[100:103], v162 offset:47872
	ds_read_b128 v[104:107], v163 offset:47872
	v_add_f32_dpp v152, v152, v152 row_half_mirror row_mask:0xf bank_mask:0xf bound_ctrl:1
	ds_read_b128 v[112:115], v198 offset:48640
	ds_read_b128 v[96:99], v198 offset:47616
	v_add_f32_dpp v152, v152, v152 row_mirror row_mask:0xf bank_mask:0xf bound_ctrl:1
	v_pk_fma_f32 v[68:69], v[128:129], v[152:153], v[154:155] op_sel_hi:[1,0,1]
	v_pk_fma_f32 v[70:71], v[130:131], v[152:153], v[156:157] op_sel_hi:[1,0,1]
	ds_read_b128 v[108:111], v198 offset:48384
	s_waitcnt lgkmcnt(5)
	v_pk_mul_f32 v[148:149], v[68:69], v[80:81] op_sel_hi:[0,1]
	v_pk_fma_f32 v[148:149], v[68:69], v[82:83], v[148:149] op_sel:[1,0,0] op_sel_hi:[1,1,1]
	v_pk_fma_f32 v[148:149], v[70:71], v[84:85], v[148:149] op_sel_hi:[0,1,1]
	v_pk_fma_f32 v[148:149], v[70:71], v[86:87], v[148:149] op_sel:[1,0,0] op_sel_hi:[1,1,1]
	v_pk_mul_f32 v[154:155], v[92:93], v[142:143] op_sel_hi:[1,0]
	v_pk_mul_f32 v[156:157], v[94:95], v[142:143] op_sel_hi:[1,0]
	v_add_f32_dpp v152, v148, v148 quad_perm:[1,0,3,2] row_mask:0xf bank_mask:0xf bound_ctrl:1
	v_pk_fma_f32 v[154:155], v[68:69], v[76:77], v[154:155]
	v_pk_fma_f32 v[156:157], v[70:71], v[78:79], v[156:157]
	v_add_f32_dpp v152, v152, v152 quad_perm:[2,3,0,1] row_mask:0xf bank_mask:0xf bound_ctrl:1
	s_nop 0
	s_nop 0
	v_add_f32_dpp v152, v152, v152 row_half_mirror row_mask:0xf bank_mask:0xf bound_ctrl:1
	s_nop 0
	s_nop 0
	v_add_f32_dpp v152, v152, v152 row_mirror row_mask:0xf bank_mask:0xf bound_ctrl:1
	v_pk_fma_f32 v[72:73], v[88:89], v[152:153], v[154:155] op_sel_hi:[1,0,1]
	v_pk_fma_f32 v[74:75], v[90:91], v[152:153], v[156:157] op_sel_hi:[1,0,1]
	s_waitcnt lgkmcnt(0)
	v_pk_mul_f32 v[150:151], v[72:73], v[100:101] op_sel_hi:[0,1]
	v_pk_fma_f32 v[150:151], v[72:73], v[102:103], v[150:151] op_sel:[1,0,0] op_sel_hi:[1,1,1]
	v_pk_fma_f32 v[150:151], v[74:75], v[104:105], v[150:151] op_sel_hi:[0,1,1]
	v_pk_fma_f32 v[150:151], v[74:75], v[106:107], v[150:151] op_sel:[1,0,0] op_sel_hi:[1,1,1]
	v_pk_mul_f32 v[154:155], v[112:113], v[142:143] op_sel:[0,1] op_sel_hi:[1,1]
	v_pk_mul_f32 v[156:157], v[114:115], v[142:143] op_sel:[0,1] op_sel_hi:[1,1]
	v_add_f32_dpp v152, v150, v150 quad_perm:[1,0,3,2] row_mask:0xf bank_mask:0xf bound_ctrl:1
	v_pk_fma_f32 v[154:155], v[72:73], v[96:97], v[154:155]
	v_pk_fma_f32 v[156:157], v[74:75], v[98:99], v[156:157]
	v_add_f32_dpp v152, v152, v152 quad_perm:[2,3,0,1] row_mask:0xf bank_mask:0xf bound_ctrl:1
	s_nop 0
	s_nop 0
	v_add_f32_dpp v152, v152, v152 row_half_mirror row_mask:0xf bank_mask:0xf bound_ctrl:1
	s_nop 0
	s_nop 0
	v_add_f32_dpp v152, v152, v152 row_mirror row_mask:0xf bank_mask:0xf bound_ctrl:1
	v_pk_fma_f32 v[68:69], v[108:109], v[152:153], v[154:155] op_sel_hi:[1,0,1]
	v_pk_fma_f32 v[70:71], v[110:111], v[152:153], v[156:157] op_sel_hi:[1,0,1]
	s_branch .LBB0_891

; #define LAS __attribute__((address_space(3)))
; __device__ __forceinline__ void rwkv_scan(Frame& F, int wg, unsigned* shw, unsigned wait_target, int wait_blk) {
;     ...
;             const LAS float* rb = buf + ((blk & 1) * RW_TB) * RW_REC + 4 * j;
;             const LAS float* rv_ = buf + ((blk & 1) * RW_TB) * RW_REC + 320 + (4 * F.wave + rg) * 4;
;     ...
;             RwOps R[4];
;             RW_LD(R[0], 0); RW_LD(R[1], 1); RW_LD(R[2], 2);
;             for (int s4 = 0; s4 < RW_TB; s4 += 4) {
;                 float pz[4], u[4];
; #pragma unroll
;                 for (int q = 0; q < 4; ++q) {
;                     RW_LD(R[(q + 3) & 3], s4 + q + 3);
;                     const RwOps& cur = R[q];
;                     const f32x2 slo = {st.x, st.y}, shi = {st.z, st.w};
;                     f32x2 ma = slo * (f32x2){cur.a.x, cur.a.y}; ma = __builtin_elementwise_fma(shi, (f32x2){cur.a.z, cur.a.w}, ma);
;                     f32x2 mz = slo * (f32x2){cur.wr.x, cur.wr.y}; mz = __builtin_elementwise_fma(shi, (f32x2){cur.wr.z, cur.wr.w}, mz);
;                     float psa = ma.x + ma.y; pz[q] = mz.x + mz.y;
;                     const f32x2 vb = {cur.vs.x, cur.vs.x};
;                     f32x2 tlo = (f32x2){cur.k.x, cur.k.y} * vb, thi = (f32x2){cur.k.z, cur.k.w} * vb;
;                     tlo = __builtin_elementwise_fma(slo, (f32x2){cur.w.x, cur.w.y}, tlo); thi = __builtin_elementwise_fma(shi, (f32x2){cur.w.z, cur.w.w}, thi);
;                     psa = red16(psa);
;                     const f32x2 pb = {psa, psa};
;                     tlo = __builtin_elementwise_fma((f32x2){cur.b.x, cur.b.y}, pb, tlo); thi = __builtin_elementwise_fma((f32x2){cur.b.z, cur.b.w}, pb, thi);
;                     st = (f32x4){tlo.x, tlo.y, thi.x, thi.y};
;                     u[q] = psa * cur.vs.z + cur.vs.y;
;                 }
;                 const float qa = (odd1 ? pz[1] : pz[0]) + dppf<0xB1>(odd1 ? pz[0] : pz[1]);
;                 const float qb = (odd1 ? pz[3] : pz[2]) + dppf<0xB1>(odd1 ? pz[2] : pz[3]);
;                 float r = (odd2 ? qb : qa) + dppf<0x4E>(odd2 ? qa : qb);
;                 r += dppf<0x124>(r); r += dppf<0x128>(r);
;                 const float us = odd2 ? (odd1 ? u[3] : u[2]) : (odd1 ? u[1] : u[0]);
;                 if (j < 4) { const int t = blk * RW_TB + s4 + j; ((float*)(Ub + (size_t)t * (PWP * 2) + URR * 2))[h * 64 + row] = r + us; }
.LBB0_891:
	s_mov_b64 s[50:51], -1
	s_and_b64 vcc, exec, s[26:27]
	s_waitcnt lgkmcnt(0)
	s_barrier
	s_cbranch_vccz .LBB0_909
	s_mul_i32 s50, s59, 0x58000
	s_add_i32 s50, s50, 0x4d000
	v_and_b32_e32 v163, 8, v194
	v_lshlrev_b32_e32 v163, 1, v163
	v_add_u32_e32 v162, v198, v202
	v_add_u32_e32 v162, v162, v163
	v_xor_b32_e32 v163, 16, v162
	ds_read_b128 v[80:83], v162 offset:256
	ds_read_b128 v[84:87], v163 offset:256
	ds_read_b128 v[92:95], v202 offset:1024
	ds_read_b128 v[136:139], v206 offset:0
	ds_read_b128 v[76:79], v202 offset:0
	ds_read_b128 v[88:91], v202 offset:768
	ds_read_b128 v[100:103], v162 offset:1792
	ds_read_b128 v[104:107], v163 offset:1792
	ds_read_b128 v[112:115], v202 offset:2560
	ds_read_b128 v[96:99], v202 offset:1536
	ds_read_b128 v[108:111], v202 offset:2304
	v_lshrrev_b32_e32 v161, 2, v194
	v_mul_u32_u24_e32 v161, 0x2c00, v161
	v_lshl_add_u32 v161, v186, 2, v161
	v_add_u32_e32 v161, s50, v161
	s_waitcnt lgkmcnt(5)
	v_pk_mul_f32 v[144:145], v[68:69], v[80:81] op_sel_hi:[0,1]
	v_pk_fma_f32 v[144:145], v[68:69], v[82:83], v[144:145] op_sel:[1,0,0] op_sel_hi:[1,1,1]
	v_pk_fma_f32 v[144:145], v[70:71], v[84:85], v[144:145] op_sel_hi:[0,1,1]
	v_pk_fma_f32 v[144:145], v[70:71], v[86:87], v[144:145] op_sel:[1,0,0] op_sel_hi:[1,1,1]
	v_pk_mul_f32 v[154:155], v[92:93], v[136:137] op_sel_hi:[1,0]
	v_pk_mul_f32 v[156:157], v[94:95], v[136:137] op_sel_hi:[1,0]
	v_add_f32_dpp v152, v144, v144 quad_perm:[1,0,3,2] row_mask:0xf bank_mask:0xf bound_ctrl:1
	v_pk_fma_f32 v[154:155], v[68:69], v[76:77], v[154:155]
	v_pk_fma_f32 v[156:157], v[70:71], v[78:79], v[156:157]
	v_add_f32_dpp v152, v152, v152 quad_perm:[2,3,0,1] row_mask:0xf bank_mask:0xf bound_ctrl:1
	v_add_f32_dpp v158, v147, v147 row_ror:8 row_mask:0xf bank_mask:0xf
	v_add_f32_dpp v159, v149, v149 row_ror:8 row_mask:0xf bank_mask:0xf
	v_add_f32_dpp v152, v152, v152 row_half_mirror row_mask:0xf bank_mask:0xf bound_ctrl:1
	v_add_f32_dpp v158, v151, v151 row_ror:8 row_mask:0xf bank_mask:0xc
	v_add_f32_dpp v159, v145, v145 row_ror:8 row_mask:0xf bank_mask:0xc
	v_add_f32_dpp v152, v152, v152 row_mirror row_mask:0xf bank_mask:0xf bound_ctrl:1
	v_pk_fma_f32 v[72:73], v[88:89], v[152:153], v[154:155] op_sel_hi:[1,0,1]
	v_pk_fma_f32 v[74:75], v[90:91], v[152:153], v[156:157] op_sel_hi:[1,0,1]
	ds_read_b128 v[120:123], v162 offset:3328
	ds_read_b128 v[124:127], v163 offset:3328
	v_add_f32_dpp v160, v158, v158 row_half_mirror row_mask:0xf bank_mask:0xf
	v_add_f32_dpp v160, v159, v159 row_half_mirror row_mask:0xf bank_mask:0xa
	ds_read_b128 v[132:135], v202 offset:4096
	ds_read_b128 v[116:119], v202 offset:3072
	v_add_f32_dpp v160, v160, v160 quad_perm:[1,0,3,2] row_mask:0xf bank_mask:0xf bound_ctrl:1
	ds_read_b128 v[128:131], v202 offset:3840
	s_nop 0
	v_add_f32_dpp v160, v160, v160 quad_perm:[2,3,0,1] row_mask:0xf bank_mask:0xf bound_ctrl:1
	global_store_dword v161, v160, s[34:35]
	v_add_u32_e32 v161, 0xb000, v161
	s_waitcnt lgkmcnt(5)
	v_pk_mul_f32 v[146:147], v[72:73], v[100:101] op_sel_hi:[0,1]
	v_pk_fma_f32 v[146:147], v[72:73], v[102:103], v[146:147] op_sel:[1,0,0] op_sel_hi:[1,1,1]
	v_pk_fma_f32 v[146:147], v[74:75], v[104:105], v[146:147] op_sel_hi:[0,1,1]
	v_pk_fma_f32 v[146:147], v[74:75], v[106:107], v[146:147] op_sel:[1,0,0] op_sel_hi:[1,1,1]
	v_pk_mul_f32 v[154:155], v[112:113], v[136:137] op_sel:[0,1] op_sel_hi:[1,1]
	v_pk_mul_f32 v[156:157], v[114:115], v[136:137] op_sel:[0,1] op_sel_hi:[1,1]
	v_add_f32_dpp v152, v146, v146 quad_perm:[1,0,3,2] row_mask:0xf bank_mask:0xf bound_ctrl:1
	v_pk_fma_f32 v[154:155], v[72:73], v[96:97], v[154:155]
	v_pk_fma_f32 v[156:157], v[74:75], v[98:99], v[156:157]
	v_add_f32_dpp v152, v152, v152 quad_perm:[2,3,0,1] row_mask:0xf bank_mask:0xf bound_ctrl:1
	ds_read_b128 v[80:83], v162 offset:4864
	ds_read_b128 v[84:87], v163 offset:4864
	v_add_f32_dpp v152, v152, v152 row_half_mirror row_mask:0xf bank_mask:0xf bound_ctrl:1
	ds_read_b128 v[92:95], v202 offset:5632
	ds_read_b128 v[76:79], v202 offset:4608
	v_add_f32_dpp v152, v152, v152 row_mirror row_mask:0xf bank_mask:0xf bound_ctrl:1
	v_pk_fma_f32 v[68:69], v[108:109], v[152:153], v[154:155] op_sel_hi:[1,0,1]
	v_pk_fma_f32 v[70:71], v[110:111], v[152:153], v[156:157] op_sel_hi:[1,0,1]
	ds_read_b128 v[88:91], v202 offset:5376
	s_waitcnt lgkmcnt(5)
	v_pk_mul_f32 v[148:149], v[68:69], v[120:121] op_sel_hi:[0,1]
	v_pk_fma_f32 v[148:149], v[68:69], v[122:123], v[148:149] op_sel:[1,0,0] op_sel_hi:[1,1,1]
	v_pk_fma_f32 v[148:149], v[70:71], v[124:125], v[148:149] op_sel_hi:[0,1,1]
	v_pk_fma_f32 v[148:149], v[70:71], v[126:127], v[148:149] op_sel:[1,0,0] op_sel_hi:[1,1,1]
	v_pk_mul_f32 v[154:155], v[132:133], v[138:139] op_sel_hi:[1,0]
	v_pk_mul_f32 v[156:157], v[134:135], v[138:139] op_sel_hi:[1,0]
	v_add_f32_dpp v152, v148, v148 quad_perm:[1,0,3,2] row_mask:0xf bank_mask:0xf bound_ctrl:1
	v_pk_fma_f32 v[154:155], v[68:69], v[116:117], v[154:155]
	v_pk_fma_f32 v[156:157], v[70:71], v[118:119], v[156:157]
	v_add_f32_dpp v152, v152, v152 quad_perm:[2,3,0,1] row_mask:0xf bank_mask:0xf bound_ctrl:1
	ds_read_b128 v[100:103], v162 offset:6400
	ds_read_b128 v[104:107], v163 offset:6400
	v_add_f32_dpp v152, v152, v152 row_half_mirror row_mask:0xf bank_mask:0xf bound_ctrl:1
	ds_read_b128 v[112:115], v202 offset:7168
	ds_read_b128 v[140:143], v206 offset:6144
	v_add_f32_dpp v152, v152, v152 row_mirror row_mask:0xf bank_mask:0xf bound_ctrl:1
	v_pk_fma_f32 v[72:73], v[128:129], v[152:153], v[154:155] op_sel_hi:[1,0,1]
	v_pk_fma_f32 v[74:75], v[130:131], v[152:153], v[156:157] op_sel_hi:[1,0,1]
	ds_read_b128 v[96:99], v202 offset:6144
	ds_read_b128 v[108:111], v202 offset:6912
	s_waitcnt lgkmcnt(6)
; __device__ __forceinline__ void rwkv_scan(Frame& F, int wg, unsigned* shw, unsigned wait_target, int wait_blk) {
;     ...
;             for (int s4 = 0; s4 < RW_TB; s4 += 4) {
;                 float pz[4], u[4];
; #pragma unroll
;                 for (int q = 0; q < 4; ++q) {
;                     RW_LD(R[(q + 3) & 3], s4 + q + 3);
;                     const RwOps& cur = R[q];
;                     const f32x2 slo = {st.x, st.y}, shi = {st.z, st.w};
;                     f32x2 ma = slo * (f32x2){cur.a.x, cur.a.y}; ma = __builtin_elementwise_fma(shi, (f32x2){cur.a.z, cur.a.w}, ma);
;                     f32x2 mz = slo * (f32x2){cur.wr.x, cur.wr.y}; mz = __builtin_elementwise_fma(shi, (f32x2){cur.wr.z, cur.wr.w}, mz);
;                     float psa = ma.x + ma.y; pz[q] = mz.x + mz.y;
;                     const f32x2 vb = {cur.vs.x, cur.vs.x};
;                     f32x2 tlo = (f32x2){cur.k.x, cur.k.y} * vb, thi = (f32x2){cur.k.z, cur.k.w} * vb;
;                     tlo = __builtin_elementwise_fma(slo, (f32x2){cur.w.x, cur.w.y}, tlo); thi = __builtin_elementwise_fma(shi, (f32x2){cur.w.z, cur.w.w}, thi);
;                     psa = red16(psa);
;                     const f32x2 pb = {psa, psa};
;                     tlo = __builtin_elementwise_fma((f32x2){cur.b.x, cur.b.y}, pb, tlo); thi = __builtin_elementwise_fma((f32x2){cur.b.z, cur.b.w}, pb, thi);
;                     st = (f32x4){tlo.x, tlo.y, thi.x, thi.y};
;                     u[q] = psa * cur.vs.z + cur.vs.y;
;                 }
;                 const float qa = (odd1 ? pz[1] : pz[0]) + dppf<0xB1>(odd1 ? pz[0] : pz[1]);
;                 const float qb = (odd1 ? pz[3] : pz[2]) + dppf<0xB1>(odd1 ? pz[2] : pz[3]);
;                 float r = (odd2 ? qb : qa) + dppf<0x4E>(odd2 ? qa : qb);
;                 r += dppf<0x124>(r); r += dppf<0x128>(r);
;                 const float us = odd2 ? (odd1 ? u[3] : u[2]) : (odd1 ? u[1] : u[0]);
;                 if (j < 4) { const int t = blk * RW_TB + s4 + j; ((float*)(Ub + (size_t)t * (PWP * 2) + URR * 2))[h * 64 + row] = r + us; }
	v_pk_mul_f32 v[150:151], v[72:73], v[80:81] op_sel_hi:[0,1]
	v_pk_fma_f32 v[150:151], v[72:73], v[82:83], v[150:151] op_sel:[1,0,0] op_sel_hi:[1,1,1]
	v_pk_fma_f32 v[150:151], v[74:75], v[84:85], v[150:151] op_sel_hi:[0,1,1]
	v_pk_fma_f32 v[150:151], v[74:75], v[86:87], v[150:151] op_sel:[1,0,0] op_sel_hi:[1,1,1]
	v_pk_mul_f32 v[154:155], v[92:93], v[138:139] op_sel:[0,1] op_sel_hi:[1,1]
	v_pk_mul_f32 v[156:157], v[94:95], v[138:139] op_sel:[0,1] op_sel_hi:[1,1]
	v_add_f32_dpp v152, v150, v150 quad_perm:[1,0,3,2] row_mask:0xf bank_mask:0xf bound_ctrl:1
	v_pk_fma_f32 v[154:155], v[72:73], v[76:77], v[154:155]
	v_pk_fma_f32 v[156:157], v[74:75], v[78:79], v[156:157]
	v_add_f32_dpp v152, v152, v152 quad_perm:[2,3,0,1] row_mask:0xf bank_mask:0xf bound_ctrl:1
	ds_read_b128 v[120:123], v162 offset:7936
	ds_read_b128 v[124:127], v163 offset:7936
	v_add_f32_dpp v152, v152, v152 row_half_mirror row_mask:0xf bank_mask:0xf bound_ctrl:1
	ds_read_b128 v[132:135], v202 offset:8704
	ds_read_b128 v[116:119], v202 offset:7680
	v_add_f32_dpp v152, v152, v152 row_mirror row_mask:0xf bank_mask:0xf bound_ctrl:1
	v_pk_fma_f32 v[68:69], v[88:89], v[152:153], v[154:155] op_sel_hi:[1,0,1]
	v_pk_fma_f32 v[70:71], v[90:91], v[152:153], v[156:157] op_sel_hi:[1,0,1]
	ds_read_b128 v[128:131], v202 offset:8448
	s_waitcnt lgkmcnt(5)
	v_pk_mul_f32 v[144:145], v[68:69], v[100:101] op_sel_hi:[0,1]
	v_pk_fma_f32 v[144:145], v[68:69], v[102:103], v[144:145] op_sel:[1,0,0] op_sel_hi:[1,1,1]
	v_pk_fma_f32 v[144:145], v[70:71], v[104:105], v[144:145] op_sel_hi:[0,1,1]
	v_pk_fma_f32 v[144:145], v[70:71], v[106:107], v[144:145] op_sel:[1,0,0] op_sel_hi:[1,1,1]
	v_pk_mul_f32 v[154:155], v[112:113], v[140:141] op_sel_hi:[1,0]
	v_pk_mul_f32 v[156:157], v[114:115], v[140:141] op_sel_hi:[1,0]
	v_add_f32_dpp v152, v144, v144 quad_perm:[1,0,3,2] row_mask:0xf bank_mask:0xf bound_ctrl:1
	v_pk_fma_f32 v[154:155], v[68:69], v[96:97], v[154:155]
	v_pk_fma_f32 v[156:157], v[70:71], v[98:99], v[156:157]
	v_add_f32_dpp v152, v152, v152 quad_perm:[2,3,0,1] row_mask:0xf bank_mask:0xf bound_ctrl:1
	v_add_f32_dpp v158, v147, v147 row_ror:8 row_mask:0xf bank_mask:0xf
	v_add_f32_dpp v159, v149, v149 row_ror:8 row_mask:0xf bank_mask:0xf
	v_add_f32_dpp v152, v152, v152 row_half_mirror row_mask:0xf bank_mask:0xf bound_ctrl:1
	v_add_f32_dpp v158, v151, v151 row_ror:8 row_mask:0xf bank_mask:0xc
	v_add_f32_dpp v159, v145, v145 row_ror:8 row_mask:0xf bank_mask:0xc
	v_add_f32_dpp v152, v152, v152 row_mirror row_mask:0xf bank_mask:0xf bound_ctrl:1
	v_pk_fma_f32 v[72:73], v[108:109], v[152:153], v[154:155] op_sel_hi:[1,0,1]
	v_pk_fma_f32 v[74:75], v[110:111], v[152:153], v[156:157] op_sel_hi:[1,0,1]
	ds_read_b128 v[80:83], v162 offset:9472
	ds_read_b128 v[84:87], v163 offset:9472
	v_add_f32_dpp v160, v158, v158 row_half_mirror row_mask:0xf bank_mask:0xf
	v_add_f32_dpp v160, v159, v159 row_half_mirror row_mask:0xf bank_mask:0xa
	ds_read_b128 v[92:95], v202 offset:10240
	ds_read_b128 v[76:79], v202 offset:9216
	v_add_f32_dpp v160, v160, v160 quad_perm:[1,0,3,2] row_mask:0xf bank_mask:0xf bound_ctrl:1
	ds_read_b128 v[88:91], v202 offset:9984
	s_nop 0
	v_add_f32_dpp v160, v160, v160 quad_perm:[2,3,0,1] row_mask:0xf bank_mask:0xf bound_ctrl:1
	global_store_dword v161, v160, s[34:35]
	v_add_u32_e32 v161, 0xb000, v161
	s_waitcnt lgkmcnt(5)
	v_pk_mul_f32 v[146:147], v[72:73], v[120:121] op_sel_hi:[0,1]
	v_pk_fma_f32 v[146:147], v[72:73], v[122:123], v[146:147] op_sel:[1,0,0] op_sel_hi:[1,1,1]
	v_pk_fma_f32 v[146:147], v[74:75], v[124:125], v[146:147] op_sel_hi:[0,1,1]
	v_pk_fma_f32 v[146:147], v[74:75], v[126:127], v[146:147] op_sel:[1,0,0] op_sel_hi:[1,1,1]
	v_pk_mul_f32 v[154:155], v[132:133], v[140:141] op_sel:[0,1] op_sel_hi:[1,1]
	v_pk_mul_f32 v[156:157], v[134:135], v[140:141] op_sel:[0,1] op_sel_hi:[1,1]
	v_add_f32_dpp v152, v146, v146 quad_perm:[1,0,3,2] row_mask:0xf bank_mask:0xf bound_ctrl:1
	v_pk_fma_f32 v[154:155], v[72:73], v[116:117], v[154:155]
	v_pk_fma_f32 v[156:157], v[74:75], v[118:119], v[156:157]
	v_add_f32_dpp v152, v152, v152 quad_perm:[2,3,0,1] row_mask:0xf bank_mask:0xf bound_ctrl:1
	ds_read_b128 v[100:103], v162 offset:11008
	ds_read_b128 v[104:107], v163 offset:11008
	v_add_f32_dpp v152, v152, v152 row_half_mirror row_mask:0xf bank_mask:0xf bound_ctrl:1
	ds_read_b128 v[112:115], v202 offset:11776
	ds_read_b128 v[96:99], v202 offset:10752
	v_add_f32_dpp v152, v152, v152 row_mirror row_mask:0xf bank_mask:0xf bound_ctrl:1
	v_pk_fma_f32 v[68:69], v[128:129], v[152:153], v[154:155] op_sel_hi:[1,0,1]
	v_pk_fma_f32 v[70:71], v[130:131], v[152:153], v[156:157] op_sel_hi:[1,0,1]
	ds_read_b128 v[108:111], v202 offset:11520
	s_waitcnt lgkmcnt(5)
	v_pk_mul_f32 v[148:149], v[68:69], v[80:81] op_sel_hi:[0,1]
	v_pk_fma_f32 v[148:149], v[68:69], v[82:83], v[148:149] op_sel:[1,0,0] op_sel_hi:[1,1,1]
	v_pk_fma_f32 v[148:149], v[70:71], v[84:85], v[148:149] op_sel_hi:[0,1,1]
	v_pk_fma_f32 v[148:149], v[70:71], v[86:87], v[148:149] op_sel:[1,0,0] op_sel_hi:[1,1,1]
	v_pk_mul_f32 v[154:155], v[92:93], v[142:143] op_sel_hi:[1,0]
	v_pk_mul_f32 v[156:157], v[94:95], v[142:143] op_sel_hi:[1,0]
	v_add_f32_dpp v152, v148, v148 quad_perm:[1,0,3,2] row_mask:0xf bank_mask:0xf bound_ctrl:1
	v_pk_fma_f32 v[154:155], v[68:69], v[76:77], v[154:155]
	v_pk_fma_f32 v[156:157], v[70:71], v[78:79], v[156:157]
	v_add_f32_dpp v152, v152, v152 quad_perm:[2,3,0,1] row_mask:0xf bank_mask:0xf bound_ctrl:1
	ds_read_b128 v[120:123], v162 offset:12544
	ds_read_b128 v[124:127], v163 offset:12544
	v_add_f32_dpp v152, v152, v152 row_half_mirror row_mask:0xf bank_mask:0xf bound_ctrl:1
	ds_read_b128 v[132:135], v202 offset:13312
	ds_read_b128 v[136:139], v206 offset:12288
	v_add_f32_dpp v152, v152, v152 row_mirror row_mask:0xf bank_mask:0xf bound_ctrl:1
	v_pk_fma_f32 v[72:73], v[88:89], v[152:153], v[154:155] op_sel_hi:[1,0,1]
	v_pk_fma_f32 v[74:75], v[90:91], v[152:153], v[156:157] op_sel_hi:[1,0,1]
	ds_read_b128 v[116:119], v202 offset:12288
	ds_read_b128 v[128:131], v202 offset:13056
	s_waitcnt lgkmcnt(6)
; __device__ __forceinline__ void rwkv_scan(Frame& F, int wg, unsigned* shw, unsigned wait_target, int wait_blk) {
;     ...
;             for (int s4 = 0; s4 < RW_TB; s4 += 4) {
;                 float pz[4], u[4];
; #pragma unroll
;                 for (int q = 0; q < 4; ++q) {
;                     RW_LD(R[(q + 3) & 3], s4 + q + 3);
;                     const RwOps& cur = R[q];
;                     const f32x2 slo = {st.x, st.y}, shi = {st.z, st.w};
;                     f32x2 ma = slo * (f32x2){cur.a.x, cur.a.y}; ma = __builtin_elementwise_fma(shi, (f32x2){cur.a.z, cur.a.w}, ma);
;                     f32x2 mz = slo * (f32x2){cur.wr.x, cur.wr.y}; mz = __builtin_elementwise_fma(shi, (f32x2){cur.wr.z, cur.wr.w}, mz);
;                     float psa = ma.x + ma.y; pz[q] = mz.x + mz.y;
;                     const f32x2 vb = {cur.vs.x, cur.vs.x};
;                     f32x2 tlo = (f32x2){cur.k.x, cur.k.y} * vb, thi = (f32x2){cur.k.z, cur.k.w} * vb;
;                     tlo = __builtin_elementwise_fma(slo, (f32x2){cur.w.x, cur.w.y}, tlo); thi = __builtin_elementwise_fma(shi, (f32x2){cur.w.z, cur.w.w}, thi);
;                     psa = red16(psa);
;                     const f32x2 pb = {psa, psa};
;                     tlo = __builtin_elementwise_fma((f32x2){cur.b.x, cur.b.y}, pb, tlo); thi = __builtin_elementwise_fma((f32x2){cur.b.z, cur.b.w}, pb, thi);
;                     st = (f32x4){tlo.x, tlo.y, thi.x, thi.y};
;                     u[q] = psa * cur.vs.z + cur.vs.y;
;                 }
;                 const float qa = (odd1 ? pz[1] : pz[0]) + dppf<0xB1>(odd1 ? pz[0] : pz[1]);
;                 const float qb = (odd1 ? pz[3] : pz[2]) + dppf<0xB1>(odd1 ? pz[2] : pz[3]);
;                 float r = (odd2 ? qb : qa) + dppf<0x4E>(odd2 ? qa : qb);
;                 r += dppf<0x124>(r); r += dppf<0x128>(r);
;                 const float us = odd2 ? (odd1 ? u[3] : u[2]) : (odd1 ? u[1] : u[0]);
;                 if (j < 4) { const int t = blk * RW_TB + s4 + j; ((float*)(Ub + (size_t)t * (PWP * 2) + URR * 2))[h * 64 + row] = r + us; }
	v_pk_mul_f32 v[150:151], v[72:73], v[100:101] op_sel_hi:[0,1]
	v_pk_fma_f32 v[150:151], v[72:73], v[102:103], v[150:151] op_sel:[1,0,0] op_sel_hi:[1,1,1]
	v_pk_fma_f32 v[150:151], v[74:75], v[104:105], v[150:151] op_sel_hi:[0,1,1]
	v_pk_fma_f32 v[150:151], v[74:75], v[106:107], v[150:151] op_sel:[1,0,0] op_sel_hi:[1,1,1]
	v_pk_mul_f32 v[154:155], v[112:113], v[142:143] op_sel:[0,1] op_sel_hi:[1,1]
	v_pk_mul_f32 v[156:157], v[114:115], v[142:143] op_sel:[0,1] op_sel_hi:[1,1]
	v_add_f32_dpp v152, v150, v150 quad_perm:[1,0,3,2] row_mask:0xf bank_mask:0xf bound_ctrl:1
	v_pk_fma_f32 v[154:155], v[72:73], v[96:97], v[154:155]
	v_pk_fma_f32 v[156:157], v[74:75], v[98:99], v[156:157]
	v_add_f32_dpp v152, v152, v152 quad_perm:[2,3,0,1] row_mask:0xf bank_mask:0xf bound_ctrl:1
	ds_read_b128 v[80:83], v162 offset:14080
	ds_read_b128 v[84:87], v163 offset:14080
	v_add_f32_dpp v152, v152, v152 row_half_mirror row_mask:0xf bank_mask:0xf bound_ctrl:1
	ds_read_b128 v[92:95], v202 offset:14848
	ds_read_b128 v[76:79], v202 offset:13824
	v_add_f32_dpp v152, v152, v152 row_mirror row_mask:0xf bank_mask:0xf bound_ctrl:1
	v_pk_fma_f32 v[68:69], v[108:109], v[152:153], v[154:155] op_sel_hi:[1,0,1]
	v_pk_fma_f32 v[70:71], v[110:111], v[152:153], v[156:157] op_sel_hi:[1,0,1]
	ds_read_b128 v[88:91], v202 offset:14592
	s_waitcnt lgkmcnt(5)
	v_pk_mul_f32 v[144:145], v[68:69], v[120:121] op_sel_hi:[0,1]
	v_pk_fma_f32 v[144:145], v[68:69], v[122:123], v[144:145] op_sel:[1,0,0] op_sel_hi:[1,1,1]
	v_pk_fma_f32 v[144:145], v[70:71], v[124:125], v[144:145] op_sel_hi:[0,1,1]
	v_pk_fma_f32 v[144:145], v[70:71], v[126:127], v[144:145] op_sel:[1,0,0] op_sel_hi:[1,1,1]
	v_pk_mul_f32 v[154:155], v[132:133], v[136:137] op_sel_hi:[1,0]
	v_pk_mul_f32 v[156:157], v[134:135], v[136:137] op_sel_hi:[1,0]
	v_add_f32_dpp v152, v144, v144 quad_perm:[1,0,3,2] row_mask:0xf bank_mask:0xf bound_ctrl:1
	v_pk_fma_f32 v[154:155], v[68:69], v[116:117], v[154:155]
	v_pk_fma_f32 v[156:157], v[70:71], v[118:119], v[156:157]
	v_add_f32_dpp v152, v152, v152 quad_perm:[2,3,0,1] row_mask:0xf bank_mask:0xf bound_ctrl:1
	v_add_f32_dpp v158, v147, v147 row_ror:8 row_mask:0xf bank_mask:0xf
	v_add_f32_dpp v159, v149, v149 row_ror:8 row_mask:0xf bank_mask:0xf
	v_add_f32_dpp v152, v152, v152 row_half_mirror row_mask:0xf bank_mask:0xf bound_ctrl:1
	v_add_f32_dpp v158, v151, v151 row_ror:8 row_mask:0xf bank_mask:0xc
	v_add_f32_dpp v159, v145, v145 row_ror:8 row_mask:0xf bank_mask:0xc
	v_add_f32_dpp v152, v152, v152 row_mirror row_mask:0xf bank_mask:0xf bound_ctrl:1
	v_pk_fma_f32 v[72:73], v[128:129], v[152:153], v[154:155] op_sel_hi:[1,0,1]
	v_pk_fma_f32 v[74:75], v[130:131], v[152:153], v[156:157] op_sel_hi:[1,0,1]
	ds_read_b128 v[100:103], v162 offset:15616
	ds_read_b128 v[104:107], v163 offset:15616
	v_add_f32_dpp v160, v158, v158 row_half_mirror row_mask:0xf bank_mask:0xf
	v_add_f32_dpp v160, v159, v159 row_half_mirror row_mask:0xf bank_mask:0xa
	ds_read_b128 v[112:115], v202 offset:16384
	ds_read_b128 v[96:99], v202 offset:15360
	v_add_f32_dpp v160, v160, v160 quad_perm:[1,0,3,2] row_mask:0xf bank_mask:0xf bound_ctrl:1
	ds_read_b128 v[108:111], v202 offset:16128
	s_nop 0
	v_add_f32_dpp v160, v160, v160 quad_perm:[2,3,0,1] row_mask:0xf bank_mask:0xf bound_ctrl:1
	global_store_dword v161, v160, s[34:35]
	v_add_u32_e32 v161, 0xb000, v161
	s_waitcnt lgkmcnt(5)
	v_pk_mul_f32 v[146:147], v[72:73], v[80:81] op_sel_hi:[0,1]
	v_pk_fma_f32 v[146:147], v[72:73], v[82:83], v[146:147] op_sel:[1,0,0] op_sel_hi:[1,1,1]
	v_pk_fma_f32 v[146:147], v[74:75], v[84:85], v[146:147] op_sel_hi:[0,1,1]
	v_pk_fma_f32 v[146:147], v[74:75], v[86:87], v[146:147] op_sel:[1,0,0] op_sel_hi:[1,1,1]
	v_pk_mul_f32 v[154:155], v[92:93], v[136:137] op_sel:[0,1] op_sel_hi:[1,1]
	v_pk_mul_f32 v[156:157], v[94:95], v[136:137] op_sel:[0,1] op_sel_hi:[1,1]
	v_add_f32_dpp v152, v146, v146 quad_perm:[1,0,3,2] row_mask:0xf bank_mask:0xf bound_ctrl:1
	v_pk_fma_f32 v[154:155], v[72:73], v[76:77], v[154:155]
	v_pk_fma_f32 v[156:157], v[74:75], v[78:79], v[156:157]
	v_add_f32_dpp v152, v152, v152 quad_perm:[2,3,0,1] row_mask:0xf bank_mask:0xf bound_ctrl:1
	ds_read_b128 v[120:123], v162 offset:17152
	ds_read_b128 v[124:127], v163 offset:17152
	v_add_f32_dpp v152, v152, v152 row_half_mirror row_mask:0xf bank_mask:0xf bound_ctrl:1
	ds_read_b128 v[132:135], v202 offset:17920
	ds_read_b128 v[116:119], v202 offset:16896
	v_add_f32_dpp v152, v152, v152 row_mirror row_mask:0xf bank_mask:0xf bound_ctrl:1
	v_pk_fma_f32 v[68:69], v[88:89], v[152:153], v[154:155] op_sel_hi:[1,0,1]
	v_pk_fma_f32 v[70:71], v[90:91], v[152:153], v[156:157] op_sel_hi:[1,0,1]
	ds_read_b128 v[128:131], v202 offset:17664
	s_waitcnt lgkmcnt(5)
	v_pk_mul_f32 v[148:149], v[68:69], v[100:101] op_sel_hi:[0,1]
	v_pk_fma_f32 v[148:149], v[68:69], v[102:103], v[148:149] op_sel:[1,0,0] op_sel_hi:[1,1,1]
	v_pk_fma_f32 v[148:149], v[70:71], v[104:105], v[148:149] op_sel_hi:[0,1,1]
	v_pk_fma_f32 v[148:149], v[70:71], v[106:107], v[148:149] op_sel:[1,0,0] op_sel_hi:[1,1,1]
	v_pk_mul_f32 v[154:155], v[112:113], v[138:139] op_sel_hi:[1,0]
	v_pk_mul_f32 v[156:157], v[114:115], v[138:139] op_sel_hi:[1,0]
	v_add_f32_dpp v152, v148, v148 quad_perm:[1,0,3,2] row_mask:0xf bank_mask:0xf bound_ctrl:1
	v_pk_fma_f32 v[154:155], v[68:69], v[96:97], v[154:155]
	v_pk_fma_f32 v[156:157], v[70:71], v[98:99], v[156:157]
	v_add_f32_dpp v152, v152, v152 quad_perm:[2,3,0,1] row_mask:0xf bank_mask:0xf bound_ctrl:1
	ds_read_b128 v[80:83], v162 offset:18688
	ds_read_b128 v[84:87], v163 offset:18688
	v_add_f32_dpp v152, v152, v152 row_half_mirror row_mask:0xf bank_mask:0xf bound_ctrl:1
	ds_read_b128 v[92:95], v202 offset:19456
	ds_read_b128 v[140:143], v206 offset:18432
	v_add_f32_dpp v152, v152, v152 row_mirror row_mask:0xf bank_mask:0xf bound_ctrl:1
	v_pk_fma_f32 v[72:73], v[108:109], v[152:153], v[154:155] op_sel_hi:[1,0,1]
	v_pk_fma_f32 v[74:75], v[110:111], v[152:153], v[156:157] op_sel_hi:[1,0,1]
	ds_read_b128 v[76:79], v202 offset:18432
	ds_read_b128 v[88:91], v202 offset:19200
	s_waitcnt lgkmcnt(6)
; __device__ __forceinline__ void rwkv_scan(Frame& F, int wg, unsigned* shw, unsigned wait_target, int wait_blk) {
;     ...
;             for (int s4 = 0; s4 < RW_TB; s4 += 4) {
;                 float pz[4], u[4];
; #pragma unroll
;                 for (int q = 0; q < 4; ++q) {
;                     RW_LD(R[(q + 3) & 3], s4 + q + 3);
;                     const RwOps& cur = R[q];
;                     const f32x2 slo = {st.x, st.y}, shi = {st.z, st.w};
;                     f32x2 ma = slo * (f32x2){cur.a.x, cur.a.y}; ma = __builtin_elementwise_fma(shi, (f32x2){cur.a.z, cur.a.w}, ma);
;                     f32x2 mz = slo * (f32x2){cur.wr.x, cur.wr.y}; mz = __builtin_elementwise_fma(shi, (f32x2){cur.wr.z, cur.wr.w}, mz);
;                     float psa = ma.x + ma.y; pz[q] = mz.x + mz.y;
;                     const f32x2 vb = {cur.vs.x, cur.vs.x};
;                     f32x2 tlo = (f32x2){cur.k.x, cur.k.y} * vb, thi = (f32x2){cur.k.z, cur.k.w} * vb;
;                     tlo = __builtin_elementwise_fma(slo, (f32x2){cur.w.x, cur.w.y}, tlo); thi = __builtin_elementwise_fma(shi, (f32x2){cur.w.z, cur.w.w}, thi);
;                     psa = red16(psa);
;                     const f32x2 pb = {psa, psa};
;                     tlo = __builtin_elementwise_fma((f32x2){cur.b.x, cur.b.y}, pb, tlo); thi = __builtin_elementwise_fma((f32x2){cur.b.z, cur.b.w}, pb, thi);
;                     st = (f32x4){tlo.x, tlo.y, thi.x, thi.y};
;                     u[q] = psa * cur.vs.z + cur.vs.y;
;                 }
;                 const float qa = (odd1 ? pz[1] : pz[0]) + dppf<0xB1>(odd1 ? pz[0] : pz[1]);
;                 const float qb = (odd1 ? pz[3] : pz[2]) + dppf<0xB1>(odd1 ? pz[2] : pz[3]);
;                 float r = (odd2 ? qb : qa) + dppf<0x4E>(odd2 ? qa : qb);
;                 r += dppf<0x124>(r); r += dppf<0x128>(r);
;                 const float us = odd2 ? (odd1 ? u[3] : u[2]) : (odd1 ? u[1] : u[0]);
;                 if (j < 4) { const int t = blk * RW_TB + s4 + j; ((float*)(Ub + (size_t)t * (PWP * 2) + URR * 2))[h * 64 + row] = r + us; }
	v_pk_mul_f32 v[150:151], v[72:73], v[120:121] op_sel_hi:[0,1]
	v_pk_fma_f32 v[150:151], v[72:73], v[122:123], v[150:151] op_sel:[1,0,0] op_sel_hi:[1,1,1]
	v_pk_fma_f32 v[150:151], v[74:75], v[124:125], v[150:151] op_sel_hi:[0,1,1]
	v_pk_fma_f32 v[150:151], v[74:75], v[126:127], v[150:151] op_sel:[1,0,0] op_sel_hi:[1,1,1]
	v_pk_mul_f32 v[154:155], v[132:133], v[138:139] op_sel:[0,1] op_sel_hi:[1,1]
	v_pk_mul_f32 v[156:157], v[134:135], v[138:139] op_sel:[0,1] op_sel_hi:[1,1]
	v_add_f32_dpp v152, v150, v150 quad_perm:[1,0,3,2] row_mask:0xf bank_mask:0xf bound_ctrl:1
	v_pk_fma_f32 v[154:155], v[72:73], v[116:117], v[154:155]
	v_pk_fma_f32 v[156:157], v[74:75], v[118:119], v[156:157]
	v_add_f32_dpp v152, v152, v152 quad_perm:[2,3,0,1] row_mask:0xf bank_mask:0xf bound_ctrl:1
	ds_read_b128 v[100:103], v162 offset:20224
	ds_read_b128 v[104:107], v163 offset:20224
	v_add_f32_dpp v152, v152, v152 row_half_mirror row_mask:0xf bank_mask:0xf bound_ctrl:1
	ds_read_b128 v[112:115], v202 offset:20992
	ds_read_b128 v[96:99], v202 offset:19968
	v_add_f32_dpp v152, v152, v152 row_mirror row_mask:0xf bank_mask:0xf bound_ctrl:1
	v_pk_fma_f32 v[68:69], v[128:129], v[152:153], v[154:155] op_sel_hi:[1,0,1]
	v_pk_fma_f32 v[70:71], v[130:131], v[152:153], v[156:157] op_sel_hi:[1,0,1]
	ds_read_b128 v[108:111], v202 offset:20736
	s_waitcnt lgkmcnt(5)
	v_pk_mul_f32 v[144:145], v[68:69], v[80:81] op_sel_hi:[0,1]
	v_pk_fma_f32 v[144:145], v[68:69], v[82:83], v[144:145] op_sel:[1,0,0] op_sel_hi:[1,1,1]
	v_pk_fma_f32 v[144:145], v[70:71], v[84:85], v[144:145] op_sel_hi:[0,1,1]
	v_pk_fma_f32 v[144:145], v[70:71], v[86:87], v[144:145] op_sel:[1,0,0] op_sel_hi:[1,1,1]
	v_pk_mul_f32 v[154:155], v[92:93], v[140:141] op_sel_hi:[1,0]
	v_pk_mul_f32 v[156:157], v[94:95], v[140:141] op_sel_hi:[1,0]
	v_add_f32_dpp v152, v144, v144 quad_perm:[1,0,3,2] row_mask:0xf bank_mask:0xf bound_ctrl:1
	v_pk_fma_f32 v[154:155], v[68:69], v[76:77], v[154:155]
	v_pk_fma_f32 v[156:157], v[70:71], v[78:79], v[156:157]
	v_add_f32_dpp v152, v152, v152 quad_perm:[2,3,0,1] row_mask:0xf bank_mask:0xf bound_ctrl:1
	v_add_f32_dpp v158, v147, v147 row_ror:8 row_mask:0xf bank_mask:0xf
	v_add_f32_dpp v159, v149, v149 row_ror:8 row_mask:0xf bank_mask:0xf
	v_add_f32_dpp v152, v152, v152 row_half_mirror row_mask:0xf bank_mask:0xf bound_ctrl:1
	v_add_f32_dpp v158, v151, v151 row_ror:8 row_mask:0xf bank_mask:0xc
	v_add_f32_dpp v159, v145, v145 row_ror:8 row_mask:0xf bank_mask:0xc
	v_add_f32_dpp v152, v152, v152 row_mirror row_mask:0xf bank_mask:0xf bound_ctrl:1
	v_pk_fma_f32 v[72:73], v[88:89], v[152:153], v[154:155] op_sel_hi:[1,0,1]
	v_pk_fma_f32 v[74:75], v[90:91], v[152:153], v[156:157] op_sel_hi:[1,0,1]
	ds_read_b128 v[120:123], v162 offset:21760
	ds_read_b128 v[124:127], v163 offset:21760
	v_add_f32_dpp v160, v158, v158 row_half_mirror row_mask:0xf bank_mask:0xf
	v_add_f32_dpp v160, v159, v159 row_half_mirror row_mask:0xf bank_mask:0xa
	ds_read_b128 v[132:135], v202 offset:22528
	ds_read_b128 v[116:119], v202 offset:21504
	v_add_f32_dpp v160, v160, v160 quad_perm:[1,0,3,2] row_mask:0xf bank_mask:0xf bound_ctrl:1
	ds_read_b128 v[128:131], v202 offset:22272
	s_nop 0
	v_add_f32_dpp v160, v160, v160 quad_perm:[2,3,0,1] row_mask:0xf bank_mask:0xf bound_ctrl:1
	global_store_dword v161, v160, s[34:35]
	v_add_u32_e32 v161, 0xb000, v161
	s_waitcnt lgkmcnt(5)
	v_pk_mul_f32 v[146:147], v[72:73], v[100:101] op_sel_hi:[0,1]
	v_pk_fma_f32 v[146:147], v[72:73], v[102:103], v[146:147] op_sel:[1,0,0] op_sel_hi:[1,1,1]
	v_pk_fma_f32 v[146:147], v[74:75], v[104:105], v[146:147] op_sel_hi:[0,1,1]
	v_pk_fma_f32 v[146:147], v[74:75], v[106:107], v[146:147] op_sel:[1,0,0] op_sel_hi:[1,1,1]
	v_pk_mul_f32 v[154:155], v[112:113], v[140:141] op_sel:[0,1] op_sel_hi:[1,1]
	v_pk_mul_f32 v[156:157], v[114:115], v[140:141] op_sel:[0,1] op_sel_hi:[1,1]
	v_add_f32_dpp v152, v146, v146 quad_perm:[1,0,3,2] row_mask:0xf bank_mask:0xf bound_ctrl:1
	v_pk_fma_f32 v[154:155], v[72:73], v[96:97], v[154:155]
	v_pk_fma_f32 v[156:157], v[74:75], v[98:99], v[156:157]
	v_add_f32_dpp v152, v152, v152 quad_perm:[2,3,0,1] row_mask:0xf bank_mask:0xf bound_ctrl:1
	ds_read_b128 v[80:83], v162 offset:23296
	ds_read_b128 v[84:87], v163 offset:23296
	v_add_f32_dpp v152, v152, v152 row_half_mirror row_mask:0xf bank_mask:0xf bound_ctrl:1
	ds_read_b128 v[92:95], v202 offset:24064
	ds_read_b128 v[76:79], v202 offset:23040
	v_add_f32_dpp v152, v152, v152 row_mirror row_mask:0xf bank_mask:0xf bound_ctrl:1
	v_pk_fma_f32 v[68:69], v[108:109], v[152:153], v[154:155] op_sel_hi:[1,0,1]
	v_pk_fma_f32 v[70:71], v[110:111], v[152:153], v[156:157] op_sel_hi:[1,0,1]
	ds_read_b128 v[88:91], v202 offset:23808
	s_waitcnt lgkmcnt(5)
	v_pk_mul_f32 v[148:149], v[68:69], v[120:121] op_sel_hi:[0,1]
	v_pk_fma_f32 v[148:149], v[68:69], v[122:123], v[148:149] op_sel:[1,0,0] op_sel_hi:[1,1,1]
	v_pk_fma_f32 v[148:149], v[70:71], v[124:125], v[148:149] op_sel_hi:[0,1,1]
	v_pk_fma_f32 v[148:149], v[70:71], v[126:127], v[148:149] op_sel:[1,0,0] op_sel_hi:[1,1,1]
	v_pk_mul_f32 v[154:155], v[132:133], v[142:143] op_sel_hi:[1,0]
	v_pk_mul_f32 v[156:157], v[134:135], v[142:143] op_sel_hi:[1,0]
	v_add_f32_dpp v152, v148, v148 quad_perm:[1,0,3,2] row_mask:0xf bank_mask:0xf bound_ctrl:1
	v_pk_fma_f32 v[154:155], v[68:69], v[116:117], v[154:155]
	v_pk_fma_f32 v[156:157], v[70:71], v[118:119], v[156:157]
	v_add_f32_dpp v152, v152, v152 quad_perm:[2,3,0,1] row_mask:0xf bank_mask:0xf bound_ctrl:1
	ds_read_b128 v[100:103], v162 offset:24832
	ds_read_b128 v[104:107], v163 offset:24832
	v_add_f32_dpp v152, v152, v152 row_half_mirror row_mask:0xf bank_mask:0xf bound_ctrl:1
	ds_read_b128 v[112:115], v202 offset:25600
	ds_read_b128 v[136:139], v206 offset:24576
	v_add_f32_dpp v152, v152, v152 row_mirror row_mask:0xf bank_mask:0xf bound_ctrl:1
	v_pk_fma_f32 v[72:73], v[128:129], v[152:153], v[154:155] op_sel_hi:[1,0,1]
	v_pk_fma_f32 v[74:75], v[130:131], v[152:153], v[156:157] op_sel_hi:[1,0,1]
	ds_read_b128 v[96:99], v202 offset:24576
	ds_read_b128 v[108:111], v202 offset:25344
	s_waitcnt lgkmcnt(6)
; __device__ __forceinline__ void rwkv_scan(Frame& F, int wg, unsigned* shw, unsigned wait_target, int wait_blk) {
;     ...
;             for (int s4 = 0; s4 < RW_TB; s4 += 4) {
;                 float pz[4], u[4];
; #pragma unroll
;                 for (int q = 0; q < 4; ++q) {
;                     RW_LD(R[(q + 3) & 3], s4 + q + 3);
;                     const RwOps& cur = R[q];
;                     const f32x2 slo = {st.x, st.y}, shi = {st.z, st.w};
;                     f32x2 ma = slo * (f32x2){cur.a.x, cur.a.y}; ma = __builtin_elementwise_fma(shi, (f32x2){cur.a.z, cur.a.w}, ma);
;                     f32x2 mz = slo * (f32x2){cur.wr.x, cur.wr.y}; mz = __builtin_elementwise_fma(shi, (f32x2){cur.wr.z, cur.wr.w}, mz);
;                     float psa = ma.x + ma.y; pz[q] = mz.x + mz.y;
;                     const f32x2 vb = {cur.vs.x, cur.vs.x};
;                     f32x2 tlo = (f32x2){cur.k.x, cur.k.y} * vb, thi = (f32x2){cur.k.z, cur.k.w} * vb;
;                     tlo = __builtin_elementwise_fma(slo, (f32x2){cur.w.x, cur.w.y}, tlo); thi = __builtin_elementwise_fma(shi, (f32x2){cur.w.z, cur.w.w}, thi);
;                     psa = red16(psa);
;                     const f32x2 pb = {psa, psa};
;                     tlo = __builtin_elementwise_fma((f32x2){cur.b.x, cur.b.y}, pb, tlo); thi = __builtin_elementwise_fma((f32x2){cur.b.z, cur.b.w}, pb, thi);
;                     st = (f32x4){tlo.x, tlo.y, thi.x, thi.y};
;                     u[q] = psa * cur.vs.z + cur.vs.y;
;                 }
;                 const float qa = (odd1 ? pz[1] : pz[0]) + dppf<0xB1>(odd1 ? pz[0] : pz[1]);
;                 const float qb = (odd1 ? pz[3] : pz[2]) + dppf<0xB1>(odd1 ? pz[2] : pz[3]);
;                 float r = (odd2 ? qb : qa) + dppf<0x4E>(odd2 ? qa : qb);
;                 r += dppf<0x124>(r); r += dppf<0x128>(r);
;                 const float us = odd2 ? (odd1 ? u[3] : u[2]) : (odd1 ? u[1] : u[0]);
;                 if (j < 4) { const int t = blk * RW_TB + s4 + j; ((float*)(Ub + (size_t)t * (PWP * 2) + URR * 2))[h * 64 + row] = r + us; }
	v_pk_mul_f32 v[150:151], v[72:73], v[80:81] op_sel_hi:[0,1]
	v_pk_fma_f32 v[150:151], v[72:73], v[82:83], v[150:151] op_sel:[1,0,0] op_sel_hi:[1,1,1]
	v_pk_fma_f32 v[150:151], v[74:75], v[84:85], v[150:151] op_sel_hi:[0,1,1]
	v_pk_fma_f32 v[150:151], v[74:75], v[86:87], v[150:151] op_sel:[1,0,0] op_sel_hi:[1,1,1]
	v_pk_mul_f32 v[154:155], v[92:93], v[142:143] op_sel:[0,1] op_sel_hi:[1,1]
	v_pk_mul_f32 v[156:157], v[94:95], v[142:143] op_sel:[0,1] op_sel_hi:[1,1]
	v_add_f32_dpp v152, v150, v150 quad_perm:[1,0,3,2] row_mask:0xf bank_mask:0xf bound_ctrl:1
	v_pk_fma_f32 v[154:155], v[72:73], v[76:77], v[154:155]
	v_pk_fma_f32 v[156:157], v[74:75], v[78:79], v[156:157]
	v_add_f32_dpp v152, v152, v152 quad_perm:[2,3,0,1] row_mask:0xf bank_mask:0xf bound_ctrl:1
	ds_read_b128 v[120:123], v162 offset:26368
	ds_read_b128 v[124:127], v163 offset:26368
	v_add_f32_dpp v152, v152, v152 row_half_mirror row_mask:0xf bank_mask:0xf bound_ctrl:1
	ds_read_b128 v[132:135], v202 offset:27136
	ds_read_b128 v[116:119], v202 offset:26112
	v_add_f32_dpp v152, v152, v152 row_mirror row_mask:0xf bank_mask:0xf bound_ctrl:1
	v_pk_fma_f32 v[68:69], v[88:89], v[152:153], v[154:155] op_sel_hi:[1,0,1]
	v_pk_fma_f32 v[70:71], v[90:91], v[152:153], v[156:157] op_sel_hi:[1,0,1]
	ds_read_b128 v[128:131], v202 offset:26880
	s_waitcnt lgkmcnt(5)
	v_pk_mul_f32 v[144:145], v[68:69], v[100:101] op_sel_hi:[0,1]
	v_pk_fma_f32 v[144:145], v[68:69], v[102:103], v[144:145] op_sel:[1,0,0] op_sel_hi:[1,1,1]
	v_pk_fma_f32 v[144:145], v[70:71], v[104:105], v[144:145] op_sel_hi:[0,1,1]
	v_pk_fma_f32 v[144:145], v[70:71], v[106:107], v[144:145] op_sel:[1,0,0] op_sel_hi:[1,1,1]
	v_pk_mul_f32 v[154:155], v[112:113], v[136:137] op_sel_hi:[1,0]
	v_pk_mul_f32 v[156:157], v[114:115], v[136:137] op_sel_hi:[1,0]
	v_add_f32_dpp v152, v144, v144 quad_perm:[1,0,3,2] row_mask:0xf bank_mask:0xf bound_ctrl:1
	v_pk_fma_f32 v[154:155], v[68:69], v[96:97], v[154:155]
	v_pk_fma_f32 v[156:157], v[70:71], v[98:99], v[156:157]
	v_add_f32_dpp v152, v152, v152 quad_perm:[2,3,0,1] row_mask:0xf bank_mask:0xf bound_ctrl:1
	v_add_f32_dpp v158, v147, v147 row_ror:8 row_mask:0xf bank_mask:0xf
	v_add_f32_dpp v159, v149, v149 row_ror:8 row_mask:0xf bank_mask:0xf
	v_add_f32_dpp v152, v152, v152 row_half_mirror row_mask:0xf bank_mask:0xf bound_ctrl:1
	v_add_f32_dpp v158, v151, v151 row_ror:8 row_mask:0xf bank_mask:0xc
	v_add_f32_dpp v159, v145, v145 row_ror:8 row_mask:0xf bank_mask:0xc
	v_add_f32_dpp v152, v152, v152 row_mirror row_mask:0xf bank_mask:0xf bound_ctrl:1
	v_pk_fma_f32 v[72:73], v[108:109], v[152:153], v[154:155] op_sel_hi:[1,0,1]
	v_pk_fma_f32 v[74:75], v[110:111], v[152:153], v[156:157] op_sel_hi:[1,0,1]
	ds_read_b128 v[80:83], v162 offset:27904
	ds_read_b128 v[84:87], v163 offset:27904
	v_add_f32_dpp v160, v158, v158 row_half_mirror row_mask:0xf bank_mask:0xf
	v_add_f32_dpp v160, v159, v159 row_half_mirror row_mask:0xf bank_mask:0xa
	ds_read_b128 v[92:95], v202 offset:28672
	ds_read_b128 v[76:79], v202 offset:27648
	v_add_f32_dpp v160, v160, v160 quad_perm:[1,0,3,2] row_mask:0xf bank_mask:0xf bound_ctrl:1
	ds_read_b128 v[88:91], v202 offset:28416
	s_nop 0
	v_add_f32_dpp v160, v160, v160 quad_perm:[2,3,0,1] row_mask:0xf bank_mask:0xf bound_ctrl:1
	global_store_dword v161, v160, s[34:35]
	v_add_u32_e32 v161, 0xb000, v161
	s_waitcnt lgkmcnt(5)
	v_pk_mul_f32 v[146:147], v[72:73], v[120:121] op_sel_hi:[0,1]
	v_pk_fma_f32 v[146:147], v[72:73], v[122:123], v[146:147] op_sel:[1,0,0] op_sel_hi:[1,1,1]
	v_pk_fma_f32 v[146:147], v[74:75], v[124:125], v[146:147] op_sel_hi:[0,1,1]
	v_pk_fma_f32 v[146:147], v[74:75], v[126:127], v[146:147] op_sel:[1,0,0] op_sel_hi:[1,1,1]
	v_pk_mul_f32 v[154:155], v[132:133], v[136:137] op_sel:[0,1] op_sel_hi:[1,1]
	v_pk_mul_f32 v[156:157], v[134:135], v[136:137] op_sel:[0,1] op_sel_hi:[1,1]
	v_add_f32_dpp v152, v146, v146 quad_perm:[1,0,3,2] row_mask:0xf bank_mask:0xf bound_ctrl:1
	v_pk_fma_f32 v[154:155], v[72:73], v[116:117], v[154:155]
	v_pk_fma_f32 v[156:157], v[74:75], v[118:119], v[156:157]
	v_add_f32_dpp v152, v152, v152 quad_perm:[2,3,0,1] row_mask:0xf bank_mask:0xf bound_ctrl:1
	ds_read_b128 v[100:103], v162 offset:29440
	ds_read_b128 v[104:107], v163 offset:29440
	v_add_f32_dpp v152, v152, v152 row_half_mirror row_mask:0xf bank_mask:0xf bound_ctrl:1
	ds_read_b128 v[112:115], v202 offset:30208
	ds_read_b128 v[96:99], v202 offset:29184
	v_add_f32_dpp v152, v152, v152 row_mirror row_mask:0xf bank_mask:0xf bound_ctrl:1
	v_pk_fma_f32 v[68:69], v[128:129], v[152:153], v[154:155] op_sel_hi:[1,0,1]
	v_pk_fma_f32 v[70:71], v[130:131], v[152:153], v[156:157] op_sel_hi:[1,0,1]
	ds_read_b128 v[108:111], v202 offset:29952
	s_waitcnt lgkmcnt(5)
	v_pk_mul_f32 v[148:149], v[68:69], v[80:81] op_sel_hi:[0,1]
	v_pk_fma_f32 v[148:149], v[68:69], v[82:83], v[148:149] op_sel:[1,0,0] op_sel_hi:[1,1,1]
	v_pk_fma_f32 v[148:149], v[70:71], v[84:85], v[148:149] op_sel_hi:[0,1,1]
	v_pk_fma_f32 v[148:149], v[70:71], v[86:87], v[148:149] op_sel:[1,0,0] op_sel_hi:[1,1,1]
	v_pk_mul_f32 v[154:155], v[92:93], v[138:139] op_sel_hi:[1,0]
	v_pk_mul_f32 v[156:157], v[94:95], v[138:139] op_sel_hi:[1,0]
	v_add_f32_dpp v152, v148, v148 quad_perm:[1,0,3,2] row_mask:0xf bank_mask:0xf bound_ctrl:1
	v_pk_fma_f32 v[154:155], v[68:69], v[76:77], v[154:155]
	v_pk_fma_f32 v[156:157], v[70:71], v[78:79], v[156:157]
	v_add_f32_dpp v152, v152, v152 quad_perm:[2,3,0,1] row_mask:0xf bank_mask:0xf bound_ctrl:1
	ds_read_b128 v[120:123], v162 offset:30976
	ds_read_b128 v[124:127], v163 offset:30976
	v_add_f32_dpp v152, v152, v152 row_half_mirror row_mask:0xf bank_mask:0xf bound_ctrl:1
	ds_read_b128 v[132:135], v202 offset:31744
	ds_read_b128 v[140:143], v206 offset:30720
	v_add_f32_dpp v152, v152, v152 row_mirror row_mask:0xf bank_mask:0xf bound_ctrl:1
	v_pk_fma_f32 v[72:73], v[88:89], v[152:153], v[154:155] op_sel_hi:[1,0,1]
	v_pk_fma_f32 v[74:75], v[90:91], v[152:153], v[156:157] op_sel_hi:[1,0,1]
	ds_read_b128 v[116:119], v202 offset:30720
	ds_read_b128 v[128:131], v202 offset:31488
	s_waitcnt lgkmcnt(6)
; __device__ __forceinline__ void rwkv_scan(Frame& F, int wg, unsigned* shw, unsigned wait_target, int wait_blk) {
;     ...
;             for (int s4 = 0; s4 < RW_TB; s4 += 4) {
;                 float pz[4], u[4];
; #pragma unroll
;                 for (int q = 0; q < 4; ++q) {
;                     RW_LD(R[(q + 3) & 3], s4 + q + 3);
;                     const RwOps& cur = R[q];
;                     const f32x2 slo = {st.x, st.y}, shi = {st.z, st.w};
;                     f32x2 ma = slo * (f32x2){cur.a.x, cur.a.y}; ma = __builtin_elementwise_fma(shi, (f32x2){cur.a.z, cur.a.w}, ma);
;                     f32x2 mz = slo * (f32x2){cur.wr.x, cur.wr.y}; mz = __builtin_elementwise_fma(shi, (f32x2){cur.wr.z, cur.wr.w}, mz);
;                     float psa = ma.x + ma.y; pz[q] = mz.x + mz.y;
;                     const f32x2 vb = {cur.vs.x, cur.vs.x};
;                     f32x2 tlo = (f32x2){cur.k.x, cur.k.y} * vb, thi = (f32x2){cur.k.z, cur.k.w} * vb;
;                     tlo = __builtin_elementwise_fma(slo, (f32x2){cur.w.x, cur.w.y}, tlo); thi = __builtin_elementwise_fma(shi, (f32x2){cur.w.z, cur.w.w}, thi);
;                     psa = red16(psa);
;                     const f32x2 pb = {psa, psa};
;                     tlo = __builtin_elementwise_fma((f32x2){cur.b.x, cur.b.y}, pb, tlo); thi = __builtin_elementwise_fma((f32x2){cur.b.z, cur.b.w}, pb, thi);
;                     st = (f32x4){tlo.x, tlo.y, thi.x, thi.y};
;                     u[q] = psa * cur.vs.z + cur.vs.y;
;                 }
;                 const float qa = (odd1 ? pz[1] : pz[0]) + dppf<0xB1>(odd1 ? pz[0] : pz[1]);
;                 const float qb = (odd1 ? pz[3] : pz[2]) + dppf<0xB1>(odd1 ? pz[2] : pz[3]);
;                 float r = (odd2 ? qb : qa) + dppf<0x4E>(odd2 ? qa : qb);
;                 r += dppf<0x124>(r); r += dppf<0x128>(r);
;                 const float us = odd2 ? (odd1 ? u[3] : u[2]) : (odd1 ? u[1] : u[0]);
;                 if (j < 4) { const int t = blk * RW_TB + s4 + j; ((float*)(Ub + (size_t)t * (PWP * 2) + URR * 2))[h * 64 + row] = r + us; }
	v_pk_mul_f32 v[150:151], v[72:73], v[100:101] op_sel_hi:[0,1]
	v_pk_fma_f32 v[150:151], v[72:73], v[102:103], v[150:151] op_sel:[1,0,0] op_sel_hi:[1,1,1]
	v_pk_fma_f32 v[150:151], v[74:75], v[104:105], v[150:151] op_sel_hi:[0,1,1]
	v_pk_fma_f32 v[150:151], v[74:75], v[106:107], v[150:151] op_sel:[1,0,0] op_sel_hi:[1,1,1]
	v_pk_mul_f32 v[154:155], v[112:113], v[138:139] op_sel:[0,1] op_sel_hi:[1,1]
	v_pk_mul_f32 v[156:157], v[114:115], v[138:139] op_sel:[0,1] op_sel_hi:[1,1]
	v_add_f32_dpp v152, v150, v150 quad_perm:[1,0,3,2] row_mask:0xf bank_mask:0xf bound_ctrl:1
	v_pk_fma_f32 v[154:155], v[72:73], v[96:97], v[154:155]
	v_pk_fma_f32 v[156:157], v[74:75], v[98:99], v[156:157]
	v_add_f32_dpp v152, v152, v152 quad_perm:[2,3,0,1] row_mask:0xf bank_mask:0xf bound_ctrl:1
	ds_read_b128 v[80:83], v162 offset:32512
	ds_read_b128 v[84:87], v163 offset:32512
	v_add_f32_dpp v152, v152, v152 row_half_mirror row_mask:0xf bank_mask:0xf bound_ctrl:1
	ds_read_b128 v[92:95], v202 offset:33280
	ds_read_b128 v[76:79], v202 offset:32256
	v_add_f32_dpp v152, v152, v152 row_mirror row_mask:0xf bank_mask:0xf bound_ctrl:1
	v_pk_fma_f32 v[68:69], v[108:109], v[152:153], v[154:155] op_sel_hi:[1,0,1]
	v_pk_fma_f32 v[70:71], v[110:111], v[152:153], v[156:157] op_sel_hi:[1,0,1]
	ds_read_b128 v[88:91], v202 offset:33024
	s_waitcnt lgkmcnt(5)
	v_pk_mul_f32 v[144:145], v[68:69], v[120:121] op_sel_hi:[0,1]
	v_pk_fma_f32 v[144:145], v[68:69], v[122:123], v[144:145] op_sel:[1,0,0] op_sel_hi:[1,1,1]
	v_pk_fma_f32 v[144:145], v[70:71], v[124:125], v[144:145] op_sel_hi:[0,1,1]
	v_pk_fma_f32 v[144:145], v[70:71], v[126:127], v[144:145] op_sel:[1,0,0] op_sel_hi:[1,1,1]
	v_pk_mul_f32 v[154:155], v[132:133], v[140:141] op_sel_hi:[1,0]
	v_pk_mul_f32 v[156:157], v[134:135], v[140:141] op_sel_hi:[1,0]
	v_add_f32_dpp v152, v144, v144 quad_perm:[1,0,3,2] row_mask:0xf bank_mask:0xf bound_ctrl:1
	v_pk_fma_f32 v[154:155], v[68:69], v[116:117], v[154:155]
	v_pk_fma_f32 v[156:157], v[70:71], v[118:119], v[156:157]
	v_add_f32_dpp v152, v152, v152 quad_perm:[2,3,0,1] row_mask:0xf bank_mask:0xf bound_ctrl:1
	v_add_f32_dpp v158, v147, v147 row_ror:8 row_mask:0xf bank_mask:0xf
	v_add_f32_dpp v159, v149, v149 row_ror:8 row_mask:0xf bank_mask:0xf
	v_add_f32_dpp v152, v152, v152 row_half_mirror row_mask:0xf bank_mask:0xf bound_ctrl:1
	v_add_f32_dpp v158, v151, v151 row_ror:8 row_mask:0xf bank_mask:0xc
	v_add_f32_dpp v159, v145, v145 row_ror:8 row_mask:0xf bank_mask:0xc
	v_add_f32_dpp v152, v152, v152 row_mirror row_mask:0xf bank_mask:0xf bound_ctrl:1
	v_pk_fma_f32 v[72:73], v[128:129], v[152:153], v[154:155] op_sel_hi:[1,0,1]
	v_pk_fma_f32 v[74:75], v[130:131], v[152:153], v[156:157] op_sel_hi:[1,0,1]
	ds_read_b128 v[100:103], v162 offset:34048
	ds_read_b128 v[104:107], v163 offset:34048
	v_add_f32_dpp v160, v158, v158 row_half_mirror row_mask:0xf bank_mask:0xf
	v_add_f32_dpp v160, v159, v159 row_half_mirror row_mask:0xf bank_mask:0xa
	ds_read_b128 v[112:115], v202 offset:34816
	ds_read_b128 v[96:99], v202 offset:33792
	v_add_f32_dpp v160, v160, v160 quad_perm:[1,0,3,2] row_mask:0xf bank_mask:0xf bound_ctrl:1
	ds_read_b128 v[108:111], v202 offset:34560
	s_nop 0
	v_add_f32_dpp v160, v160, v160 quad_perm:[2,3,0,1] row_mask:0xf bank_mask:0xf bound_ctrl:1
	global_store_dword v161, v160, s[34:35]
	v_add_u32_e32 v161, 0xb000, v161
	s_waitcnt lgkmcnt(5)
	v_pk_mul_f32 v[146:147], v[72:73], v[80:81] op_sel_hi:[0,1]
	v_pk_fma_f32 v[146:147], v[72:73], v[82:83], v[146:147] op_sel:[1,0,0] op_sel_hi:[1,1,1]
	v_pk_fma_f32 v[146:147], v[74:75], v[84:85], v[146:147] op_sel_hi:[0,1,1]
	v_pk_fma_f32 v[146:147], v[74:75], v[86:87], v[146:147] op_sel:[1,0,0] op_sel_hi:[1,1,1]
	v_pk_mul_f32 v[154:155], v[92:93], v[140:141] op_sel:[0,1] op_sel_hi:[1,1]
	v_pk_mul_f32 v[156:157], v[94:95], v[140:141] op_sel:[0,1] op_sel_hi:[1,1]
	v_add_f32_dpp v152, v146, v146 quad_perm:[1,0,3,2] row_mask:0xf bank_mask:0xf bound_ctrl:1
	v_pk_fma_f32 v[154:155], v[72:73], v[76:77], v[154:155]
	v_pk_fma_f32 v[156:157], v[74:75], v[78:79], v[156:157]
	v_add_f32_dpp v152, v152, v152 quad_perm:[2,3,0,1] row_mask:0xf bank_mask:0xf bound_ctrl:1
	ds_read_b128 v[120:123], v162 offset:35584
	ds_read_b128 v[124:127], v163 offset:35584
	v_add_f32_dpp v152, v152, v152 row_half_mirror row_mask:0xf bank_mask:0xf bound_ctrl:1
	ds_read_b128 v[132:135], v202 offset:36352
	ds_read_b128 v[116:119], v202 offset:35328
	v_add_f32_dpp v152, v152, v152 row_mirror row_mask:0xf bank_mask:0xf bound_ctrl:1
	v_pk_fma_f32 v[68:69], v[88:89], v[152:153], v[154:155] op_sel_hi:[1,0,1]
	v_pk_fma_f32 v[70:71], v[90:91], v[152:153], v[156:157] op_sel_hi:[1,0,1]
	ds_read_b128 v[128:131], v202 offset:36096
	s_waitcnt lgkmcnt(5)
	v_pk_mul_f32 v[148:149], v[68:69], v[100:101] op_sel_hi:[0,1]
	v_pk_fma_f32 v[148:149], v[68:69], v[102:103], v[148:149] op_sel:[1,0,0] op_sel_hi:[1,1,1]
	v_pk_fma_f32 v[148:149], v[70:71], v[104:105], v[148:149] op_sel_hi:[0,1,1]
	v_pk_fma_f32 v[148:149], v[70:71], v[106:107], v[148:149] op_sel:[1,0,0] op_sel_hi:[1,1,1]
	v_pk_mul_f32 v[154:155], v[112:113], v[142:143] op_sel_hi:[1,0]
	v_pk_mul_f32 v[156:157], v[114:115], v[142:143] op_sel_hi:[1,0]
	v_add_f32_dpp v152, v148, v148 quad_perm:[1,0,3,2] row_mask:0xf bank_mask:0xf bound_ctrl:1
	v_pk_fma_f32 v[154:155], v[68:69], v[96:97], v[154:155]
	v_pk_fma_f32 v[156:157], v[70:71], v[98:99], v[156:157]
	v_add_f32_dpp v152, v152, v152 quad_perm:[2,3,0,1] row_mask:0xf bank_mask:0xf bound_ctrl:1
	ds_read_b128 v[80:83], v162 offset:37120
	ds_read_b128 v[84:87], v163 offset:37120
	v_add_f32_dpp v152, v152, v152 row_half_mirror row_mask:0xf bank_mask:0xf bound_ctrl:1
	ds_read_b128 v[92:95], v202 offset:37888
	ds_read_b128 v[136:139], v206 offset:36864
	v_add_f32_dpp v152, v152, v152 row_mirror row_mask:0xf bank_mask:0xf bound_ctrl:1
	v_pk_fma_f32 v[72:73], v[108:109], v[152:153], v[154:155] op_sel_hi:[1,0,1]
	v_pk_fma_f32 v[74:75], v[110:111], v[152:153], v[156:157] op_sel_hi:[1,0,1]
	ds_read_b128 v[76:79], v202 offset:36864
	ds_read_b128 v[88:91], v202 offset:37632
	s_waitcnt lgkmcnt(6)
; __device__ __forceinline__ void rwkv_scan(Frame& F, int wg, unsigned* shw, unsigned wait_target, int wait_blk) {
;     ...
;             for (int s4 = 0; s4 < RW_TB; s4 += 4) {
;                 float pz[4], u[4];
; #pragma unroll
;                 for (int q = 0; q < 4; ++q) {
;                     RW_LD(R[(q + 3) & 3], s4 + q + 3);
;                     const RwOps& cur = R[q];
;                     const f32x2 slo = {st.x, st.y}, shi = {st.z, st.w};
;                     f32x2 ma = slo * (f32x2){cur.a.x, cur.a.y}; ma = __builtin_elementwise_fma(shi, (f32x2){cur.a.z, cur.a.w}, ma);
;                     f32x2 mz = slo * (f32x2){cur.wr.x, cur.wr.y}; mz = __builtin_elementwise_fma(shi, (f32x2){cur.wr.z, cur.wr.w}, mz);
;                     float psa = ma.x + ma.y; pz[q] = mz.x + mz.y;
;                     const f32x2 vb = {cur.vs.x, cur.vs.x};
;                     f32x2 tlo = (f32x2){cur.k.x, cur.k.y} * vb, thi = (f32x2){cur.k.z, cur.k.w} * vb;
;                     tlo = __builtin_elementwise_fma(slo, (f32x2){cur.w.x, cur.w.y}, tlo); thi = __builtin_elementwise_fma(shi, (f32x2){cur.w.z, cur.w.w}, thi);
;                     psa = red16(psa);
;                     const f32x2 pb = {psa, psa};
;                     tlo = __builtin_elementwise_fma((f32x2){cur.b.x, cur.b.y}, pb, tlo); thi = __builtin_elementwise_fma((f32x2){cur.b.z, cur.b.w}, pb, thi);
;                     st = (f32x4){tlo.x, tlo.y, thi.x, thi.y};
;                     u[q] = psa * cur.vs.z + cur.vs.y;
;                 }
;                 const float qa = (odd1 ? pz[1] : pz[0]) + dppf<0xB1>(odd1 ? pz[0] : pz[1]);
;                 const float qb = (odd1 ? pz[3] : pz[2]) + dppf<0xB1>(odd1 ? pz[2] : pz[3]);
;                 float r = (odd2 ? qb : qa) + dppf<0x4E>(odd2 ? qa : qb);
;                 r += dppf<0x124>(r); r += dppf<0x128>(r);
;                 const float us = odd2 ? (odd1 ? u[3] : u[2]) : (odd1 ? u[1] : u[0]);
;                 if (j < 4) { const int t = blk * RW_TB + s4 + j; ((float*)(Ub + (size_t)t * (PWP * 2) + URR * 2))[h * 64 + row] = r + us; }
	v_pk_mul_f32 v[150:151], v[72:73], v[120:121] op_sel_hi:[0,1]
	v_pk_fma_f32 v[150:151], v[72:73], v[122:123], v[150:151] op_sel:[1,0,0] op_sel_hi:[1,1,1]
	v_pk_fma_f32 v[150:151], v[74:75], v[124:125], v[150:151] op_sel_hi:[0,1,1]
	v_pk_fma_f32 v[150:151], v[74:75], v[126:127], v[150:151] op_sel:[1,0,0] op_sel_hi:[1,1,1]
	v_pk_mul_f32 v[154:155], v[132:133], v[142:143] op_sel:[0,1] op_sel_hi:[1,1]
	v_pk_mul_f32 v[156:157], v[134:135], v[142:143] op_sel:[0,1] op_sel_hi:[1,1]
	v_add_f32_dpp v152, v150, v150 quad_perm:[1,0,3,2] row_mask:0xf bank_mask:0xf bound_ctrl:1
	v_pk_fma_f32 v[154:155], v[72:73], v[116:117], v[154:155]
	v_pk_fma_f32 v[156:157], v[74:75], v[118:119], v[156:157]
	v_add_f32_dpp v152, v152, v152 quad_perm:[2,3,0,1] row_mask:0xf bank_mask:0xf bound_ctrl:1
	ds_read_b128 v[100:103], v162 offset:38656
	ds_read_b128 v[104:107], v163 offset:38656
	v_add_f32_dpp v152, v152, v152 row_half_mirror row_mask:0xf bank_mask:0xf bound_ctrl:1
	ds_read_b128 v[112:115], v202 offset:39424
	ds_read_b128 v[96:99], v202 offset:38400
	v_add_f32_dpp v152, v152, v152 row_mirror row_mask:0xf bank_mask:0xf bound_ctrl:1
	v_pk_fma_f32 v[68:69], v[128:129], v[152:153], v[154:155] op_sel_hi:[1,0,1]
	v_pk_fma_f32 v[70:71], v[130:131], v[152:153], v[156:157] op_sel_hi:[1,0,1]
	ds_read_b128 v[108:111], v202 offset:39168
	s_waitcnt lgkmcnt(5)
	v_pk_mul_f32 v[144:145], v[68:69], v[80:81] op_sel_hi:[0,1]
	v_pk_fma_f32 v[144:145], v[68:69], v[82:83], v[144:145] op_sel:[1,0,0] op_sel_hi:[1,1,1]
	v_pk_fma_f32 v[144:145], v[70:71], v[84:85], v[144:145] op_sel_hi:[0,1,1]
	v_pk_fma_f32 v[144:145], v[70:71], v[86:87], v[144:145] op_sel:[1,0,0] op_sel_hi:[1,1,1]
	v_pk_mul_f32 v[154:155], v[92:93], v[136:137] op_sel_hi:[1,0]
	v_pk_mul_f32 v[156:157], v[94:95], v[136:137] op_sel_hi:[1,0]
	v_add_f32_dpp v152, v144, v144 quad_perm:[1,0,3,2] row_mask:0xf bank_mask:0xf bound_ctrl:1
	v_pk_fma_f32 v[154:155], v[68:69], v[76:77], v[154:155]
	v_pk_fma_f32 v[156:157], v[70:71], v[78:79], v[156:157]
	v_add_f32_dpp v152, v152, v152 quad_perm:[2,3,0,1] row_mask:0xf bank_mask:0xf bound_ctrl:1
	v_add_f32_dpp v158, v147, v147 row_ror:8 row_mask:0xf bank_mask:0xf
	v_add_f32_dpp v159, v149, v149 row_ror:8 row_mask:0xf bank_mask:0xf
	v_add_f32_dpp v152, v152, v152 row_half_mirror row_mask:0xf bank_mask:0xf bound_ctrl:1
	v_add_f32_dpp v158, v151, v151 row_ror:8 row_mask:0xf bank_mask:0xc
	v_add_f32_dpp v159, v145, v145 row_ror:8 row_mask:0xf bank_mask:0xc
	v_add_f32_dpp v152, v152, v152 row_mirror row_mask:0xf bank_mask:0xf bound_ctrl:1
	v_pk_fma_f32 v[72:73], v[88:89], v[152:153], v[154:155] op_sel_hi:[1,0,1]
	v_pk_fma_f32 v[74:75], v[90:91], v[152:153], v[156:157] op_sel_hi:[1,0,1]
	ds_read_b128 v[120:123], v162 offset:40192
	ds_read_b128 v[124:127], v163 offset:40192
	v_add_f32_dpp v160, v158, v158 row_half_mirror row_mask:0xf bank_mask:0xf
	v_add_f32_dpp v160, v159, v159 row_half_mirror row_mask:0xf bank_mask:0xa
	ds_read_b128 v[132:135], v202 offset:40960
	ds_read_b128 v[116:119], v202 offset:39936
	v_add_f32_dpp v160, v160, v160 quad_perm:[1,0,3,2] row_mask:0xf bank_mask:0xf bound_ctrl:1
	ds_read_b128 v[128:131], v202 offset:40704
	s_nop 0
	v_add_f32_dpp v160, v160, v160 quad_perm:[2,3,0,1] row_mask:0xf bank_mask:0xf bound_ctrl:1
	global_store_dword v161, v160, s[34:35]
	v_add_u32_e32 v161, 0xb000, v161
	s_waitcnt lgkmcnt(5)
	v_pk_mul_f32 v[146:147], v[72:73], v[100:101] op_sel_hi:[0,1]
	v_pk_fma_f32 v[146:147], v[72:73], v[102:103], v[146:147] op_sel:[1,0,0] op_sel_hi:[1,1,1]
	v_pk_fma_f32 v[146:147], v[74:75], v[104:105], v[146:147] op_sel_hi:[0,1,1]
	v_pk_fma_f32 v[146:147], v[74:75], v[106:107], v[146:147] op_sel:[1,0,0] op_sel_hi:[1,1,1]
	v_pk_mul_f32 v[154:155], v[112:113], v[136:137] op_sel:[0,1] op_sel_hi:[1,1]
	v_pk_mul_f32 v[156:157], v[114:115], v[136:137] op_sel:[0,1] op_sel_hi:[1,1]
	v_add_f32_dpp v152, v146, v146 quad_perm:[1,0,3,2] row_mask:0xf bank_mask:0xf bound_ctrl:1
	v_pk_fma_f32 v[154:155], v[72:73], v[96:97], v[154:155]
	v_pk_fma_f32 v[156:157], v[74:75], v[98:99], v[156:157]
	v_add_f32_dpp v152, v152, v152 quad_perm:[2,3,0,1] row_mask:0xf bank_mask:0xf bound_ctrl:1
	ds_read_b128 v[80:83], v162 offset:41728
	ds_read_b128 v[84:87], v163 offset:41728
	v_add_f32_dpp v152, v152, v152 row_half_mirror row_mask:0xf bank_mask:0xf bound_ctrl:1
	ds_read_b128 v[92:95], v202 offset:42496
	ds_read_b128 v[76:79], v202 offset:41472
	v_add_f32_dpp v152, v152, v152 row_mirror row_mask:0xf bank_mask:0xf bound_ctrl:1
	v_pk_fma_f32 v[68:69], v[108:109], v[152:153], v[154:155] op_sel_hi:[1,0,1]
	v_pk_fma_f32 v[70:71], v[110:111], v[152:153], v[156:157] op_sel_hi:[1,0,1]
	ds_read_b128 v[88:91], v202 offset:42240
	s_waitcnt lgkmcnt(5)
	v_pk_mul_f32 v[148:149], v[68:69], v[120:121] op_sel_hi:[0,1]
	v_pk_fma_f32 v[148:149], v[68:69], v[122:123], v[148:149] op_sel:[1,0,0] op_sel_hi:[1,1,1]
	v_pk_fma_f32 v[148:149], v[70:71], v[124:125], v[148:149] op_sel_hi:[0,1,1]
	v_pk_fma_f32 v[148:149], v[70:71], v[126:127], v[148:149] op_sel:[1,0,0] op_sel_hi:[1,1,1]
	v_pk_mul_f32 v[154:155], v[132:133], v[138:139] op_sel_hi:[1,0]
	v_pk_mul_f32 v[156:157], v[134:135], v[138:139] op_sel_hi:[1,0]
	v_add_f32_dpp v152, v148, v148 quad_perm:[1,0,3,2] row_mask:0xf bank_mask:0xf bound_ctrl:1
	v_pk_fma_f32 v[154:155], v[68:69], v[116:117], v[154:155]
	v_pk_fma_f32 v[156:157], v[70:71], v[118:119], v[156:157]
	v_add_f32_dpp v152, v152, v152 quad_perm:[2,3,0,1] row_mask:0xf bank_mask:0xf bound_ctrl:1
	ds_read_b128 v[100:103], v162 offset:43264
	ds_read_b128 v[104:107], v163 offset:43264
	v_add_f32_dpp v152, v152, v152 row_half_mirror row_mask:0xf bank_mask:0xf bound_ctrl:1
	ds_read_b128 v[112:115], v202 offset:44032
	ds_read_b128 v[140:143], v206 offset:43008
	v_add_f32_dpp v152, v152, v152 row_mirror row_mask:0xf bank_mask:0xf bound_ctrl:1
	v_pk_fma_f32 v[72:73], v[128:129], v[152:153], v[154:155] op_sel_hi:[1,0,1]
	v_pk_fma_f32 v[74:75], v[130:131], v[152:153], v[156:157] op_sel_hi:[1,0,1]
	ds_read_b128 v[96:99], v202 offset:43008
	ds_read_b128 v[108:111], v202 offset:43776
	s_waitcnt lgkmcnt(6)
; __device__ __forceinline__ void rwkv_scan(Frame& F, int wg, unsigned* shw, unsigned wait_target, int wait_blk) {
;     ...
;             for (int s4 = 0; s4 < RW_TB; s4 += 4) {
;                 float pz[4], u[4];
; #pragma unroll
;                 for (int q = 0; q < 4; ++q) {
;                     RW_LD(R[(q + 3) & 3], s4 + q + 3);
;                     const RwOps& cur = R[q];
;                     const f32x2 slo = {st.x, st.y}, shi = {st.z, st.w};
;                     f32x2 ma = slo * (f32x2){cur.a.x, cur.a.y}; ma = __builtin_elementwise_fma(shi, (f32x2){cur.a.z, cur.a.w}, ma);
;                     f32x2 mz = slo * (f32x2){cur.wr.x, cur.wr.y}; mz = __builtin_elementwise_fma(shi, (f32x2){cur.wr.z, cur.wr.w}, mz);
;                     float psa = ma.x + ma.y; pz[q] = mz.x + mz.y;
;                     const f32x2 vb = {cur.vs.x, cur.vs.x};
;                     f32x2 tlo = (f32x2){cur.k.x, cur.k.y} * vb, thi = (f32x2){cur.k.z, cur.k.w} * vb;
;                     tlo = __builtin_elementwise_fma(slo, (f32x2){cur.w.x, cur.w.y}, tlo); thi = __builtin_elementwise_fma(shi, (f32x2){cur.w.z, cur.w.w}, thi);
;                     psa = red16(psa);
;                     const f32x2 pb = {psa, psa};
;                     tlo = __builtin_elementwise_fma((f32x2){cur.b.x, cur.b.y}, pb, tlo); thi = __builtin_elementwise_fma((f32x2){cur.b.z, cur.b.w}, pb, thi);
;                     st = (f32x4){tlo.x, tlo.y, thi.x, thi.y};
;                     u[q] = psa * cur.vs.z + cur.vs.y;
;                 }
;                 const float qa = (odd1 ? pz[1] : pz[0]) + dppf<0xB1>(odd1 ? pz[0] : pz[1]);
;                 const float qb = (odd1 ? pz[3] : pz[2]) + dppf<0xB1>(odd1 ? pz[2] : pz[3]);
;                 float r = (odd2 ? qb : qa) + dppf<0x4E>(odd2 ? qa : qb);
;                 r += dppf<0x124>(r); r += dppf<0x128>(r);
;                 const float us = odd2 ? (odd1 ? u[3] : u[2]) : (odd1 ? u[1] : u[0]);
;                 if (j < 4) { const int t = blk * RW_TB + s4 + j; ((float*)(Ub + (size_t)t * (PWP * 2) + URR * 2))[h * 64 + row] = r + us; }
	v_pk_mul_f32 v[150:151], v[72:73], v[80:81] op_sel_hi:[0,1]
	v_pk_fma_f32 v[150:151], v[72:73], v[82:83], v[150:151] op_sel:[1,0,0] op_sel_hi:[1,1,1]
	v_pk_fma_f32 v[150:151], v[74:75], v[84:85], v[150:151] op_sel_hi:[0,1,1]
	v_pk_fma_f32 v[150:151], v[74:75], v[86:87], v[150:151] op_sel:[1,0,0] op_sel_hi:[1,1,1]
	v_pk_mul_f32 v[154:155], v[92:93], v[138:139] op_sel:[0,1] op_sel_hi:[1,1]
	v_pk_mul_f32 v[156:157], v[94:95], v[138:139] op_sel:[0,1] op_sel_hi:[1,1]
	v_add_f32_dpp v152, v150, v150 quad_perm:[1,0,3,2] row_mask:0xf bank_mask:0xf bound_ctrl:1
	v_pk_fma_f32 v[154:155], v[72:73], v[76:77], v[154:155]
	v_pk_fma_f32 v[156:157], v[74:75], v[78:79], v[156:157]
	v_add_f32_dpp v152, v152, v152 quad_perm:[2,3,0,1] row_mask:0xf bank_mask:0xf bound_ctrl:1
	ds_read_b128 v[120:123], v162 offset:44800
	ds_read_b128 v[124:127], v163 offset:44800
	v_add_f32_dpp v152, v152, v152 row_half_mirror row_mask:0xf bank_mask:0xf bound_ctrl:1
	ds_read_b128 v[132:135], v202 offset:45568
	ds_read_b128 v[116:119], v202 offset:44544
	v_add_f32_dpp v152, v152, v152 row_mirror row_mask:0xf bank_mask:0xf bound_ctrl:1
	v_pk_fma_f32 v[68:69], v[88:89], v[152:153], v[154:155] op_sel_hi:[1,0,1]
	v_pk_fma_f32 v[70:71], v[90:91], v[152:153], v[156:157] op_sel_hi:[1,0,1]
	ds_read_b128 v[128:131], v202 offset:45312
	s_waitcnt lgkmcnt(5)
	v_pk_mul_f32 v[144:145], v[68:69], v[100:101] op_sel_hi:[0,1]
	v_pk_fma_f32 v[144:145], v[68:69], v[102:103], v[144:145] op_sel:[1,0,0] op_sel_hi:[1,1,1]
	v_pk_fma_f32 v[144:145], v[70:71], v[104:105], v[144:145] op_sel_hi:[0,1,1]
	v_pk_fma_f32 v[144:145], v[70:71], v[106:107], v[144:145] op_sel:[1,0,0] op_sel_hi:[1,1,1]
	v_pk_mul_f32 v[154:155], v[112:113], v[140:141] op_sel_hi:[1,0]
	v_pk_mul_f32 v[156:157], v[114:115], v[140:141] op_sel_hi:[1,0]
	v_add_f32_dpp v152, v144, v144 quad_perm:[1,0,3,2] row_mask:0xf bank_mask:0xf bound_ctrl:1
	v_pk_fma_f32 v[154:155], v[68:69], v[96:97], v[154:155]
	v_pk_fma_f32 v[156:157], v[70:71], v[98:99], v[156:157]
	v_add_f32_dpp v152, v152, v152 quad_perm:[2,3,0,1] row_mask:0xf bank_mask:0xf bound_ctrl:1
	v_add_f32_dpp v158, v147, v147 row_ror:8 row_mask:0xf bank_mask:0xf
	v_add_f32_dpp v159, v149, v149 row_ror:8 row_mask:0xf bank_mask:0xf
	v_add_f32_dpp v152, v152, v152 row_half_mirror row_mask:0xf bank_mask:0xf bound_ctrl:1
	v_add_f32_dpp v158, v151, v151 row_ror:8 row_mask:0xf bank_mask:0xc
	v_add_f32_dpp v159, v145, v145 row_ror:8 row_mask:0xf bank_mask:0xc
	v_add_f32_dpp v152, v152, v152 row_mirror row_mask:0xf bank_mask:0xf bound_ctrl:1
	v_pk_fma_f32 v[72:73], v[108:109], v[152:153], v[154:155] op_sel_hi:[1,0,1]
	v_pk_fma_f32 v[74:75], v[110:111], v[152:153], v[156:157] op_sel_hi:[1,0,1]
	ds_read_b128 v[80:83], v162 offset:46336
	ds_read_b128 v[84:87], v163 offset:46336
	v_add_f32_dpp v160, v158, v158 row_half_mirror row_mask:0xf bank_mask:0xf
	v_add_f32_dpp v160, v159, v159 row_half_mirror row_mask:0xf bank_mask:0xa
	ds_read_b128 v[92:95], v202 offset:47104
	ds_read_b128 v[76:79], v202 offset:46080
	v_add_f32_dpp v160, v160, v160 quad_perm:[1,0,3,2] row_mask:0xf bank_mask:0xf bound_ctrl:1
	ds_read_b128 v[88:91], v202 offset:46848
	s_nop 0
	v_add_f32_dpp v160, v160, v160 quad_perm:[2,3,0,1] row_mask:0xf bank_mask:0xf bound_ctrl:1
	global_store_dword v161, v160, s[34:35]
	v_add_u32_e32 v161, 0xb000, v161
	s_waitcnt lgkmcnt(5)
	v_pk_mul_f32 v[146:147], v[72:73], v[120:121] op_sel_hi:[0,1]
	v_pk_fma_f32 v[146:147], v[72:73], v[122:123], v[146:147] op_sel:[1,0,0] op_sel_hi:[1,1,1]
	v_pk_fma_f32 v[146:147], v[74:75], v[124:125], v[146:147] op_sel_hi:[0,1,1]
	v_pk_fma_f32 v[146:147], v[74:75], v[126:127], v[146:147] op_sel:[1,0,0] op_sel_hi:[1,1,1]
	v_pk_mul_f32 v[154:155], v[132:133], v[140:141] op_sel:[0,1] op_sel_hi:[1,1]
	v_pk_mul_f32 v[156:157], v[134:135], v[140:141] op_sel:[0,1] op_sel_hi:[1,1]
	v_add_f32_dpp v152, v146, v146 quad_perm:[1,0,3,2] row_mask:0xf bank_mask:0xf bound_ctrl:1
	v_pk_fma_f32 v[154:155], v[72:73], v[116:117], v[154:155]
	v_pk_fma_f32 v[156:157], v[74:75], v[118:119], v[156:157]
	v_add_f32_dpp v152, v152, v152 quad_perm:[2,3,0,1] row_mask:0xf bank_mask:0xf bound_ctrl:1
	ds_read_b128 v[100:103], v162 offset:47872
	ds_read_b128 v[104:107], v163 offset:47872
	v_add_f32_dpp v152, v152, v152 row_half_mirror row_mask:0xf bank_mask:0xf bound_ctrl:1
	ds_read_b128 v[112:115], v202 offset:48640
	ds_read_b128 v[96:99], v202 offset:47616
	v_add_f32_dpp v152, v152, v152 row_mirror row_mask:0xf bank_mask:0xf bound_ctrl:1
	v_pk_fma_f32 v[68:69], v[128:129], v[152:153], v[154:155] op_sel_hi:[1,0,1]
	v_pk_fma_f32 v[70:71], v[130:131], v[152:153], v[156:157] op_sel_hi:[1,0,1]
	ds_read_b128 v[108:111], v202 offset:48384
	s_waitcnt lgkmcnt(5)
	v_pk_mul_f32 v[148:149], v[68:69], v[80:81] op_sel_hi:[0,1]
	v_pk_fma_f32 v[148:149], v[68:69], v[82:83], v[148:149] op_sel:[1,0,0] op_sel_hi:[1,1,1]
	v_pk_fma_f32 v[148:149], v[70:71], v[84:85], v[148:149] op_sel_hi:[0,1,1]
	v_pk_fma_f32 v[148:149], v[70:71], v[86:87], v[148:149] op_sel:[1,0,0] op_sel_hi:[1,1,1]
	v_pk_mul_f32 v[154:155], v[92:93], v[142:143] op_sel_hi:[1,0]
	v_pk_mul_f32 v[156:157], v[94:95], v[142:143] op_sel_hi:[1,0]
	v_add_f32_dpp v152, v148, v148 quad_perm:[1,0,3,2] row_mask:0xf bank_mask:0xf bound_ctrl:1
	v_pk_fma_f32 v[154:155], v[68:69], v[76:77], v[154:155]
	v_pk_fma_f32 v[156:157], v[70:71], v[78:79], v[156:157]
	v_add_f32_dpp v152, v152, v152 quad_perm:[2,3,0,1] row_mask:0xf bank_mask:0xf bound_ctrl:1
	s_nop 0
	s_nop 0
	v_add_f32_dpp v152, v152, v152 row_half_mirror row_mask:0xf bank_mask:0xf bound_ctrl:1
	s_nop 0
	s_nop 0
	v_add_f32_dpp v152, v152, v152 row_mirror row_mask:0xf bank_mask:0xf bound_ctrl:1
	v_pk_fma_f32 v[72:73], v[88:89], v[152:153], v[154:155] op_sel_hi:[1,0,1]
	v_pk_fma_f32 v[74:75], v[90:91], v[152:153], v[156:157] op_sel_hi:[1,0,1]
	s_waitcnt lgkmcnt(0)
	v_pk_mul_f32 v[150:151], v[72:73], v[100:101] op_sel_hi:[0,1]
	v_pk_fma_f32 v[150:151], v[72:73], v[102:103], v[150:151] op_sel:[1,0,0] op_sel_hi:[1,1,1]
	v_pk_fma_f32 v[150:151], v[74:75], v[104:105], v[150:151] op_sel_hi:[0,1,1]
	v_pk_fma_f32 v[150:151], v[74:75], v[106:107], v[150:151] op_sel:[1,0,0] op_sel_hi:[1,1,1]
	v_pk_mul_f32 v[154:155], v[112:113], v[142:143] op_sel:[0,1] op_sel_hi:[1,1]
	v_pk_mul_f32 v[156:157], v[114:115], v[142:143] op_sel:[0,1] op_sel_hi:[1,1]
	v_add_f32_dpp v152, v150, v150 quad_perm:[1,0,3,2] row_mask:0xf bank_mask:0xf bound_ctrl:1
	v_pk_fma_f32 v[154:155], v[72:73], v[96:97], v[154:155]
	v_pk_fma_f32 v[156:157], v[74:75], v[98:99], v[156:157]
	v_add_f32_dpp v152, v152, v152 quad_perm:[2,3,0,1] row_mask:0xf bank_mask:0xf bound_ctrl:1
	s_nop 0
	s_nop 0
	v_add_f32_dpp v152, v152, v152 row_half_mirror row_mask:0xf bank_mask:0xf bound_ctrl:1
	s_nop 0
	s_nop 0
	v_add_f32_dpp v152, v152, v152 row_mirror row_mask:0xf bank_mask:0xf bound_ctrl:1
	v_pk_fma_f32 v[68:69], v[108:109], v[152:153], v[154:155] op_sel_hi:[1,0,1]
	v_pk_fma_f32 v[70:71], v[110:111], v[152:153], v[156:157] op_sel_hi:[1,0,1]
	s_branch .LBB0_847
; #define LAS __attribute__((address_space(3)))
; __device__ __forceinline__ void rwkv_scan(Frame& F, int wg, unsigned* shw, unsigned wait_target, int wait_blk) {
;     ...
;     auto lstore = [&](const LdRegs& L, int b) {
;         LAS float* rec = buf + (b * RW_TB + lstep) * RW_REC;
;         const u32x4 av = L.a, bv = L.b, kv = L.k, rv = L.r;
;         f32x4 a_0 = {bflo(av.x), bfhi(av.x), bflo(av.y), bfhi(av.y)}, a_1 = {bflo(av.z), bfhi(av.z), bflo(av.w), bfhi(av.w)};
;         f32x4 b_0 = {bflo(bv.x), bfhi(bv.x), bflo(bv.y), bfhi(bv.y)}, b_1 = {bflo(bv.z), bfhi(bv.z), bflo(bv.w), bfhi(bv.w)};
;         f32x4 k_0 = {bflo(kv.x), bfhi(kv.x), bflo(kv.y), bfhi(kv.y)}, k_1 = {bflo(kv.z), bfhi(kv.z), bflo(kv.w), bfhi(kv.w)};
;         f32x4 r_0 = {bflo(rv.x), bfhi(rv.x), bflo(rv.y), bfhi(rv.y)}, r_1 = {bflo(rv.z), bfhi(rv.z), bflo(rv.w), bfhi(rv.w)};
;         *(LAS f32x4*)(rec + 8 * part) = L.w0; *(LAS f32x4*)(rec + 8 * part + 4) = L.w1;
;         *(LAS f32x4*)(rec + 64 + 8 * part) = a_0; *(LAS f32x4*)(rec + 64 + 8 * part + 4) = a_1;
;         *(LAS f32x4*)(rec + 128 + 8 * part) = b_0; *(LAS f32x4*)(rec + 128 + 8 * part + 4) = b_1;
;         *(LAS f32x4*)(rec + 192 + 8 * part) = k_0; *(LAS f32x4*)(rec + 192 + 8 * part + 4) = k_1;
;         *(LAS f32x4*)(rec + 256 + 8 * part) = L.w0 * r_0; *(LAS f32x4*)(rec + 256 + 8 * part + 4) = L.w1 * r_1;
;         if (part < 2) { const u32x4 vv = L.v;
;             const float v8[8] = {bflo(vv.x), bfhi(vv.x), bflo(vv.y), bfhi(vv.y), bflo(vv.z), bfhi(vv.z), bflo(vv.w), bfhi(vv.w)};
; #pragma unroll
;             for (int e = 0; e < 8; ++e) *(LAS f32x4*)(rec + 320 + (8 * part + e) * 4) = (f32x4){v8[e], v8[e] * L.kr, L.br, 0.f}; }
.LBB0_909:
	s_and_b64 vcc, exec, s[50:51]
	s_cbranch_vccz .LBB0_846
	s_cmpk_gt_u32 s59, 0x1fd
	s_cbranch_scc1 .LBB0_847
	s_waitcnt vmcnt(0)
	v_add_u32_e32 v100, v199, v195
	v_lshl_add_u32 v101, v195, 1, v199
	v_lshrrev_b32_e32 v102, 3, v195
	v_and_b32_e32 v102, 16, v102
	v_add_u32_e32 v101, v101, v102
	v_xor_b32_e32 v103, 16, v101
	v_lshlrev_b32_e32 v104, 16, v44
	v_and_b32_e32 v105, 0xffff0000, v44
	v_lshlrev_b32_e32 v106, 16, v45
	v_and_b32_e32 v107, 0xffff0000, v45
	v_lshlrev_b32_e32 v108, 16, v46
	v_and_b32_e32 v109, 0xffff0000, v46
	v_lshlrev_b32_e32 v110, 16, v47
	v_and_b32_e32 v111, 0xffff0000, v47
	ds_write_b128 v100, v[104:107] offset:768
	ds_write_b128 v100, v[108:111] offset:784
	v_lshlrev_b32_e32 v112, 16, v48
	v_and_b32_e32 v113, 0xffff0000, v48
	v_lshlrev_b32_e32 v114, 16, v49
	v_and_b32_e32 v115, 0xffff0000, v49
	v_lshlrev_b32_e32 v116, 16, v50
	v_and_b32_e32 v117, 0xffff0000, v50
	v_lshlrev_b32_e32 v118, 16, v51
	v_and_b32_e32 v119, 0xffff0000, v51
	ds_write_b128 v100, v[112:115] offset:1024
	ds_write_b128 v100, v[116:119] offset:1040
	v_lshlrev_b32_e32 v120, 16, v40
	v_lshlrev_b32_e32 v121, 16, v52
	v_and_b32_e32 v122, 0xffff0000, v40
	v_and_b32_e32 v123, 0xffff0000, v52
	ds_write_b128 v101, v[120:123] offset:256
	v_lshlrev_b32_e32 v124, 16, v41
	v_lshlrev_b32_e32 v125, 16, v53
	v_and_b32_e32 v126, 0xffff0000, v41
	v_and_b32_e32 v127, 0xffff0000, v53
	ds_write_b128 v103, v[124:127] offset:256
	v_lshlrev_b32_e32 v128, 16, v42
	v_lshlrev_b32_e32 v129, 16, v54
	v_and_b32_e32 v130, 0xffff0000, v42
	v_and_b32_e32 v131, 0xffff0000, v54
	ds_write_b128 v101, v[128:131] offset:288
	v_lshlrev_b32_e32 v132, 16, v43
	v_lshlrev_b32_e32 v133, 16, v55
	v_and_b32_e32 v134, 0xffff0000, v43
	v_and_b32_e32 v135, 0xffff0000, v55
	ds_write_b128 v103, v[132:135] offset:288
	ds_write_b128 v100, v[36:39] offset:0
	ds_write_b128 v100, v[32:35] offset:16
	s_and_saveexec_b64 s[50:51], s[10:11]
	s_cbranch_execz .LBB0_913
	v_and_b32_e32 v100, 3, v201
	v_mul_u32_u24_e32 v100, 0x5fc, v100
	v_add_u32_e32 v101, v199, v200
	v_sub_u32_e32 v101, v101, v100
	v_lshlrev_b32_e32 v104, 16, v56
	v_and_b32_e32 v105, 0xffff0000, v56
	v_lshlrev_b32_e32 v106, 16, v57
	v_and_b32_e32 v107, 0xffff0000, v57
	v_lshlrev_b32_e32 v108, 16, v58
	v_and_b32_e32 v109, 0xffff0000, v58
	v_lshlrev_b32_e32 v110, 16, v59
	v_and_b32_e32 v111, 0xffff0000, v59
	ds_write_b32 v101, v104 offset:1280
	ds_write_b32 v101, v105 offset:1296
	ds_write_b32 v101, v106 offset:1312
	ds_write_b32 v101, v107 offset:1328
	ds_write_b32 v101, v108 offset:1344
	ds_write_b32 v101, v109 offset:1360
	ds_write_b32 v101, v110 offset:1376
	ds_write_b32 v101, v111 offset:1392

; __device__ __forceinline__ void rwkv_scan(Frame& F, int wg, unsigned* shw, unsigned wait_target, int wait_blk) {
;     ...
;                     const f32x2 slo = {st.x, st.y}, shi = {st.z, st.w};
;                     f32x2 ma = slo * (f32x2){cur.a.x, cur.a.y}; ma = __builtin_elementwise_fma(shi, (f32x2){cur.a.z, cur.a.w}, ma);
;                     f32x2 mz = slo * (f32x2){cur.wr.x, cur.wr.y}; mz = __builtin_elementwise_fma(shi, (f32x2){cur.wr.z, cur.wr.w}, mz);
;                     float psa = ma.x + ma.y; pz[q] = mz.x + mz.y;
;                     const f32x2 vb = {cur.vs.x, cur.vs.x};
;                     f32x2 tlo = (f32x2){cur.k.x, cur.k.y} * vb, thi = (f32x2){cur.k.z, cur.k.w} * vb;
;                     tlo = __builtin_elementwise_fma(slo, (f32x2){cur.w.x, cur.w.y}, tlo); thi = __builtin_elementwise_fma(shi, (f32x2){cur.w.z, cur.w.w}, thi);
;                     psa = red16(psa);
;                     const f32x2 pb = {psa, psa};
;                     tlo = __builtin_elementwise_fma((f32x2){cur.b.x, cur.b.y}, pb, tlo); thi = __builtin_elementwise_fma((f32x2){cur.b.z, cur.b.w}, pb, thi);
;                     st = (f32x4){tlo.x, tlo.y, thi.x, thi.y};
;                     u[q] = psa * cur.vs.z + cur.vs.y;
;                 }
;                 const float qa = (odd1 ? pz[1] : pz[0]) + dppf<0xB1>(odd1 ? pz[0] : pz[1]);
;                 const float qb = (odd1 ? pz[3] : pz[2]) + dppf<0xB1>(odd1 ? pz[2] : pz[3]);
;                 float r = (odd2 ? qb : qa) + dppf<0x4E>(odd2 ? qa : qb);
;                 r += dppf<0x124>(r); r += dppf<0x128>(r);
;                 const float us = odd2 ? (odd1 ? u[3] : u[2]) : (odd1 ? u[1] : u[0]);
;                 if (j < 4) { const int t = blk * RW_TB + s4 + j; ((float*)(Ub + (size_t)t * (PWP * 2) + URR * 2))[h * 64 + row] = r + us; }
.LBB0_917:
	s_and_b64 vcc, exec, s[26:27]
	s_cbranch_vccz .Lscan_epi_done
	s_lshl_b32 s50, s58, 7
	s_add_u32 s50, s50, 0x1fff800
	v_lshl_add_u32 v76, v194, 3, s50
	global_load_dwordx2 v[78:79], v76, s[40:41]
	s_waitcnt vmcnt(0)
	v_lshlrev_b32_e32 v80, 16, v78
	v_and_b32_e32 v81, 0xffff0000, v78
	v_lshlrev_b32_e32 v82, 16, v79
	v_and_b32_e32 v83, 0xffff0000, v79
	v_pk_mul_f32 v[84:85], v[68:69], v[80:81]
	v_pk_fma_f32 v[84:85], v[70:71], v[82:83], v[84:85]
	v_add_f32_e32 v86, v84, v85
	s_nop 1
	v_add_f32_dpp v158, v147, v147 row_ror:8 row_mask:0xf bank_mask:0xf
	v_add_f32_dpp v159, v149, v149 row_ror:8 row_mask:0xf bank_mask:0xf
	v_add_f32_dpp v158, v151, v151 row_ror:8 row_mask:0xf bank_mask:0xc
	v_add_f32_dpp v159, v86, v86 row_ror:8 row_mask:0xf bank_mask:0xc
	s_nop 0
	s_nop 0
	v_add_f32_dpp v160, v158, v158 row_half_mirror row_mask:0xf bank_mask:0xf
	v_add_f32_dpp v160, v159, v159 row_half_mirror row_mask:0xf bank_mask:0xa
	s_nop 0
	s_nop 0
	v_add_f32_dpp v160, v160, v160 quad_perm:[1,0,3,2] row_mask:0xf bank_mask:0xf bound_ctrl:1
	s_nop 0
	s_nop 0
	v_add_f32_dpp v160, v160, v160 quad_perm:[2,3,0,1] row_mask:0xf bank_mask:0xf bound_ctrl:1
	global_store_dword v161, v160, s[34:35]
	v_add_u32_e32 v161, 0xb000, v161
